# P9/P10 gate epilogues rewritten by hand: loads batched 5-11 steps deep with counted vmcnt, packed f32 math
# speedup vs baseline: 1.0128x; 1.0128x over previous
; __device__ __forceinline__ unsigned cvt_pk_bf16(float lo, float hi) { unsigned r; asm volatile("v_cvt_pk_bf16_f32 %0, %1, %2" : "=v"(r) : "v"(lo), "v"(hi)); return r; }
;     __device__ __forceinline__ void operator()(const f32x4 (&acc)[2][2][4][2], const Unit& u, int wr, int wc, int fr, int fq) const {
;     ...
;             for (int m = 0; m < 4; ++m) { const size_t ro = (size_t)(row0 + ai * HALF + m * 16) * ldc + col0;
; #pragma unroll
;                 for (int bj = 0; bj < 2; ++bj) { const f32x4 v0 = acc[ai][bj][m][0], v1 = acc[ai][bj][m][1];
;                     const u32x4 gw = *(const u32x4*)(G + ro + bj * HALF);
;                     float r[8]; const float a[8] = {v0[0], v0[1], v0[2], v0[3], v1[0], v1[1], v1[2], v1[3]};
; #pragma unroll
;                     for (int i = 0; i < 4; ++i) { const unsigned w = gw[i]; const float g0 = __builtin_bit_cast(float, w << 16), g1 = __builtin_bit_cast(float, w & 0xffff0000u);
;                         if (MODE == 0) { r[2 * i] = a[2 * i] * __builtin_amdgcn_rcpf(1.0f + __builtin_amdgcn_exp2f(-1.4426950408889634f * g0)); r[2 * i + 1] = a[2 * i + 1] * __builtin_amdgcn_rcpf(1.0f + __builtin_amdgcn_exp2f(-1.4426950408889634f * g1)); }
;                         else { r[2 * i] = g0 * a[2 * i] * __builtin_amdgcn_rcpf(1.0f + __builtin_amdgcn_exp2f(-1.4426950408889634f * a[2 * i])); r[2 * i + 1] = g1 * a[2 * i + 1] * __builtin_amdgcn_rcpf(1.0f + __builtin_amdgcn_exp2f(-1.4426950408889634f * a[2 * i + 1])); } }
;                     if (Add) { const u32x4 aw = *(const u32x4*)(Add + ro + bj * HALF);
; #pragma unroll
;                         for (int i = 0; i < 4; ++i) { const unsigned w = aw[i]; r[2 * i] += __builtin_bit_cast(float, w << 16); r[2 * i + 1] += __builtin_bit_cast(float, w & 0xffff0000u); } }
;                     u32x4 w; w.x = cvt_pk_bf16(r[0], r[1]); w.y = cvt_pk_bf16(r[2], r[3]); w.z = cvt_pk_bf16(r[4], r[5]); w.w = cvt_pk_bf16(r[6], r[7]);
;                     *(u32x4*)(O + ro + bj * HALF) = w; } }
;     __device__ __forceinline__ void operator()(const f32x4 (&acc)[2][2][4][2], const Unit& u, int wr, int wc, int fr, int fq) const {
;         if (u.pn < 4) { EpiGate<1> E{ob_out, ob, nullptr, 1024, 0}; E(acc, u, wr, wc, fr, fq); }
.LBB0_818:
	v_readlane_b32 s4, v254, 37
	v_readlane_b32 s5, v254, 38
	v_lshl_or_b32 v131, s38, 8, v158
	v_lshl_add_u32 v130, v152, 10, v131
	v_lshlrev_b32_e32 v130, 1, v130
	s_mov_b32 s100, 0xbfb8aa3b
	s_nop 1
	v_mov_b32_e32 v131, v130
	global_load_dwordx4 v[182:185], v131, s[4:5]
	v_mov_b32_e32 v131, v130
	global_load_dwordx4 v[186:189], v131, s[4:5] offset:256
	v_add_u32_e32 v131, 0x8000, v130
	global_load_dwordx4 v[190:193], v131, s[4:5]
	v_add_u32_e32 v131, 0x8000, v130
	global_load_dwordx4 v[194:197], v131, s[4:5] offset:256
	v_add_u32_e32 v131, 0x10000, v130
	global_load_dwordx4 v[198:201], v131, s[4:5]
	v_add_u32_e32 v131, 0x10000, v130
	global_load_dwordx4 v[202:205], v131, s[4:5] offset:256
	v_add_u32_e32 v131, 0x18000, v130
	global_load_dwordx4 v[206:209], v131, s[4:5]
	v_add_u32_e32 v131, 0x18000, v130
	global_load_dwordx4 v[210:213], v131, s[4:5] offset:256
	v_add_u32_e32 v131, 0x40000, v130
	global_load_dwordx4 v[214:217], v131, s[4:5]
	v_add_u32_e32 v131, 0x40000, v130
	global_load_dwordx4 v[218:221], v131, s[4:5] offset:256
	s_waitcnt vmcnt(9)
	v_pk_mul_f32 v[166:167], v[126:127], s[100:101] op_sel_hi:[1,0]
	v_pk_mul_f32 v[168:169], v[128:129], s[100:101] op_sel_hi:[1,0]
	v_pk_mul_f32 v[170:171], v[122:123], s[100:101] op_sel_hi:[1,0]
	v_pk_mul_f32 v[172:173], v[124:125], s[100:101] op_sel_hi:[1,0]
	v_exp_f32_e32 v166, v166
	v_exp_f32_e32 v167, v167
	v_exp_f32_e32 v168, v168
	v_exp_f32_e32 v169, v169
	v_exp_f32_e32 v170, v170
	v_exp_f32_e32 v171, v171
	v_exp_f32_e32 v172, v172
	v_exp_f32_e32 v173, v173
	v_lshlrev_b32_e32 v174, 16, v182
	v_and_b32_e32 v175, 0xffff0000, v182
	v_lshlrev_b32_e32 v176, 16, v183
	v_and_b32_e32 v177, 0xffff0000, v183
	v_lshlrev_b32_e32 v178, 16, v184
	v_and_b32_e32 v179, 0xffff0000, v184
	v_lshlrev_b32_e32 v180, 16, v185
	v_and_b32_e32 v181, 0xffff0000, v185
	v_pk_add_f32 v[166:167], v[166:167], 1.0 op_sel_hi:[1,0]
	v_pk_add_f32 v[168:169], v[168:169], 1.0 op_sel_hi:[1,0]
	v_pk_add_f32 v[170:171], v[170:171], 1.0 op_sel_hi:[1,0]
	v_pk_add_f32 v[172:173], v[172:173], 1.0 op_sel_hi:[1,0]
	v_rcp_f32_e32 v166, v166
	v_rcp_f32_e32 v167, v167
	v_rcp_f32_e32 v168, v168
	v_rcp_f32_e32 v169, v169
	v_rcp_f32_e32 v170, v170
	v_rcp_f32_e32 v171, v171
	v_rcp_f32_e32 v172, v172
	v_rcp_f32_e32 v173, v173
	v_pk_mul_f32 v[174:175], v[174:175], v[126:127]
	v_pk_mul_f32 v[176:177], v[176:177], v[128:129]
	v_pk_mul_f32 v[178:179], v[178:179], v[122:123]
	v_pk_mul_f32 v[180:181], v[180:181], v[124:125]
	v_pk_mul_f32 v[174:175], v[174:175], v[166:167]
	v_pk_mul_f32 v[176:177], v[176:177], v[168:169]
	v_pk_mul_f32 v[178:179], v[178:179], v[170:171]
	v_pk_mul_f32 v[180:181], v[180:181], v[172:173]
	v_cvt_pk_bf16_f32 v174, v174, v175
	v_cvt_pk_bf16_f32 v175, v176, v177
	v_cvt_pk_bf16_f32 v176, v178, v179
	v_cvt_pk_bf16_f32 v177, v180, v181
	v_mov_b32_e32 v132, v130
	global_store_dwordx4 v132, v[174:177], s[4:5]
	v_add_u32_e32 v131, 0x48000, v130
	global_load_dwordx4 v[182:185], v131, s[4:5]
	s_waitcnt vmcnt(10)
	v_pk_mul_f32 v[166:167], v[118:119], s[100:101] op_sel_hi:[1,0]
	v_pk_mul_f32 v[168:169], v[120:121], s[100:101] op_sel_hi:[1,0]
	v_pk_mul_f32 v[170:171], v[114:115], s[100:101] op_sel_hi:[1,0]
	v_pk_mul_f32 v[172:173], v[116:117], s[100:101] op_sel_hi:[1,0]
	v_exp_f32_e32 v166, v166
	v_exp_f32_e32 v167, v167
	v_exp_f32_e32 v168, v168
	v_exp_f32_e32 v169, v169
	v_exp_f32_e32 v170, v170
	v_exp_f32_e32 v171, v171
	v_exp_f32_e32 v172, v172
	v_exp_f32_e32 v173, v173
	v_lshlrev_b32_e32 v174, 16, v186
	v_and_b32_e32 v175, 0xffff0000, v186
	v_lshlrev_b32_e32 v176, 16, v187
	v_and_b32_e32 v177, 0xffff0000, v187
	v_lshlrev_b32_e32 v178, 16, v188
	v_and_b32_e32 v179, 0xffff0000, v188
	v_lshlrev_b32_e32 v180, 16, v189
	v_and_b32_e32 v181, 0xffff0000, v189
	v_pk_add_f32 v[166:167], v[166:167], 1.0 op_sel_hi:[1,0]
	v_pk_add_f32 v[168:169], v[168:169], 1.0 op_sel_hi:[1,0]
	v_pk_add_f32 v[170:171], v[170:171], 1.0 op_sel_hi:[1,0]
	v_pk_add_f32 v[172:173], v[172:173], 1.0 op_sel_hi:[1,0]
	v_rcp_f32_e32 v166, v166
	v_rcp_f32_e32 v167, v167
	v_rcp_f32_e32 v168, v168
	v_rcp_f32_e32 v169, v169
	v_rcp_f32_e32 v170, v170
	v_rcp_f32_e32 v171, v171
	v_rcp_f32_e32 v172, v172
	v_rcp_f32_e32 v173, v173
	v_pk_mul_f32 v[174:175], v[174:175], v[118:119]
	v_pk_mul_f32 v[176:177], v[176:177], v[120:121]
	v_pk_mul_f32 v[178:179], v[178:179], v[114:115]
	v_pk_mul_f32 v[180:181], v[180:181], v[116:117]
	v_pk_mul_f32 v[174:175], v[174:175], v[166:167]
	v_pk_mul_f32 v[176:177], v[176:177], v[168:169]
	v_pk_mul_f32 v[178:179], v[178:179], v[170:171]
	v_pk_mul_f32 v[180:181], v[180:181], v[172:173]
	v_cvt_pk_bf16_f32 v174, v174, v175
	v_cvt_pk_bf16_f32 v175, v176, v177
	v_cvt_pk_bf16_f32 v176, v178, v179
	v_cvt_pk_bf16_f32 v177, v180, v181
	v_mov_b32_e32 v132, v130
	global_store_dwordx4 v132, v[174:177], s[4:5] offset:256
	v_add_u32_e32 v131, 0x48000, v130
	global_load_dwordx4 v[186:189], v131, s[4:5] offset:256
	s_waitcnt vmcnt(11)
; __device__ __forceinline__ unsigned cvt_pk_bf16(float lo, float hi) { unsigned r; asm volatile("v_cvt_pk_bf16_f32 %0, %1, %2" : "=v"(r) : "v"(lo), "v"(hi)); return r; }
;     __device__ __forceinline__ void operator()(const f32x4 (&acc)[2][2][4][2], const Unit& u, int wr, int wc, int fr, int fq) const {
;     ...
;             for (int m = 0; m < 4; ++m) { const size_t ro = (size_t)(row0 + ai * HALF + m * 16) * ldc + col0;
; #pragma unroll
;                 for (int bj = 0; bj < 2; ++bj) { const f32x4 v0 = acc[ai][bj][m][0], v1 = acc[ai][bj][m][1];
;                     const u32x4 gw = *(const u32x4*)(G + ro + bj * HALF);
;                     float r[8]; const float a[8] = {v0[0], v0[1], v0[2], v0[3], v1[0], v1[1], v1[2], v1[3]};
; #pragma unroll
;                     for (int i = 0; i < 4; ++i) { const unsigned w = gw[i]; const float g0 = __builtin_bit_cast(float, w << 16), g1 = __builtin_bit_cast(float, w & 0xffff0000u);
;                         if (MODE == 0) { r[2 * i] = a[2 * i] * __builtin_amdgcn_rcpf(1.0f + __builtin_amdgcn_exp2f(-1.4426950408889634f * g0)); r[2 * i + 1] = a[2 * i + 1] * __builtin_amdgcn_rcpf(1.0f + __builtin_amdgcn_exp2f(-1.4426950408889634f * g1)); }
;                         else { r[2 * i] = g0 * a[2 * i] * __builtin_amdgcn_rcpf(1.0f + __builtin_amdgcn_exp2f(-1.4426950408889634f * a[2 * i])); r[2 * i + 1] = g1 * a[2 * i + 1] * __builtin_amdgcn_rcpf(1.0f + __builtin_amdgcn_exp2f(-1.4426950408889634f * a[2 * i + 1])); } }
;                     if (Add) { const u32x4 aw = *(const u32x4*)(Add + ro + bj * HALF);
; #pragma unroll
;                         for (int i = 0; i < 4; ++i) { const unsigned w = aw[i]; r[2 * i] += __builtin_bit_cast(float, w << 16); r[2 * i + 1] += __builtin_bit_cast(float, w & 0xffff0000u); } }
;                     u32x4 w; w.x = cvt_pk_bf16(r[0], r[1]); w.y = cvt_pk_bf16(r[2], r[3]); w.z = cvt_pk_bf16(r[4], r[5]); w.w = cvt_pk_bf16(r[6], r[7]);
;                     *(u32x4*)(O + ro + bj * HALF) = w; } }
	v_pk_mul_f32 v[166:167], v[110:111], s[100:101] op_sel_hi:[1,0]
	v_pk_mul_f32 v[168:169], v[112:113], s[100:101] op_sel_hi:[1,0]
	v_pk_mul_f32 v[170:171], v[106:107], s[100:101] op_sel_hi:[1,0]
	v_pk_mul_f32 v[172:173], v[108:109], s[100:101] op_sel_hi:[1,0]
	v_exp_f32_e32 v166, v166
	v_exp_f32_e32 v167, v167
	v_exp_f32_e32 v168, v168
	v_exp_f32_e32 v169, v169
	v_exp_f32_e32 v170, v170
	v_exp_f32_e32 v171, v171
	v_exp_f32_e32 v172, v172
	v_exp_f32_e32 v173, v173
	v_lshlrev_b32_e32 v174, 16, v190
	v_and_b32_e32 v175, 0xffff0000, v190
	v_lshlrev_b32_e32 v176, 16, v191
	v_and_b32_e32 v177, 0xffff0000, v191
	v_lshlrev_b32_e32 v178, 16, v192
	v_and_b32_e32 v179, 0xffff0000, v192
	v_lshlrev_b32_e32 v180, 16, v193
	v_and_b32_e32 v181, 0xffff0000, v193
	v_pk_add_f32 v[166:167], v[166:167], 1.0 op_sel_hi:[1,0]
	v_pk_add_f32 v[168:169], v[168:169], 1.0 op_sel_hi:[1,0]
	v_pk_add_f32 v[170:171], v[170:171], 1.0 op_sel_hi:[1,0]
	v_pk_add_f32 v[172:173], v[172:173], 1.0 op_sel_hi:[1,0]
	v_rcp_f32_e32 v166, v166
	v_rcp_f32_e32 v167, v167
	v_rcp_f32_e32 v168, v168
	v_rcp_f32_e32 v169, v169
	v_rcp_f32_e32 v170, v170
	v_rcp_f32_e32 v171, v171
	v_rcp_f32_e32 v172, v172
	v_rcp_f32_e32 v173, v173
	v_pk_mul_f32 v[174:175], v[174:175], v[110:111]
	v_pk_mul_f32 v[176:177], v[176:177], v[112:113]
	v_pk_mul_f32 v[178:179], v[178:179], v[106:107]
	v_pk_mul_f32 v[180:181], v[180:181], v[108:109]
	v_pk_mul_f32 v[174:175], v[174:175], v[166:167]
	v_pk_mul_f32 v[176:177], v[176:177], v[168:169]
	v_pk_mul_f32 v[178:179], v[178:179], v[170:171]
	v_pk_mul_f32 v[180:181], v[180:181], v[172:173]
	v_cvt_pk_bf16_f32 v174, v174, v175
	v_cvt_pk_bf16_f32 v175, v176, v177
	v_cvt_pk_bf16_f32 v176, v178, v179
	v_cvt_pk_bf16_f32 v177, v180, v181
	v_add_u32_e32 v132, 0x8000, v130
	global_store_dwordx4 v132, v[174:177], s[4:5]
	v_add_u32_e32 v131, 0x50000, v130
	global_load_dwordx4 v[190:193], v131, s[4:5]
	s_waitcnt vmcnt(12)
	v_pk_mul_f32 v[166:167], v[102:103], s[100:101] op_sel_hi:[1,0]
	v_pk_mul_f32 v[168:169], v[104:105], s[100:101] op_sel_hi:[1,0]
	v_pk_mul_f32 v[170:171], v[98:99], s[100:101] op_sel_hi:[1,0]
	v_pk_mul_f32 v[172:173], v[100:101], s[100:101] op_sel_hi:[1,0]
	v_exp_f32_e32 v166, v166
	v_exp_f32_e32 v167, v167
	v_exp_f32_e32 v168, v168
	v_exp_f32_e32 v169, v169
	v_exp_f32_e32 v170, v170
	v_exp_f32_e32 v171, v171
	v_exp_f32_e32 v172, v172
	v_exp_f32_e32 v173, v173
	v_lshlrev_b32_e32 v174, 16, v194
	v_and_b32_e32 v175, 0xffff0000, v194
	v_lshlrev_b32_e32 v176, 16, v195
	v_and_b32_e32 v177, 0xffff0000, v195
	v_lshlrev_b32_e32 v178, 16, v196
	v_and_b32_e32 v179, 0xffff0000, v196
	v_lshlrev_b32_e32 v180, 16, v197
	v_and_b32_e32 v181, 0xffff0000, v197
	v_pk_add_f32 v[166:167], v[166:167], 1.0 op_sel_hi:[1,0]
	v_pk_add_f32 v[168:169], v[168:169], 1.0 op_sel_hi:[1,0]
	v_pk_add_f32 v[170:171], v[170:171], 1.0 op_sel_hi:[1,0]
	v_pk_add_f32 v[172:173], v[172:173], 1.0 op_sel_hi:[1,0]
	v_rcp_f32_e32 v166, v166
	v_rcp_f32_e32 v167, v167
	v_rcp_f32_e32 v168, v168
	v_rcp_f32_e32 v169, v169
	v_rcp_f32_e32 v170, v170
	v_rcp_f32_e32 v171, v171
	v_rcp_f32_e32 v172, v172
	v_rcp_f32_e32 v173, v173
	v_pk_mul_f32 v[174:175], v[174:175], v[102:103]
	v_pk_mul_f32 v[176:177], v[176:177], v[104:105]
	v_pk_mul_f32 v[178:179], v[178:179], v[98:99]
	v_pk_mul_f32 v[180:181], v[180:181], v[100:101]
	v_pk_mul_f32 v[174:175], v[174:175], v[166:167]
	v_pk_mul_f32 v[176:177], v[176:177], v[168:169]
	v_pk_mul_f32 v[178:179], v[178:179], v[170:171]
	v_pk_mul_f32 v[180:181], v[180:181], v[172:173]
	v_cvt_pk_bf16_f32 v174, v174, v175
	v_cvt_pk_bf16_f32 v175, v176, v177
	v_cvt_pk_bf16_f32 v176, v178, v179
	v_cvt_pk_bf16_f32 v177, v180, v181
	v_add_u32_e32 v132, 0x8000, v130
	global_store_dwordx4 v132, v[174:177], s[4:5] offset:256
	v_add_u32_e32 v131, 0x50000, v130
	global_load_dwordx4 v[194:197], v131, s[4:5] offset:256
	s_waitcnt vmcnt(13)
	v_pk_mul_f32 v[166:167], v[94:95], s[100:101] op_sel_hi:[1,0]
	v_pk_mul_f32 v[168:169], v[96:97], s[100:101] op_sel_hi:[1,0]
	v_pk_mul_f32 v[170:171], v[90:91], s[100:101] op_sel_hi:[1,0]
	v_pk_mul_f32 v[172:173], v[92:93], s[100:101] op_sel_hi:[1,0]
	v_exp_f32_e32 v166, v166
	v_exp_f32_e32 v167, v167
	v_exp_f32_e32 v168, v168
	v_exp_f32_e32 v169, v169
	v_exp_f32_e32 v170, v170
	v_exp_f32_e32 v171, v171
	v_exp_f32_e32 v172, v172
	v_exp_f32_e32 v173, v173
	v_lshlrev_b32_e32 v174, 16, v198
	v_and_b32_e32 v175, 0xffff0000, v198
	v_lshlrev_b32_e32 v176, 16, v199
	v_and_b32_e32 v177, 0xffff0000, v199
	v_lshlrev_b32_e32 v178, 16, v200
	v_and_b32_e32 v179, 0xffff0000, v200
	v_lshlrev_b32_e32 v180, 16, v201
	v_and_b32_e32 v181, 0xffff0000, v201
	v_pk_add_f32 v[166:167], v[166:167], 1.0 op_sel_hi:[1,0]
	v_pk_add_f32 v[168:169], v[168:169], 1.0 op_sel_hi:[1,0]
	v_pk_add_f32 v[170:171], v[170:171], 1.0 op_sel_hi:[1,0]
	v_pk_add_f32 v[172:173], v[172:173], 1.0 op_sel_hi:[1,0]
	v_rcp_f32_e32 v166, v166
	v_rcp_f32_e32 v167, v167
	v_rcp_f32_e32 v168, v168
	v_rcp_f32_e32 v169, v169
	v_rcp_f32_e32 v170, v170
	v_rcp_f32_e32 v171, v171
	v_rcp_f32_e32 v172, v172
	v_rcp_f32_e32 v173, v173
	v_pk_mul_f32 v[174:175], v[174:175], v[94:95]
	v_pk_mul_f32 v[176:177], v[176:177], v[96:97]
	v_pk_mul_f32 v[178:179], v[178:179], v[90:91]
	v_pk_mul_f32 v[180:181], v[180:181], v[92:93]
	v_pk_mul_f32 v[174:175], v[174:175], v[166:167]
	v_pk_mul_f32 v[176:177], v[176:177], v[168:169]
	v_pk_mul_f32 v[178:179], v[178:179], v[170:171]
	v_pk_mul_f32 v[180:181], v[180:181], v[172:173]
	v_cvt_pk_bf16_f32 v174, v174, v175
	v_cvt_pk_bf16_f32 v175, v176, v177
	v_cvt_pk_bf16_f32 v176, v178, v179
	v_cvt_pk_bf16_f32 v177, v180, v181
	v_add_u32_e32 v132, 0x10000, v130
	global_store_dwordx4 v132, v[174:177], s[4:5]
	v_add_u32_e32 v131, 0x58000, v130
	global_load_dwordx4 v[198:201], v131, s[4:5]
	s_waitcnt vmcnt(14)
; __device__ __forceinline__ unsigned cvt_pk_bf16(float lo, float hi) { unsigned r; asm volatile("v_cvt_pk_bf16_f32 %0, %1, %2" : "=v"(r) : "v"(lo), "v"(hi)); return r; }
;     __device__ __forceinline__ void operator()(const f32x4 (&acc)[2][2][4][2], const Unit& u, int wr, int wc, int fr, int fq) const {
;     ...
;             for (int m = 0; m < 4; ++m) { const size_t ro = (size_t)(row0 + ai * HALF + m * 16) * ldc + col0;
; #pragma unroll
;                 for (int bj = 0; bj < 2; ++bj) { const f32x4 v0 = acc[ai][bj][m][0], v1 = acc[ai][bj][m][1];
;                     const u32x4 gw = *(const u32x4*)(G + ro + bj * HALF);
;                     float r[8]; const float a[8] = {v0[0], v0[1], v0[2], v0[3], v1[0], v1[1], v1[2], v1[3]};
; #pragma unroll
;                     for (int i = 0; i < 4; ++i) { const unsigned w = gw[i]; const float g0 = __builtin_bit_cast(float, w << 16), g1 = __builtin_bit_cast(float, w & 0xffff0000u);
;                         if (MODE == 0) { r[2 * i] = a[2 * i] * __builtin_amdgcn_rcpf(1.0f + __builtin_amdgcn_exp2f(-1.4426950408889634f * g0)); r[2 * i + 1] = a[2 * i + 1] * __builtin_amdgcn_rcpf(1.0f + __builtin_amdgcn_exp2f(-1.4426950408889634f * g1)); }
;                         else { r[2 * i] = g0 * a[2 * i] * __builtin_amdgcn_rcpf(1.0f + __builtin_amdgcn_exp2f(-1.4426950408889634f * a[2 * i])); r[2 * i + 1] = g1 * a[2 * i + 1] * __builtin_amdgcn_rcpf(1.0f + __builtin_amdgcn_exp2f(-1.4426950408889634f * a[2 * i + 1])); } }
;                     if (Add) { const u32x4 aw = *(const u32x4*)(Add + ro + bj * HALF);
; #pragma unroll
;                         for (int i = 0; i < 4; ++i) { const unsigned w = aw[i]; r[2 * i] += __builtin_bit_cast(float, w << 16); r[2 * i + 1] += __builtin_bit_cast(float, w & 0xffff0000u); } }
;                     u32x4 w; w.x = cvt_pk_bf16(r[0], r[1]); w.y = cvt_pk_bf16(r[2], r[3]); w.z = cvt_pk_bf16(r[4], r[5]); w.w = cvt_pk_bf16(r[6], r[7]);
;                     *(u32x4*)(O + ro + bj * HALF) = w; } }
	v_pk_mul_f32 v[166:167], v[86:87], s[100:101] op_sel_hi:[1,0]
	v_pk_mul_f32 v[168:169], v[88:89], s[100:101] op_sel_hi:[1,0]
	v_pk_mul_f32 v[170:171], v[82:83], s[100:101] op_sel_hi:[1,0]
	v_pk_mul_f32 v[172:173], v[84:85], s[100:101] op_sel_hi:[1,0]
	v_exp_f32_e32 v166, v166
	v_exp_f32_e32 v167, v167
	v_exp_f32_e32 v168, v168
	v_exp_f32_e32 v169, v169
	v_exp_f32_e32 v170, v170
	v_exp_f32_e32 v171, v171
	v_exp_f32_e32 v172, v172
	v_exp_f32_e32 v173, v173
	v_lshlrev_b32_e32 v174, 16, v202
	v_and_b32_e32 v175, 0xffff0000, v202
	v_lshlrev_b32_e32 v176, 16, v203
	v_and_b32_e32 v177, 0xffff0000, v203
	v_lshlrev_b32_e32 v178, 16, v204
	v_and_b32_e32 v179, 0xffff0000, v204
	v_lshlrev_b32_e32 v180, 16, v205
	v_and_b32_e32 v181, 0xffff0000, v205
	v_pk_add_f32 v[166:167], v[166:167], 1.0 op_sel_hi:[1,0]
	v_pk_add_f32 v[168:169], v[168:169], 1.0 op_sel_hi:[1,0]
	v_pk_add_f32 v[170:171], v[170:171], 1.0 op_sel_hi:[1,0]
	v_pk_add_f32 v[172:173], v[172:173], 1.0 op_sel_hi:[1,0]
	v_rcp_f32_e32 v166, v166
	v_rcp_f32_e32 v167, v167
	v_rcp_f32_e32 v168, v168
	v_rcp_f32_e32 v169, v169
	v_rcp_f32_e32 v170, v170
	v_rcp_f32_e32 v171, v171
	v_rcp_f32_e32 v172, v172
	v_rcp_f32_e32 v173, v173
	v_pk_mul_f32 v[174:175], v[174:175], v[86:87]
	v_pk_mul_f32 v[176:177], v[176:177], v[88:89]
	v_pk_mul_f32 v[178:179], v[178:179], v[82:83]
	v_pk_mul_f32 v[180:181], v[180:181], v[84:85]
	v_pk_mul_f32 v[174:175], v[174:175], v[166:167]
	v_pk_mul_f32 v[176:177], v[176:177], v[168:169]
	v_pk_mul_f32 v[178:179], v[178:179], v[170:171]
	v_pk_mul_f32 v[180:181], v[180:181], v[172:173]
	v_cvt_pk_bf16_f32 v174, v174, v175
	v_cvt_pk_bf16_f32 v175, v176, v177
	v_cvt_pk_bf16_f32 v176, v178, v179
	v_cvt_pk_bf16_f32 v177, v180, v181
	v_add_u32_e32 v132, 0x10000, v130
	global_store_dwordx4 v132, v[174:177], s[4:5] offset:256
	v_add_u32_e32 v131, 0x58000, v130
	global_load_dwordx4 v[202:205], v131, s[4:5] offset:256
	s_waitcnt vmcnt(15)
	v_pk_mul_f32 v[166:167], v[78:79], s[100:101] op_sel_hi:[1,0]
	v_pk_mul_f32 v[168:169], v[80:81], s[100:101] op_sel_hi:[1,0]
	v_pk_mul_f32 v[170:171], v[74:75], s[100:101] op_sel_hi:[1,0]
	v_pk_mul_f32 v[172:173], v[76:77], s[100:101] op_sel_hi:[1,0]
	v_exp_f32_e32 v166, v166
	v_exp_f32_e32 v167, v167
	v_exp_f32_e32 v168, v168
	v_exp_f32_e32 v169, v169
	v_exp_f32_e32 v170, v170
	v_exp_f32_e32 v171, v171
	v_exp_f32_e32 v172, v172
	v_exp_f32_e32 v173, v173
	v_lshlrev_b32_e32 v174, 16, v206
	v_and_b32_e32 v175, 0xffff0000, v206
	v_lshlrev_b32_e32 v176, 16, v207
	v_and_b32_e32 v177, 0xffff0000, v207
	v_lshlrev_b32_e32 v178, 16, v208
	v_and_b32_e32 v179, 0xffff0000, v208
	v_lshlrev_b32_e32 v180, 16, v209
	v_and_b32_e32 v181, 0xffff0000, v209
	v_pk_add_f32 v[166:167], v[166:167], 1.0 op_sel_hi:[1,0]
	v_pk_add_f32 v[168:169], v[168:169], 1.0 op_sel_hi:[1,0]
	v_pk_add_f32 v[170:171], v[170:171], 1.0 op_sel_hi:[1,0]
	v_pk_add_f32 v[172:173], v[172:173], 1.0 op_sel_hi:[1,0]
	v_rcp_f32_e32 v166, v166
	v_rcp_f32_e32 v167, v167
	v_rcp_f32_e32 v168, v168
	v_rcp_f32_e32 v169, v169
	v_rcp_f32_e32 v170, v170
	v_rcp_f32_e32 v171, v171
	v_rcp_f32_e32 v172, v172
	v_rcp_f32_e32 v173, v173
	v_pk_mul_f32 v[174:175], v[174:175], v[78:79]
	v_pk_mul_f32 v[176:177], v[176:177], v[80:81]
	v_pk_mul_f32 v[178:179], v[178:179], v[74:75]
	v_pk_mul_f32 v[180:181], v[180:181], v[76:77]
	v_pk_mul_f32 v[174:175], v[174:175], v[166:167]
	v_pk_mul_f32 v[176:177], v[176:177], v[168:169]
	v_pk_mul_f32 v[178:179], v[178:179], v[170:171]
	v_pk_mul_f32 v[180:181], v[180:181], v[172:173]
	v_cvt_pk_bf16_f32 v174, v174, v175
	v_cvt_pk_bf16_f32 v175, v176, v177
	v_cvt_pk_bf16_f32 v176, v178, v179
	v_cvt_pk_bf16_f32 v177, v180, v181
	v_add_u32_e32 v132, 0x18000, v130
	global_store_dwordx4 v132, v[174:177], s[4:5]
	s_waitcnt vmcnt(15)
	v_pk_mul_f32 v[166:167], v[70:71], s[100:101] op_sel_hi:[1,0]
	v_pk_mul_f32 v[168:169], v[72:73], s[100:101] op_sel_hi:[1,0]
	v_pk_mul_f32 v[170:171], v[66:67], s[100:101] op_sel_hi:[1,0]
	v_pk_mul_f32 v[172:173], v[68:69], s[100:101] op_sel_hi:[1,0]
	v_exp_f32_e32 v166, v166
	v_exp_f32_e32 v167, v167
	v_exp_f32_e32 v168, v168
	v_exp_f32_e32 v169, v169
	v_exp_f32_e32 v170, v170
	v_exp_f32_e32 v171, v171
	v_exp_f32_e32 v172, v172
	v_exp_f32_e32 v173, v173
	v_lshlrev_b32_e32 v174, 16, v210
	v_and_b32_e32 v175, 0xffff0000, v210
	v_lshlrev_b32_e32 v176, 16, v211
	v_and_b32_e32 v177, 0xffff0000, v211
	v_lshlrev_b32_e32 v178, 16, v212
	v_and_b32_e32 v179, 0xffff0000, v212
	v_lshlrev_b32_e32 v180, 16, v213
	v_and_b32_e32 v181, 0xffff0000, v213
	v_pk_add_f32 v[166:167], v[166:167], 1.0 op_sel_hi:[1,0]
	v_pk_add_f32 v[168:169], v[168:169], 1.0 op_sel_hi:[1,0]
	v_pk_add_f32 v[170:171], v[170:171], 1.0 op_sel_hi:[1,0]
	v_pk_add_f32 v[172:173], v[172:173], 1.0 op_sel_hi:[1,0]
	v_rcp_f32_e32 v166, v166
	v_rcp_f32_e32 v167, v167
	v_rcp_f32_e32 v168, v168
	v_rcp_f32_e32 v169, v169
	v_rcp_f32_e32 v170, v170
	v_rcp_f32_e32 v171, v171
	v_rcp_f32_e32 v172, v172
	v_rcp_f32_e32 v173, v173
	v_pk_mul_f32 v[174:175], v[174:175], v[70:71]
	v_pk_mul_f32 v[176:177], v[176:177], v[72:73]
	v_pk_mul_f32 v[178:179], v[178:179], v[66:67]
	v_pk_mul_f32 v[180:181], v[180:181], v[68:69]
	v_pk_mul_f32 v[174:175], v[174:175], v[166:167]
	v_pk_mul_f32 v[176:177], v[176:177], v[168:169]
	v_pk_mul_f32 v[178:179], v[178:179], v[170:171]
	v_pk_mul_f32 v[180:181], v[180:181], v[172:173]
	v_cvt_pk_bf16_f32 v174, v174, v175
	v_cvt_pk_bf16_f32 v175, v176, v177
	v_cvt_pk_bf16_f32 v176, v178, v179
	v_cvt_pk_bf16_f32 v177, v180, v181
	v_add_u32_e32 v132, 0x18000, v130
	global_store_dwordx4 v132, v[174:177], s[4:5] offset:256
	s_waitcnt vmcnt(15)
; __device__ __forceinline__ unsigned cvt_pk_bf16(float lo, float hi) { unsigned r; asm volatile("v_cvt_pk_bf16_f32 %0, %1, %2" : "=v"(r) : "v"(lo), "v"(hi)); return r; }
;     __device__ __forceinline__ void operator()(const f32x4 (&acc)[2][2][4][2], const Unit& u, int wr, int wc, int fr, int fq) const {
;     ...
;             for (int m = 0; m < 4; ++m) { const size_t ro = (size_t)(row0 + ai * HALF + m * 16) * ldc + col0;
; #pragma unroll
;                 for (int bj = 0; bj < 2; ++bj) { const f32x4 v0 = acc[ai][bj][m][0], v1 = acc[ai][bj][m][1];
;                     const u32x4 gw = *(const u32x4*)(G + ro + bj * HALF);
;                     float r[8]; const float a[8] = {v0[0], v0[1], v0[2], v0[3], v1[0], v1[1], v1[2], v1[3]};
; #pragma unroll
;                     for (int i = 0; i < 4; ++i) { const unsigned w = gw[i]; const float g0 = __builtin_bit_cast(float, w << 16), g1 = __builtin_bit_cast(float, w & 0xffff0000u);
;                         if (MODE == 0) { r[2 * i] = a[2 * i] * __builtin_amdgcn_rcpf(1.0f + __builtin_amdgcn_exp2f(-1.4426950408889634f * g0)); r[2 * i + 1] = a[2 * i + 1] * __builtin_amdgcn_rcpf(1.0f + __builtin_amdgcn_exp2f(-1.4426950408889634f * g1)); }
;                         else { r[2 * i] = g0 * a[2 * i] * __builtin_amdgcn_rcpf(1.0f + __builtin_amdgcn_exp2f(-1.4426950408889634f * a[2 * i])); r[2 * i + 1] = g1 * a[2 * i + 1] * __builtin_amdgcn_rcpf(1.0f + __builtin_amdgcn_exp2f(-1.4426950408889634f * a[2 * i + 1])); } }
;                     if (Add) { const u32x4 aw = *(const u32x4*)(Add + ro + bj * HALF);
; #pragma unroll
;                         for (int i = 0; i < 4; ++i) { const unsigned w = aw[i]; r[2 * i] += __builtin_bit_cast(float, w << 16); r[2 * i + 1] += __builtin_bit_cast(float, w & 0xffff0000u); } }
;                     u32x4 w; w.x = cvt_pk_bf16(r[0], r[1]); w.y = cvt_pk_bf16(r[2], r[3]); w.z = cvt_pk_bf16(r[4], r[5]); w.w = cvt_pk_bf16(r[6], r[7]);
;                     *(u32x4*)(O + ro + bj * HALF) = w; } }
	v_pk_mul_f32 v[166:167], v[62:63], s[100:101] op_sel_hi:[1,0]
	v_pk_mul_f32 v[168:169], v[64:65], s[100:101] op_sel_hi:[1,0]
	v_pk_mul_f32 v[170:171], v[58:59], s[100:101] op_sel_hi:[1,0]
	v_pk_mul_f32 v[172:173], v[60:61], s[100:101] op_sel_hi:[1,0]
	v_exp_f32_e32 v166, v166
	v_exp_f32_e32 v167, v167
	v_exp_f32_e32 v168, v168
	v_exp_f32_e32 v169, v169
	v_exp_f32_e32 v170, v170
	v_exp_f32_e32 v171, v171
	v_exp_f32_e32 v172, v172
	v_exp_f32_e32 v173, v173
	v_lshlrev_b32_e32 v174, 16, v214
	v_and_b32_e32 v175, 0xffff0000, v214
	v_lshlrev_b32_e32 v176, 16, v215
	v_and_b32_e32 v177, 0xffff0000, v215
	v_lshlrev_b32_e32 v178, 16, v216
	v_and_b32_e32 v179, 0xffff0000, v216
	v_lshlrev_b32_e32 v180, 16, v217
	v_and_b32_e32 v181, 0xffff0000, v217
	v_pk_add_f32 v[166:167], v[166:167], 1.0 op_sel_hi:[1,0]
	v_pk_add_f32 v[168:169], v[168:169], 1.0 op_sel_hi:[1,0]
	v_pk_add_f32 v[170:171], v[170:171], 1.0 op_sel_hi:[1,0]
	v_pk_add_f32 v[172:173], v[172:173], 1.0 op_sel_hi:[1,0]
	v_rcp_f32_e32 v166, v166
	v_rcp_f32_e32 v167, v167
	v_rcp_f32_e32 v168, v168
	v_rcp_f32_e32 v169, v169
	v_rcp_f32_e32 v170, v170
	v_rcp_f32_e32 v171, v171
	v_rcp_f32_e32 v172, v172
	v_rcp_f32_e32 v173, v173
	v_pk_mul_f32 v[174:175], v[174:175], v[62:63]
	v_pk_mul_f32 v[176:177], v[176:177], v[64:65]
	v_pk_mul_f32 v[178:179], v[178:179], v[58:59]
	v_pk_mul_f32 v[180:181], v[180:181], v[60:61]
	v_pk_mul_f32 v[174:175], v[174:175], v[166:167]
	v_pk_mul_f32 v[176:177], v[176:177], v[168:169]
	v_pk_mul_f32 v[178:179], v[178:179], v[170:171]
	v_pk_mul_f32 v[180:181], v[180:181], v[172:173]
	v_cvt_pk_bf16_f32 v174, v174, v175
	v_cvt_pk_bf16_f32 v175, v176, v177
	v_cvt_pk_bf16_f32 v176, v178, v179
	v_cvt_pk_bf16_f32 v177, v180, v181
	v_add_u32_e32 v132, 0x40000, v130
	global_store_dwordx4 v132, v[174:177], s[4:5]
	s_waitcnt vmcnt(15)
	v_pk_mul_f32 v[166:167], v[54:55], s[100:101] op_sel_hi:[1,0]
	v_pk_mul_f32 v[168:169], v[56:57], s[100:101] op_sel_hi:[1,0]
	v_pk_mul_f32 v[170:171], v[50:51], s[100:101] op_sel_hi:[1,0]
	v_pk_mul_f32 v[172:173], v[52:53], s[100:101] op_sel_hi:[1,0]
	v_exp_f32_e32 v166, v166
	v_exp_f32_e32 v167, v167
	v_exp_f32_e32 v168, v168
	v_exp_f32_e32 v169, v169
	v_exp_f32_e32 v170, v170
	v_exp_f32_e32 v171, v171
	v_exp_f32_e32 v172, v172
	v_exp_f32_e32 v173, v173
	v_lshlrev_b32_e32 v174, 16, v218
	v_and_b32_e32 v175, 0xffff0000, v218
	v_lshlrev_b32_e32 v176, 16, v219
	v_and_b32_e32 v177, 0xffff0000, v219
	v_lshlrev_b32_e32 v178, 16, v220
	v_and_b32_e32 v179, 0xffff0000, v220
	v_lshlrev_b32_e32 v180, 16, v221
	v_and_b32_e32 v181, 0xffff0000, v221
	v_pk_add_f32 v[166:167], v[166:167], 1.0 op_sel_hi:[1,0]
	v_pk_add_f32 v[168:169], v[168:169], 1.0 op_sel_hi:[1,0]
	v_pk_add_f32 v[170:171], v[170:171], 1.0 op_sel_hi:[1,0]
	v_pk_add_f32 v[172:173], v[172:173], 1.0 op_sel_hi:[1,0]
	v_rcp_f32_e32 v166, v166
	v_rcp_f32_e32 v167, v167
	v_rcp_f32_e32 v168, v168
	v_rcp_f32_e32 v169, v169
	v_rcp_f32_e32 v170, v170
	v_rcp_f32_e32 v171, v171
	v_rcp_f32_e32 v172, v172
	v_rcp_f32_e32 v173, v173
	v_pk_mul_f32 v[174:175], v[174:175], v[54:55]
	v_pk_mul_f32 v[176:177], v[176:177], v[56:57]
	v_pk_mul_f32 v[178:179], v[178:179], v[50:51]
	v_pk_mul_f32 v[180:181], v[180:181], v[52:53]
	v_pk_mul_f32 v[174:175], v[174:175], v[166:167]
	v_pk_mul_f32 v[176:177], v[176:177], v[168:169]
	v_pk_mul_f32 v[178:179], v[178:179], v[170:171]
	v_pk_mul_f32 v[180:181], v[180:181], v[172:173]
	v_cvt_pk_bf16_f32 v174, v174, v175
	v_cvt_pk_bf16_f32 v175, v176, v177
	v_cvt_pk_bf16_f32 v176, v178, v179
	v_cvt_pk_bf16_f32 v177, v180, v181
	v_add_u32_e32 v132, 0x40000, v130
	global_store_dwordx4 v132, v[174:177], s[4:5] offset:256
	s_waitcnt vmcnt(14)
	v_pk_mul_f32 v[166:167], v[46:47], s[100:101] op_sel_hi:[1,0]
	v_pk_mul_f32 v[168:169], v[48:49], s[100:101] op_sel_hi:[1,0]
	v_pk_mul_f32 v[170:171], v[42:43], s[100:101] op_sel_hi:[1,0]
	v_pk_mul_f32 v[172:173], v[44:45], s[100:101] op_sel_hi:[1,0]
	v_exp_f32_e32 v166, v166
	v_exp_f32_e32 v167, v167
	v_exp_f32_e32 v168, v168
	v_exp_f32_e32 v169, v169
	v_exp_f32_e32 v170, v170
	v_exp_f32_e32 v171, v171
	v_exp_f32_e32 v172, v172
	v_exp_f32_e32 v173, v173
	v_lshlrev_b32_e32 v174, 16, v182
	v_and_b32_e32 v175, 0xffff0000, v182
	v_lshlrev_b32_e32 v176, 16, v183
	v_and_b32_e32 v177, 0xffff0000, v183
	v_lshlrev_b32_e32 v178, 16, v184
	v_and_b32_e32 v179, 0xffff0000, v184
	v_lshlrev_b32_e32 v180, 16, v185
	v_and_b32_e32 v181, 0xffff0000, v185
	v_pk_add_f32 v[166:167], v[166:167], 1.0 op_sel_hi:[1,0]
	v_pk_add_f32 v[168:169], v[168:169], 1.0 op_sel_hi:[1,0]
	v_pk_add_f32 v[170:171], v[170:171], 1.0 op_sel_hi:[1,0]
	v_pk_add_f32 v[172:173], v[172:173], 1.0 op_sel_hi:[1,0]
	v_rcp_f32_e32 v166, v166
	v_rcp_f32_e32 v167, v167
	v_rcp_f32_e32 v168, v168
	v_rcp_f32_e32 v169, v169
	v_rcp_f32_e32 v170, v170
	v_rcp_f32_e32 v171, v171
	v_rcp_f32_e32 v172, v172
	v_rcp_f32_e32 v173, v173
	v_pk_mul_f32 v[174:175], v[174:175], v[46:47]
	v_pk_mul_f32 v[176:177], v[176:177], v[48:49]
	v_pk_mul_f32 v[178:179], v[178:179], v[42:43]
	v_pk_mul_f32 v[180:181], v[180:181], v[44:45]
	v_pk_mul_f32 v[174:175], v[174:175], v[166:167]
	v_pk_mul_f32 v[176:177], v[176:177], v[168:169]
	v_pk_mul_f32 v[178:179], v[178:179], v[170:171]
	v_pk_mul_f32 v[180:181], v[180:181], v[172:173]
	v_cvt_pk_bf16_f32 v174, v174, v175
	v_cvt_pk_bf16_f32 v175, v176, v177
	v_cvt_pk_bf16_f32 v176, v178, v179
	v_cvt_pk_bf16_f32 v177, v180, v181
	v_add_u32_e32 v132, 0x48000, v130
	global_store_dwordx4 v132, v[174:177], s[4:5]
	s_waitcnt vmcnt(13)
; __device__ __forceinline__ unsigned cvt_pk_bf16(float lo, float hi) { unsigned r; asm volatile("v_cvt_pk_bf16_f32 %0, %1, %2" : "=v"(r) : "v"(lo), "v"(hi)); return r; }
;     __device__ __forceinline__ void operator()(const f32x4 (&acc)[2][2][4][2], const Unit& u, int wr, int wc, int fr, int fq) const {
;     ...
;             for (int m = 0; m < 4; ++m) { const size_t ro = (size_t)(row0 + ai * HALF + m * 16) * ldc + col0;
; #pragma unroll
;                 for (int bj = 0; bj < 2; ++bj) { const f32x4 v0 = acc[ai][bj][m][0], v1 = acc[ai][bj][m][1];
;                     const u32x4 gw = *(const u32x4*)(G + ro + bj * HALF);
;                     float r[8]; const float a[8] = {v0[0], v0[1], v0[2], v0[3], v1[0], v1[1], v1[2], v1[3]};
; #pragma unroll
;                     for (int i = 0; i < 4; ++i) { const unsigned w = gw[i]; const float g0 = __builtin_bit_cast(float, w << 16), g1 = __builtin_bit_cast(float, w & 0xffff0000u);
;                         if (MODE == 0) { r[2 * i] = a[2 * i] * __builtin_amdgcn_rcpf(1.0f + __builtin_amdgcn_exp2f(-1.4426950408889634f * g0)); r[2 * i + 1] = a[2 * i + 1] * __builtin_amdgcn_rcpf(1.0f + __builtin_amdgcn_exp2f(-1.4426950408889634f * g1)); }
;                         else { r[2 * i] = g0 * a[2 * i] * __builtin_amdgcn_rcpf(1.0f + __builtin_amdgcn_exp2f(-1.4426950408889634f * a[2 * i])); r[2 * i + 1] = g1 * a[2 * i + 1] * __builtin_amdgcn_rcpf(1.0f + __builtin_amdgcn_exp2f(-1.4426950408889634f * a[2 * i + 1])); } }
;                     if (Add) { const u32x4 aw = *(const u32x4*)(Add + ro + bj * HALF);
; #pragma unroll
;                         for (int i = 0; i < 4; ++i) { const unsigned w = aw[i]; r[2 * i] += __builtin_bit_cast(float, w << 16); r[2 * i + 1] += __builtin_bit_cast(float, w & 0xffff0000u); } }
;                     u32x4 w; w.x = cvt_pk_bf16(r[0], r[1]); w.y = cvt_pk_bf16(r[2], r[3]); w.z = cvt_pk_bf16(r[4], r[5]); w.w = cvt_pk_bf16(r[6], r[7]);
;                     *(u32x4*)(O + ro + bj * HALF) = w; } }
	v_pk_mul_f32 v[166:167], v[38:39], s[100:101] op_sel_hi:[1,0]
	v_pk_mul_f32 v[168:169], v[40:41], s[100:101] op_sel_hi:[1,0]
	v_pk_mul_f32 v[170:171], v[34:35], s[100:101] op_sel_hi:[1,0]
	v_pk_mul_f32 v[172:173], v[36:37], s[100:101] op_sel_hi:[1,0]
	v_exp_f32_e32 v166, v166
	v_exp_f32_e32 v167, v167
	v_exp_f32_e32 v168, v168
	v_exp_f32_e32 v169, v169
	v_exp_f32_e32 v170, v170
	v_exp_f32_e32 v171, v171
	v_exp_f32_e32 v172, v172
	v_exp_f32_e32 v173, v173
	v_lshlrev_b32_e32 v174, 16, v186
	v_and_b32_e32 v175, 0xffff0000, v186
	v_lshlrev_b32_e32 v176, 16, v187
	v_and_b32_e32 v177, 0xffff0000, v187
	v_lshlrev_b32_e32 v178, 16, v188
	v_and_b32_e32 v179, 0xffff0000, v188
	v_lshlrev_b32_e32 v180, 16, v189
	v_and_b32_e32 v181, 0xffff0000, v189
	v_pk_add_f32 v[166:167], v[166:167], 1.0 op_sel_hi:[1,0]
	v_pk_add_f32 v[168:169], v[168:169], 1.0 op_sel_hi:[1,0]
	v_pk_add_f32 v[170:171], v[170:171], 1.0 op_sel_hi:[1,0]
	v_pk_add_f32 v[172:173], v[172:173], 1.0 op_sel_hi:[1,0]
	v_rcp_f32_e32 v166, v166
	v_rcp_f32_e32 v167, v167
	v_rcp_f32_e32 v168, v168
	v_rcp_f32_e32 v169, v169
	v_rcp_f32_e32 v170, v170
	v_rcp_f32_e32 v171, v171
	v_rcp_f32_e32 v172, v172
	v_rcp_f32_e32 v173, v173
	v_pk_mul_f32 v[174:175], v[174:175], v[38:39]
	v_pk_mul_f32 v[176:177], v[176:177], v[40:41]
	v_pk_mul_f32 v[178:179], v[178:179], v[34:35]
	v_pk_mul_f32 v[180:181], v[180:181], v[36:37]
	v_pk_mul_f32 v[174:175], v[174:175], v[166:167]
	v_pk_mul_f32 v[176:177], v[176:177], v[168:169]
	v_pk_mul_f32 v[178:179], v[178:179], v[170:171]
	v_pk_mul_f32 v[180:181], v[180:181], v[172:173]
	v_cvt_pk_bf16_f32 v174, v174, v175
	v_cvt_pk_bf16_f32 v175, v176, v177
	v_cvt_pk_bf16_f32 v176, v178, v179
	v_cvt_pk_bf16_f32 v177, v180, v181
	v_add_u32_e32 v132, 0x48000, v130
	global_store_dwordx4 v132, v[174:177], s[4:5] offset:256
	s_waitcnt vmcnt(12)
	v_pk_mul_f32 v[166:167], v[30:31], s[100:101] op_sel_hi:[1,0]
	v_pk_mul_f32 v[168:169], v[32:33], s[100:101] op_sel_hi:[1,0]
	v_pk_mul_f32 v[170:171], v[26:27], s[100:101] op_sel_hi:[1,0]
	v_pk_mul_f32 v[172:173], v[28:29], s[100:101] op_sel_hi:[1,0]
	v_exp_f32_e32 v166, v166
	v_exp_f32_e32 v167, v167
	v_exp_f32_e32 v168, v168
	v_exp_f32_e32 v169, v169
	v_exp_f32_e32 v170, v170
	v_exp_f32_e32 v171, v171
	v_exp_f32_e32 v172, v172
	v_exp_f32_e32 v173, v173
	v_lshlrev_b32_e32 v174, 16, v190
	v_and_b32_e32 v175, 0xffff0000, v190
	v_lshlrev_b32_e32 v176, 16, v191
	v_and_b32_e32 v177, 0xffff0000, v191
	v_lshlrev_b32_e32 v178, 16, v192
	v_and_b32_e32 v179, 0xffff0000, v192
	v_lshlrev_b32_e32 v180, 16, v193
	v_and_b32_e32 v181, 0xffff0000, v193
	v_pk_add_f32 v[166:167], v[166:167], 1.0 op_sel_hi:[1,0]
	v_pk_add_f32 v[168:169], v[168:169], 1.0 op_sel_hi:[1,0]
	v_pk_add_f32 v[170:171], v[170:171], 1.0 op_sel_hi:[1,0]
	v_pk_add_f32 v[172:173], v[172:173], 1.0 op_sel_hi:[1,0]
	v_rcp_f32_e32 v166, v166
	v_rcp_f32_e32 v167, v167
	v_rcp_f32_e32 v168, v168
	v_rcp_f32_e32 v169, v169
	v_rcp_f32_e32 v170, v170
	v_rcp_f32_e32 v171, v171
	v_rcp_f32_e32 v172, v172
	v_rcp_f32_e32 v173, v173
	v_pk_mul_f32 v[174:175], v[174:175], v[30:31]
	v_pk_mul_f32 v[176:177], v[176:177], v[32:33]
	v_pk_mul_f32 v[178:179], v[178:179], v[26:27]
	v_pk_mul_f32 v[180:181], v[180:181], v[28:29]
	v_pk_mul_f32 v[174:175], v[174:175], v[166:167]
	v_pk_mul_f32 v[176:177], v[176:177], v[168:169]
	v_pk_mul_f32 v[178:179], v[178:179], v[170:171]
	v_pk_mul_f32 v[180:181], v[180:181], v[172:173]
	v_cvt_pk_bf16_f32 v174, v174, v175
	v_cvt_pk_bf16_f32 v175, v176, v177
	v_cvt_pk_bf16_f32 v176, v178, v179
	v_cvt_pk_bf16_f32 v177, v180, v181
	v_add_u32_e32 v132, 0x50000, v130
	global_store_dwordx4 v132, v[174:177], s[4:5]
	s_waitcnt vmcnt(11)
	v_pk_mul_f32 v[166:167], v[22:23], s[100:101] op_sel_hi:[1,0]
	v_pk_mul_f32 v[168:169], v[24:25], s[100:101] op_sel_hi:[1,0]
	v_pk_mul_f32 v[170:171], v[18:19], s[100:101] op_sel_hi:[1,0]
	v_pk_mul_f32 v[172:173], v[20:21], s[100:101] op_sel_hi:[1,0]
	v_exp_f32_e32 v166, v166
	v_exp_f32_e32 v167, v167
	v_exp_f32_e32 v168, v168
	v_exp_f32_e32 v169, v169
	v_exp_f32_e32 v170, v170
	v_exp_f32_e32 v171, v171
	v_exp_f32_e32 v172, v172
	v_exp_f32_e32 v173, v173
	v_lshlrev_b32_e32 v174, 16, v194
	v_and_b32_e32 v175, 0xffff0000, v194
	v_lshlrev_b32_e32 v176, 16, v195
	v_and_b32_e32 v177, 0xffff0000, v195
	v_lshlrev_b32_e32 v178, 16, v196
	v_and_b32_e32 v179, 0xffff0000, v196
	v_lshlrev_b32_e32 v180, 16, v197
	v_and_b32_e32 v181, 0xffff0000, v197
	v_pk_add_f32 v[166:167], v[166:167], 1.0 op_sel_hi:[1,0]
	v_pk_add_f32 v[168:169], v[168:169], 1.0 op_sel_hi:[1,0]
	v_pk_add_f32 v[170:171], v[170:171], 1.0 op_sel_hi:[1,0]
	v_pk_add_f32 v[172:173], v[172:173], 1.0 op_sel_hi:[1,0]
	v_rcp_f32_e32 v166, v166
	v_rcp_f32_e32 v167, v167
	v_rcp_f32_e32 v168, v168
	v_rcp_f32_e32 v169, v169
	v_rcp_f32_e32 v170, v170
	v_rcp_f32_e32 v171, v171
	v_rcp_f32_e32 v172, v172
	v_rcp_f32_e32 v173, v173
	v_pk_mul_f32 v[174:175], v[174:175], v[22:23]
	v_pk_mul_f32 v[176:177], v[176:177], v[24:25]
	v_pk_mul_f32 v[178:179], v[178:179], v[18:19]
	v_pk_mul_f32 v[180:181], v[180:181], v[20:21]
	v_pk_mul_f32 v[174:175], v[174:175], v[166:167]
	v_pk_mul_f32 v[176:177], v[176:177], v[168:169]
	v_pk_mul_f32 v[178:179], v[178:179], v[170:171]
	v_pk_mul_f32 v[180:181], v[180:181], v[172:173]
	v_cvt_pk_bf16_f32 v174, v174, v175
	v_cvt_pk_bf16_f32 v175, v176, v177
	v_cvt_pk_bf16_f32 v176, v178, v179
	v_cvt_pk_bf16_f32 v177, v180, v181
	v_add_u32_e32 v132, 0x50000, v130
	global_store_dwordx4 v132, v[174:177], s[4:5] offset:256
	s_waitcnt vmcnt(10)
; __device__ __forceinline__ unsigned cvt_pk_bf16(float lo, float hi) { unsigned r; asm volatile("v_cvt_pk_bf16_f32 %0, %1, %2" : "=v"(r) : "v"(lo), "v"(hi)); return r; }
;     __device__ __forceinline__ void operator()(const f32x4 (&acc)[2][2][4][2], const Unit& u, int wr, int wc, int fr, int fq) const {
;     ...
;             for (int m = 0; m < 4; ++m) { const size_t ro = (size_t)(row0 + ai * HALF + m * 16) * ldc + col0;
; #pragma unroll
;                 for (int bj = 0; bj < 2; ++bj) { const f32x4 v0 = acc[ai][bj][m][0], v1 = acc[ai][bj][m][1];
;                     const u32x4 gw = *(const u32x4*)(G + ro + bj * HALF);
;                     float r[8]; const float a[8] = {v0[0], v0[1], v0[2], v0[3], v1[0], v1[1], v1[2], v1[3]};
; #pragma unroll
;                     for (int i = 0; i < 4; ++i) { const unsigned w = gw[i]; const float g0 = __builtin_bit_cast(float, w << 16), g1 = __builtin_bit_cast(float, w & 0xffff0000u);
;                         if (MODE == 0) { r[2 * i] = a[2 * i] * __builtin_amdgcn_rcpf(1.0f + __builtin_amdgcn_exp2f(-1.4426950408889634f * g0)); r[2 * i + 1] = a[2 * i + 1] * __builtin_amdgcn_rcpf(1.0f + __builtin_amdgcn_exp2f(-1.4426950408889634f * g1)); }
;                         else { r[2 * i] = g0 * a[2 * i] * __builtin_amdgcn_rcpf(1.0f + __builtin_amdgcn_exp2f(-1.4426950408889634f * a[2 * i])); r[2 * i + 1] = g1 * a[2 * i + 1] * __builtin_amdgcn_rcpf(1.0f + __builtin_amdgcn_exp2f(-1.4426950408889634f * a[2 * i + 1])); } }
;                     if (Add) { const u32x4 aw = *(const u32x4*)(Add + ro + bj * HALF);
; #pragma unroll
;                         for (int i = 0; i < 4; ++i) { const unsigned w = aw[i]; r[2 * i] += __builtin_bit_cast(float, w << 16); r[2 * i + 1] += __builtin_bit_cast(float, w & 0xffff0000u); } }
;                     u32x4 w; w.x = cvt_pk_bf16(r[0], r[1]); w.y = cvt_pk_bf16(r[2], r[3]); w.z = cvt_pk_bf16(r[4], r[5]); w.w = cvt_pk_bf16(r[6], r[7]);
;                     *(u32x4*)(O + ro + bj * HALF) = w; } }
	v_pk_mul_f32 v[166:167], v[14:15], s[100:101] op_sel_hi:[1,0]
	v_pk_mul_f32 v[168:169], v[16:17], s[100:101] op_sel_hi:[1,0]
	v_pk_mul_f32 v[170:171], v[10:11], s[100:101] op_sel_hi:[1,0]
	v_pk_mul_f32 v[172:173], v[12:13], s[100:101] op_sel_hi:[1,0]
	v_exp_f32_e32 v166, v166
	v_exp_f32_e32 v167, v167
	v_exp_f32_e32 v168, v168
	v_exp_f32_e32 v169, v169
	v_exp_f32_e32 v170, v170
	v_exp_f32_e32 v171, v171
	v_exp_f32_e32 v172, v172
	v_exp_f32_e32 v173, v173
	v_lshlrev_b32_e32 v174, 16, v198
	v_and_b32_e32 v175, 0xffff0000, v198
	v_lshlrev_b32_e32 v176, 16, v199
	v_and_b32_e32 v177, 0xffff0000, v199
	v_lshlrev_b32_e32 v178, 16, v200
	v_and_b32_e32 v179, 0xffff0000, v200
	v_lshlrev_b32_e32 v180, 16, v201
	v_and_b32_e32 v181, 0xffff0000, v201
	v_pk_add_f32 v[166:167], v[166:167], 1.0 op_sel_hi:[1,0]
	v_pk_add_f32 v[168:169], v[168:169], 1.0 op_sel_hi:[1,0]
	v_pk_add_f32 v[170:171], v[170:171], 1.0 op_sel_hi:[1,0]
	v_pk_add_f32 v[172:173], v[172:173], 1.0 op_sel_hi:[1,0]
	v_rcp_f32_e32 v166, v166
	v_rcp_f32_e32 v167, v167
	v_rcp_f32_e32 v168, v168
	v_rcp_f32_e32 v169, v169
	v_rcp_f32_e32 v170, v170
	v_rcp_f32_e32 v171, v171
	v_rcp_f32_e32 v172, v172
	v_rcp_f32_e32 v173, v173
	v_pk_mul_f32 v[174:175], v[174:175], v[14:15]
	v_pk_mul_f32 v[176:177], v[176:177], v[16:17]
	v_pk_mul_f32 v[178:179], v[178:179], v[10:11]
	v_pk_mul_f32 v[180:181], v[180:181], v[12:13]
	v_pk_mul_f32 v[174:175], v[174:175], v[166:167]
	v_pk_mul_f32 v[176:177], v[176:177], v[168:169]
	v_pk_mul_f32 v[178:179], v[178:179], v[170:171]
	v_pk_mul_f32 v[180:181], v[180:181], v[172:173]
	v_cvt_pk_bf16_f32 v174, v174, v175
	v_cvt_pk_bf16_f32 v175, v176, v177
	v_cvt_pk_bf16_f32 v176, v178, v179
	v_cvt_pk_bf16_f32 v177, v180, v181
	v_add_u32_e32 v132, 0x58000, v130
	global_store_dwordx4 v132, v[174:177], s[4:5]
	s_waitcnt vmcnt(9)
	v_pk_mul_f32 v[166:167], v[6:7], s[100:101] op_sel_hi:[1,0]
	v_pk_mul_f32 v[168:169], v[8:9], s[100:101] op_sel_hi:[1,0]
	v_pk_mul_f32 v[170:171], v[2:3], s[100:101] op_sel_hi:[1,0]
	v_pk_mul_f32 v[172:173], v[4:5], s[100:101] op_sel_hi:[1,0]
	v_exp_f32_e32 v166, v166
	v_exp_f32_e32 v167, v167
	v_exp_f32_e32 v168, v168
	v_exp_f32_e32 v169, v169
	v_exp_f32_e32 v170, v170
	v_exp_f32_e32 v171, v171
	v_exp_f32_e32 v172, v172
	v_exp_f32_e32 v173, v173
	v_lshlrev_b32_e32 v174, 16, v202
	v_and_b32_e32 v175, 0xffff0000, v202
	v_lshlrev_b32_e32 v176, 16, v203
	v_and_b32_e32 v177, 0xffff0000, v203
	v_lshlrev_b32_e32 v178, 16, v204
	v_and_b32_e32 v179, 0xffff0000, v204
	v_lshlrev_b32_e32 v180, 16, v205
	v_and_b32_e32 v181, 0xffff0000, v205
	v_pk_add_f32 v[166:167], v[166:167], 1.0 op_sel_hi:[1,0]
	v_pk_add_f32 v[168:169], v[168:169], 1.0 op_sel_hi:[1,0]
	v_pk_add_f32 v[170:171], v[170:171], 1.0 op_sel_hi:[1,0]
	v_pk_add_f32 v[172:173], v[172:173], 1.0 op_sel_hi:[1,0]
	v_rcp_f32_e32 v166, v166
	v_rcp_f32_e32 v167, v167
	v_rcp_f32_e32 v168, v168
	v_rcp_f32_e32 v169, v169
	v_rcp_f32_e32 v170, v170
	v_rcp_f32_e32 v171, v171
	v_rcp_f32_e32 v172, v172
	v_rcp_f32_e32 v173, v173
	v_pk_mul_f32 v[174:175], v[174:175], v[6:7]
	v_pk_mul_f32 v[176:177], v[176:177], v[8:9]
	v_pk_mul_f32 v[178:179], v[178:179], v[2:3]
	v_pk_mul_f32 v[180:181], v[180:181], v[4:5]
	v_pk_mul_f32 v[174:175], v[174:175], v[166:167]
	v_pk_mul_f32 v[176:177], v[176:177], v[168:169]
	v_pk_mul_f32 v[178:179], v[178:179], v[170:171]
	v_pk_mul_f32 v[180:181], v[180:181], v[172:173]
	v_cvt_pk_bf16_f32 v174, v174, v175
	v_cvt_pk_bf16_f32 v175, v176, v177
	v_cvt_pk_bf16_f32 v176, v178, v179
	v_cvt_pk_bf16_f32 v177, v180, v181
	v_add_u32_e32 v132, 0x58000, v130
	global_store_dwordx4 v132, v[174:177], s[4:5] offset:256
	s_and_b64 vcc, exec, s[2:3]
	s_mov_b64 s[2:3], -1
	s_cbranch_vccnz .LBB0_793

; __device__ __forceinline__ unsigned cvt_pk_bf16(float lo, float hi) { unsigned r; asm volatile("v_cvt_pk_bf16_f32 %0, %1, %2" : "=v"(r) : "v"(lo), "v"(hi)); return r; }
;     __device__ __forceinline__ void operator()(const f32x4 (&acc)[2][2][4][2], const Unit& u, int wr, int wc, int fr, int fq) const {
;     ...
;             for (int m = 0; m < 4; ++m) { const size_t ro = (size_t)(row0 + ai * HALF + m * 16) * ldc + col0;
; #pragma unroll
;                 for (int bj = 0; bj < 2; ++bj) { const f32x4 v0 = acc[ai][bj][m][0], v1 = acc[ai][bj][m][1];
;                     const u32x4 gw = *(const u32x4*)(G + ro + bj * HALF);
;                     float r[8]; const float a[8] = {v0[0], v0[1], v0[2], v0[3], v1[0], v1[1], v1[2], v1[3]};
; #pragma unroll
;                     for (int i = 0; i < 4; ++i) { const unsigned w = gw[i]; const float g0 = __builtin_bit_cast(float, w << 16), g1 = __builtin_bit_cast(float, w & 0xffff0000u);
;                         if (MODE == 0) { r[2 * i] = a[2 * i] * __builtin_amdgcn_rcpf(1.0f + __builtin_amdgcn_exp2f(-1.4426950408889634f * g0)); r[2 * i + 1] = a[2 * i + 1] * __builtin_amdgcn_rcpf(1.0f + __builtin_amdgcn_exp2f(-1.4426950408889634f * g1)); }
;                         else { r[2 * i] = g0 * a[2 * i] * __builtin_amdgcn_rcpf(1.0f + __builtin_amdgcn_exp2f(-1.4426950408889634f * a[2 * i])); r[2 * i + 1] = g1 * a[2 * i + 1] * __builtin_amdgcn_rcpf(1.0f + __builtin_amdgcn_exp2f(-1.4426950408889634f * a[2 * i + 1])); } }
;                     if (Add) { const u32x4 aw = *(const u32x4*)(Add + ro + bj * HALF);
; #pragma unroll
;                         for (int i = 0; i < 4; ++i) { const unsigned w = aw[i]; r[2 * i] += __builtin_bit_cast(float, w << 16); r[2 * i + 1] += __builtin_bit_cast(float, w & 0xffff0000u); } }
;                     u32x4 w; w.x = cvt_pk_bf16(r[0], r[1]); w.y = cvt_pk_bf16(r[2], r[3]); w.z = cvt_pk_bf16(r[4], r[5]); w.w = cvt_pk_bf16(r[6], r[7]);
;                     *(u32x4*)(O + ro + bj * HALF) = w; } }
;     __device__ __forceinline__ void operator()(const f32x4 (&acc)[2][2][4][2], const Unit& u, int wr, int wc, int fr, int fq) const {
;     ...
;         else { Unit v; v.pm = u.pm - nM; v.pn = u.pn - nN; EpiGate<0> E{merged, gates + gate_stride, m1, 1024, 0}; E(acc, v, wr, wc, fr, fq); }
.LBB0_887:
	s_lshl_b32 s17, s42, 8
	s_lshl_b32 s19, s43, 8
	s_cmp_gt_i32 s42, 63
	s_mov_b64 s[42:43], -1
	s_cbranch_scc0 .LBB0_890
	v_add_u32_e32 v131, s17, v158
	v_add_u32_e32 v132, s19, v157
	v_lshl_add_u32 v130, v131, 10, v132
	v_lshlrev_b32_e32 v130, 1, v130
	s_mov_b32 s100, 0xbfb8aa3b
	v_mov_b32_e32 v131, v130
	global_load_dwordx4 v[170:173], v131, s[10:11]
	global_load_dwordx4 v[174:177], v131, s[6:7]
	v_mov_b32_e32 v131, v130
	global_load_dwordx4 v[178:181], v131, s[10:11] offset:256
	global_load_dwordx4 v[182:185], v131, s[6:7] offset:256
	v_add_u32_e32 v131, 0x8000, v130
	global_load_dwordx4 v[186:189], v131, s[10:11]
	global_load_dwordx4 v[190:193], v131, s[6:7]
	v_add_u32_e32 v131, 0x8000, v130
	global_load_dwordx4 v[194:197], v131, s[10:11] offset:256
	global_load_dwordx4 v[198:201], v131, s[6:7] offset:256
	v_add_u32_e32 v131, 0x10000, v130
	global_load_dwordx4 v[202:205], v131, s[10:11]
	global_load_dwordx4 v[206:209], v131, s[6:7]
	s_waitcnt vmcnt(8)
	v_lshlrev_b32_e32 v146, 16, v170
	v_and_b32_e32 v147, 0xffff0000, v170
	v_lshlrev_b32_e32 v148, 16, v171
	v_and_b32_e32 v149, 0xffff0000, v171
	v_lshlrev_b32_e32 v150, 16, v172
	v_and_b32_e32 v151, 0xffff0000, v172
	v_lshlrev_b32_e32 v152, 16, v173
	v_and_b32_e32 v153, 0xffff0000, v173
	v_pk_mul_f32 v[146:147], v[146:147], s[100:101] op_sel_hi:[1,0]
	v_pk_mul_f32 v[148:149], v[148:149], s[100:101] op_sel_hi:[1,0]
	v_pk_mul_f32 v[150:151], v[150:151], s[100:101] op_sel_hi:[1,0]
	v_pk_mul_f32 v[152:153], v[152:153], s[100:101] op_sel_hi:[1,0]
	v_exp_f32_e32 v146, v146
	v_exp_f32_e32 v147, v147
	v_exp_f32_e32 v148, v148
	v_exp_f32_e32 v149, v149
	v_exp_f32_e32 v150, v150
	v_exp_f32_e32 v151, v151
	v_exp_f32_e32 v152, v152
	v_exp_f32_e32 v153, v153
	v_pk_add_f32 v[146:147], v[146:147], 1.0 op_sel_hi:[1,0]
	v_pk_add_f32 v[148:149], v[148:149], 1.0 op_sel_hi:[1,0]
	v_pk_add_f32 v[150:151], v[150:151], 1.0 op_sel_hi:[1,0]
	v_pk_add_f32 v[152:153], v[152:153], 1.0 op_sel_hi:[1,0]
	v_rcp_f32_e32 v146, v146
	v_rcp_f32_e32 v147, v147
	v_rcp_f32_e32 v148, v148
	v_rcp_f32_e32 v149, v149
	v_rcp_f32_e32 v150, v150
	v_rcp_f32_e32 v151, v151
	v_rcp_f32_e32 v152, v152
	v_rcp_f32_e32 v153, v153
	v_lshlrev_b32_e32 v162, 16, v174
	v_and_b32_e32 v163, 0xffff0000, v174
	v_lshlrev_b32_e32 v164, 16, v175
	v_and_b32_e32 v165, 0xffff0000, v175
	v_lshlrev_b32_e32 v166, 16, v176
	v_and_b32_e32 v167, 0xffff0000, v176
	v_lshlrev_b32_e32 v168, 16, v177
	v_and_b32_e32 v169, 0xffff0000, v177
	v_pk_fma_f32 v[162:163], v[126:127], v[146:147], v[162:163]
	v_pk_fma_f32 v[164:165], v[128:129], v[148:149], v[164:165]
	v_pk_fma_f32 v[166:167], v[122:123], v[150:151], v[166:167]
	v_pk_fma_f32 v[168:169], v[124:125], v[152:153], v[168:169]
	v_cvt_pk_bf16_f32 v162, v162, v163
	v_cvt_pk_bf16_f32 v163, v164, v165
	v_cvt_pk_bf16_f32 v164, v166, v167
	v_cvt_pk_bf16_f32 v165, v168, v169
	v_mov_b32_e32 v132, v130
	global_store_dwordx4 v132, v[162:165], s[8:9]
	v_add_u32_e32 v131, 0x10000, v130
	global_load_dwordx4 v[170:173], v131, s[10:11] offset:256
	global_load_dwordx4 v[174:177], v131, s[6:7] offset:256
	s_waitcnt vmcnt(9)
	v_lshlrev_b32_e32 v146, 16, v178
	v_and_b32_e32 v147, 0xffff0000, v178
	v_lshlrev_b32_e32 v148, 16, v179
	v_and_b32_e32 v149, 0xffff0000, v179
	v_lshlrev_b32_e32 v150, 16, v180
	v_and_b32_e32 v151, 0xffff0000, v180
	v_lshlrev_b32_e32 v152, 16, v181
	v_and_b32_e32 v153, 0xffff0000, v181
	v_pk_mul_f32 v[146:147], v[146:147], s[100:101] op_sel_hi:[1,0]
	v_pk_mul_f32 v[148:149], v[148:149], s[100:101] op_sel_hi:[1,0]
	v_pk_mul_f32 v[150:151], v[150:151], s[100:101] op_sel_hi:[1,0]
	v_pk_mul_f32 v[152:153], v[152:153], s[100:101] op_sel_hi:[1,0]
	v_exp_f32_e32 v146, v146
	v_exp_f32_e32 v147, v147
	v_exp_f32_e32 v148, v148
	v_exp_f32_e32 v149, v149
	v_exp_f32_e32 v150, v150
	v_exp_f32_e32 v151, v151
	v_exp_f32_e32 v152, v152
	v_exp_f32_e32 v153, v153
	v_pk_add_f32 v[146:147], v[146:147], 1.0 op_sel_hi:[1,0]
	v_pk_add_f32 v[148:149], v[148:149], 1.0 op_sel_hi:[1,0]
	v_pk_add_f32 v[150:151], v[150:151], 1.0 op_sel_hi:[1,0]
	v_pk_add_f32 v[152:153], v[152:153], 1.0 op_sel_hi:[1,0]
	v_rcp_f32_e32 v146, v146
	v_rcp_f32_e32 v147, v147
	v_rcp_f32_e32 v148, v148
	v_rcp_f32_e32 v149, v149
	v_rcp_f32_e32 v150, v150
	v_rcp_f32_e32 v151, v151
	v_rcp_f32_e32 v152, v152
	v_rcp_f32_e32 v153, v153
	v_lshlrev_b32_e32 v162, 16, v182
	v_and_b32_e32 v163, 0xffff0000, v182
	v_lshlrev_b32_e32 v164, 16, v183
	v_and_b32_e32 v165, 0xffff0000, v183
	v_lshlrev_b32_e32 v166, 16, v184
	v_and_b32_e32 v167, 0xffff0000, v184
	v_lshlrev_b32_e32 v168, 16, v185
	v_and_b32_e32 v169, 0xffff0000, v185
	v_pk_fma_f32 v[162:163], v[118:119], v[146:147], v[162:163]
	v_pk_fma_f32 v[164:165], v[120:121], v[148:149], v[164:165]
	v_pk_fma_f32 v[166:167], v[114:115], v[150:151], v[166:167]
	v_pk_fma_f32 v[168:169], v[116:117], v[152:153], v[168:169]
	v_cvt_pk_bf16_f32 v162, v162, v163
	v_cvt_pk_bf16_f32 v163, v164, v165
	v_cvt_pk_bf16_f32 v164, v166, v167
	v_cvt_pk_bf16_f32 v165, v168, v169
	v_mov_b32_e32 v132, v130
	global_store_dwordx4 v132, v[162:165], s[8:9] offset:256
	v_add_u32_e32 v131, 0x18000, v130
	global_load_dwordx4 v[178:181], v131, s[10:11]
	global_load_dwordx4 v[182:185], v131, s[6:7]
	s_waitcnt vmcnt(10)
; __device__ __forceinline__ unsigned cvt_pk_bf16(float lo, float hi) { unsigned r; asm volatile("v_cvt_pk_bf16_f32 %0, %1, %2" : "=v"(r) : "v"(lo), "v"(hi)); return r; }
;     __device__ __forceinline__ void operator()(const f32x4 (&acc)[2][2][4][2], const Unit& u, int wr, int wc, int fr, int fq) const {
;     ...
;             for (int m = 0; m < 4; ++m) { const size_t ro = (size_t)(row0 + ai * HALF + m * 16) * ldc + col0;
; #pragma unroll
;                 for (int bj = 0; bj < 2; ++bj) { const f32x4 v0 = acc[ai][bj][m][0], v1 = acc[ai][bj][m][1];
;                     const u32x4 gw = *(const u32x4*)(G + ro + bj * HALF);
;                     float r[8]; const float a[8] = {v0[0], v0[1], v0[2], v0[3], v1[0], v1[1], v1[2], v1[3]};
; #pragma unroll
;                     for (int i = 0; i < 4; ++i) { const unsigned w = gw[i]; const float g0 = __builtin_bit_cast(float, w << 16), g1 = __builtin_bit_cast(float, w & 0xffff0000u);
;                         if (MODE == 0) { r[2 * i] = a[2 * i] * __builtin_amdgcn_rcpf(1.0f + __builtin_amdgcn_exp2f(-1.4426950408889634f * g0)); r[2 * i + 1] = a[2 * i + 1] * __builtin_amdgcn_rcpf(1.0f + __builtin_amdgcn_exp2f(-1.4426950408889634f * g1)); }
;                         else { r[2 * i] = g0 * a[2 * i] * __builtin_amdgcn_rcpf(1.0f + __builtin_amdgcn_exp2f(-1.4426950408889634f * a[2 * i])); r[2 * i + 1] = g1 * a[2 * i + 1] * __builtin_amdgcn_rcpf(1.0f + __builtin_amdgcn_exp2f(-1.4426950408889634f * a[2 * i + 1])); } }
;                     if (Add) { const u32x4 aw = *(const u32x4*)(Add + ro + bj * HALF);
; #pragma unroll
;                         for (int i = 0; i < 4; ++i) { const unsigned w = aw[i]; r[2 * i] += __builtin_bit_cast(float, w << 16); r[2 * i + 1] += __builtin_bit_cast(float, w & 0xffff0000u); } }
;                     u32x4 w; w.x = cvt_pk_bf16(r[0], r[1]); w.y = cvt_pk_bf16(r[2], r[3]); w.z = cvt_pk_bf16(r[4], r[5]); w.w = cvt_pk_bf16(r[6], r[7]);
;                     *(u32x4*)(O + ro + bj * HALF) = w; } }
;     __device__ __forceinline__ void operator()(const f32x4 (&acc)[2][2][4][2], const Unit& u, int wr, int wc, int fr, int fq) const {
;     ...
;         else { Unit v; v.pm = u.pm - nM; v.pn = u.pn - nN; EpiGate<0> E{merged, gates + gate_stride, m1, 1024, 0}; E(acc, v, wr, wc, fr, fq); }
	v_lshlrev_b32_e32 v146, 16, v186
	v_and_b32_e32 v147, 0xffff0000, v186
	v_lshlrev_b32_e32 v148, 16, v187
	v_and_b32_e32 v149, 0xffff0000, v187
	v_lshlrev_b32_e32 v150, 16, v188
	v_and_b32_e32 v151, 0xffff0000, v188
	v_lshlrev_b32_e32 v152, 16, v189
	v_and_b32_e32 v153, 0xffff0000, v189
	v_pk_mul_f32 v[146:147], v[146:147], s[100:101] op_sel_hi:[1,0]
	v_pk_mul_f32 v[148:149], v[148:149], s[100:101] op_sel_hi:[1,0]
	v_pk_mul_f32 v[150:151], v[150:151], s[100:101] op_sel_hi:[1,0]
	v_pk_mul_f32 v[152:153], v[152:153], s[100:101] op_sel_hi:[1,0]
	v_exp_f32_e32 v146, v146
	v_exp_f32_e32 v147, v147
	v_exp_f32_e32 v148, v148
	v_exp_f32_e32 v149, v149
	v_exp_f32_e32 v150, v150
	v_exp_f32_e32 v151, v151
	v_exp_f32_e32 v152, v152
	v_exp_f32_e32 v153, v153
	v_pk_add_f32 v[146:147], v[146:147], 1.0 op_sel_hi:[1,0]
	v_pk_add_f32 v[148:149], v[148:149], 1.0 op_sel_hi:[1,0]
	v_pk_add_f32 v[150:151], v[150:151], 1.0 op_sel_hi:[1,0]
	v_pk_add_f32 v[152:153], v[152:153], 1.0 op_sel_hi:[1,0]
	v_rcp_f32_e32 v146, v146
	v_rcp_f32_e32 v147, v147
	v_rcp_f32_e32 v148, v148
	v_rcp_f32_e32 v149, v149
	v_rcp_f32_e32 v150, v150
	v_rcp_f32_e32 v151, v151
	v_rcp_f32_e32 v152, v152
	v_rcp_f32_e32 v153, v153
	v_lshlrev_b32_e32 v162, 16, v190
	v_and_b32_e32 v163, 0xffff0000, v190
	v_lshlrev_b32_e32 v164, 16, v191
	v_and_b32_e32 v165, 0xffff0000, v191
	v_lshlrev_b32_e32 v166, 16, v192
	v_and_b32_e32 v167, 0xffff0000, v192
	v_lshlrev_b32_e32 v168, 16, v193
	v_and_b32_e32 v169, 0xffff0000, v193
	v_pk_fma_f32 v[162:163], v[110:111], v[146:147], v[162:163]
	v_pk_fma_f32 v[164:165], v[112:113], v[148:149], v[164:165]
	v_pk_fma_f32 v[166:167], v[106:107], v[150:151], v[166:167]
	v_pk_fma_f32 v[168:169], v[108:109], v[152:153], v[168:169]
	v_cvt_pk_bf16_f32 v162, v162, v163
	v_cvt_pk_bf16_f32 v163, v164, v165
	v_cvt_pk_bf16_f32 v164, v166, v167
	v_cvt_pk_bf16_f32 v165, v168, v169
	v_add_u32_e32 v132, 0x8000, v130
	global_store_dwordx4 v132, v[162:165], s[8:9]
	v_add_u32_e32 v131, 0x18000, v130
	global_load_dwordx4 v[186:189], v131, s[10:11] offset:256
	global_load_dwordx4 v[190:193], v131, s[6:7] offset:256
	s_waitcnt vmcnt(11)
	v_lshlrev_b32_e32 v146, 16, v194
	v_and_b32_e32 v147, 0xffff0000, v194
	v_lshlrev_b32_e32 v148, 16, v195
	v_and_b32_e32 v149, 0xffff0000, v195
	v_lshlrev_b32_e32 v150, 16, v196
	v_and_b32_e32 v151, 0xffff0000, v196
	v_lshlrev_b32_e32 v152, 16, v197
	v_and_b32_e32 v153, 0xffff0000, v197
	v_pk_mul_f32 v[146:147], v[146:147], s[100:101] op_sel_hi:[1,0]
	v_pk_mul_f32 v[148:149], v[148:149], s[100:101] op_sel_hi:[1,0]
	v_pk_mul_f32 v[150:151], v[150:151], s[100:101] op_sel_hi:[1,0]
	v_pk_mul_f32 v[152:153], v[152:153], s[100:101] op_sel_hi:[1,0]
	v_exp_f32_e32 v146, v146
	v_exp_f32_e32 v147, v147
	v_exp_f32_e32 v148, v148
	v_exp_f32_e32 v149, v149
	v_exp_f32_e32 v150, v150
	v_exp_f32_e32 v151, v151
	v_exp_f32_e32 v152, v152
	v_exp_f32_e32 v153, v153
	v_pk_add_f32 v[146:147], v[146:147], 1.0 op_sel_hi:[1,0]
	v_pk_add_f32 v[148:149], v[148:149], 1.0 op_sel_hi:[1,0]
	v_pk_add_f32 v[150:151], v[150:151], 1.0 op_sel_hi:[1,0]
	v_pk_add_f32 v[152:153], v[152:153], 1.0 op_sel_hi:[1,0]
	v_rcp_f32_e32 v146, v146
	v_rcp_f32_e32 v147, v147
	v_rcp_f32_e32 v148, v148
	v_rcp_f32_e32 v149, v149
	v_rcp_f32_e32 v150, v150
	v_rcp_f32_e32 v151, v151
	v_rcp_f32_e32 v152, v152
	v_rcp_f32_e32 v153, v153
	v_lshlrev_b32_e32 v162, 16, v198
	v_and_b32_e32 v163, 0xffff0000, v198
	v_lshlrev_b32_e32 v164, 16, v199
	v_and_b32_e32 v165, 0xffff0000, v199
	v_lshlrev_b32_e32 v166, 16, v200
	v_and_b32_e32 v167, 0xffff0000, v200
	v_lshlrev_b32_e32 v168, 16, v201
	v_and_b32_e32 v169, 0xffff0000, v201
	v_pk_fma_f32 v[162:163], v[102:103], v[146:147], v[162:163]
	v_pk_fma_f32 v[164:165], v[104:105], v[148:149], v[164:165]
	v_pk_fma_f32 v[166:167], v[98:99], v[150:151], v[166:167]
	v_pk_fma_f32 v[168:169], v[100:101], v[152:153], v[168:169]
	v_cvt_pk_bf16_f32 v162, v162, v163
	v_cvt_pk_bf16_f32 v163, v164, v165
	v_cvt_pk_bf16_f32 v164, v166, v167
	v_cvt_pk_bf16_f32 v165, v168, v169
	v_add_u32_e32 v132, 0x8000, v130
	global_store_dwordx4 v132, v[162:165], s[8:9] offset:256
	v_add_u32_e32 v131, 0x40000, v130
	global_load_dwordx4 v[194:197], v131, s[10:11]
	global_load_dwordx4 v[198:201], v131, s[6:7]
	s_waitcnt vmcnt(12)
	v_lshlrev_b32_e32 v146, 16, v202
	v_and_b32_e32 v147, 0xffff0000, v202
	v_lshlrev_b32_e32 v148, 16, v203
	v_and_b32_e32 v149, 0xffff0000, v203
	v_lshlrev_b32_e32 v150, 16, v204
	v_and_b32_e32 v151, 0xffff0000, v204
	v_lshlrev_b32_e32 v152, 16, v205
	v_and_b32_e32 v153, 0xffff0000, v205
	v_pk_mul_f32 v[146:147], v[146:147], s[100:101] op_sel_hi:[1,0]
	v_pk_mul_f32 v[148:149], v[148:149], s[100:101] op_sel_hi:[1,0]
	v_pk_mul_f32 v[150:151], v[150:151], s[100:101] op_sel_hi:[1,0]
	v_pk_mul_f32 v[152:153], v[152:153], s[100:101] op_sel_hi:[1,0]
	v_exp_f32_e32 v146, v146
	v_exp_f32_e32 v147, v147
	v_exp_f32_e32 v148, v148
	v_exp_f32_e32 v149, v149
	v_exp_f32_e32 v150, v150
	v_exp_f32_e32 v151, v151
	v_exp_f32_e32 v152, v152
	v_exp_f32_e32 v153, v153
	v_pk_add_f32 v[146:147], v[146:147], 1.0 op_sel_hi:[1,0]
	v_pk_add_f32 v[148:149], v[148:149], 1.0 op_sel_hi:[1,0]
	v_pk_add_f32 v[150:151], v[150:151], 1.0 op_sel_hi:[1,0]
	v_pk_add_f32 v[152:153], v[152:153], 1.0 op_sel_hi:[1,0]
	v_rcp_f32_e32 v146, v146
	v_rcp_f32_e32 v147, v147
	v_rcp_f32_e32 v148, v148
	v_rcp_f32_e32 v149, v149
	v_rcp_f32_e32 v150, v150
	v_rcp_f32_e32 v151, v151
	v_rcp_f32_e32 v152, v152
	v_rcp_f32_e32 v153, v153
	v_lshlrev_b32_e32 v162, 16, v206
	v_and_b32_e32 v163, 0xffff0000, v206
	v_lshlrev_b32_e32 v164, 16, v207
	v_and_b32_e32 v165, 0xffff0000, v207
	v_lshlrev_b32_e32 v166, 16, v208
	v_and_b32_e32 v167, 0xffff0000, v208
	v_lshlrev_b32_e32 v168, 16, v209
	v_and_b32_e32 v169, 0xffff0000, v209
	v_pk_fma_f32 v[162:163], v[94:95], v[146:147], v[162:163]
	v_pk_fma_f32 v[164:165], v[96:97], v[148:149], v[164:165]
	v_pk_fma_f32 v[166:167], v[90:91], v[150:151], v[166:167]
	v_pk_fma_f32 v[168:169], v[92:93], v[152:153], v[168:169]
	v_cvt_pk_bf16_f32 v162, v162, v163
	v_cvt_pk_bf16_f32 v163, v164, v165
	v_cvt_pk_bf16_f32 v164, v166, v167
	v_cvt_pk_bf16_f32 v165, v168, v169
	v_add_u32_e32 v132, 0x10000, v130
	global_store_dwordx4 v132, v[162:165], s[8:9]
	v_add_u32_e32 v131, 0x40000, v130
	global_load_dwordx4 v[202:205], v131, s[10:11] offset:256
	global_load_dwordx4 v[206:209], v131, s[6:7] offset:256
	s_waitcnt vmcnt(12)
; __device__ __forceinline__ unsigned cvt_pk_bf16(float lo, float hi) { unsigned r; asm volatile("v_cvt_pk_bf16_f32 %0, %1, %2" : "=v"(r) : "v"(lo), "v"(hi)); return r; }
;     __device__ __forceinline__ void operator()(const f32x4 (&acc)[2][2][4][2], const Unit& u, int wr, int wc, int fr, int fq) const {
;     ...
;             for (int m = 0; m < 4; ++m) { const size_t ro = (size_t)(row0 + ai * HALF + m * 16) * ldc + col0;
; #pragma unroll
;                 for (int bj = 0; bj < 2; ++bj) { const f32x4 v0 = acc[ai][bj][m][0], v1 = acc[ai][bj][m][1];
;                     const u32x4 gw = *(const u32x4*)(G + ro + bj * HALF);
;                     float r[8]; const float a[8] = {v0[0], v0[1], v0[2], v0[3], v1[0], v1[1], v1[2], v1[3]};
; #pragma unroll
;                     for (int i = 0; i < 4; ++i) { const unsigned w = gw[i]; const float g0 = __builtin_bit_cast(float, w << 16), g1 = __builtin_bit_cast(float, w & 0xffff0000u);
;                         if (MODE == 0) { r[2 * i] = a[2 * i] * __builtin_amdgcn_rcpf(1.0f + __builtin_amdgcn_exp2f(-1.4426950408889634f * g0)); r[2 * i + 1] = a[2 * i + 1] * __builtin_amdgcn_rcpf(1.0f + __builtin_amdgcn_exp2f(-1.4426950408889634f * g1)); }
;                         else { r[2 * i] = g0 * a[2 * i] * __builtin_amdgcn_rcpf(1.0f + __builtin_amdgcn_exp2f(-1.4426950408889634f * a[2 * i])); r[2 * i + 1] = g1 * a[2 * i + 1] * __builtin_amdgcn_rcpf(1.0f + __builtin_amdgcn_exp2f(-1.4426950408889634f * a[2 * i + 1])); } }
;                     if (Add) { const u32x4 aw = *(const u32x4*)(Add + ro + bj * HALF);
; #pragma unroll
;                         for (int i = 0; i < 4; ++i) { const unsigned w = aw[i]; r[2 * i] += __builtin_bit_cast(float, w << 16); r[2 * i + 1] += __builtin_bit_cast(float, w & 0xffff0000u); } }
;                     u32x4 w; w.x = cvt_pk_bf16(r[0], r[1]); w.y = cvt_pk_bf16(r[2], r[3]); w.z = cvt_pk_bf16(r[4], r[5]); w.w = cvt_pk_bf16(r[6], r[7]);
;                     *(u32x4*)(O + ro + bj * HALF) = w; } }
;     __device__ __forceinline__ void operator()(const f32x4 (&acc)[2][2][4][2], const Unit& u, int wr, int wc, int fr, int fq) const {
;     ...
;         else { Unit v; v.pm = u.pm - nM; v.pn = u.pn - nN; EpiGate<0> E{merged, gates + gate_stride, m1, 1024, 0}; E(acc, v, wr, wc, fr, fq); }
	v_lshlrev_b32_e32 v146, 16, v170
	v_and_b32_e32 v147, 0xffff0000, v170
	v_lshlrev_b32_e32 v148, 16, v171
	v_and_b32_e32 v149, 0xffff0000, v171
	v_lshlrev_b32_e32 v150, 16, v172
	v_and_b32_e32 v151, 0xffff0000, v172
	v_lshlrev_b32_e32 v152, 16, v173
	v_and_b32_e32 v153, 0xffff0000, v173
	v_pk_mul_f32 v[146:147], v[146:147], s[100:101] op_sel_hi:[1,0]
	v_pk_mul_f32 v[148:149], v[148:149], s[100:101] op_sel_hi:[1,0]
	v_pk_mul_f32 v[150:151], v[150:151], s[100:101] op_sel_hi:[1,0]
	v_pk_mul_f32 v[152:153], v[152:153], s[100:101] op_sel_hi:[1,0]
	v_exp_f32_e32 v146, v146
	v_exp_f32_e32 v147, v147
	v_exp_f32_e32 v148, v148
	v_exp_f32_e32 v149, v149
	v_exp_f32_e32 v150, v150
	v_exp_f32_e32 v151, v151
	v_exp_f32_e32 v152, v152
	v_exp_f32_e32 v153, v153
	v_pk_add_f32 v[146:147], v[146:147], 1.0 op_sel_hi:[1,0]
	v_pk_add_f32 v[148:149], v[148:149], 1.0 op_sel_hi:[1,0]
	v_pk_add_f32 v[150:151], v[150:151], 1.0 op_sel_hi:[1,0]
	v_pk_add_f32 v[152:153], v[152:153], 1.0 op_sel_hi:[1,0]
	v_rcp_f32_e32 v146, v146
	v_rcp_f32_e32 v147, v147
	v_rcp_f32_e32 v148, v148
	v_rcp_f32_e32 v149, v149
	v_rcp_f32_e32 v150, v150
	v_rcp_f32_e32 v151, v151
	v_rcp_f32_e32 v152, v152
	v_rcp_f32_e32 v153, v153
	v_lshlrev_b32_e32 v162, 16, v174
	v_and_b32_e32 v163, 0xffff0000, v174
	v_lshlrev_b32_e32 v164, 16, v175
	v_and_b32_e32 v165, 0xffff0000, v175
	v_lshlrev_b32_e32 v166, 16, v176
	v_and_b32_e32 v167, 0xffff0000, v176
	v_lshlrev_b32_e32 v168, 16, v177
	v_and_b32_e32 v169, 0xffff0000, v177
	v_pk_fma_f32 v[162:163], v[86:87], v[146:147], v[162:163]
	v_pk_fma_f32 v[164:165], v[88:89], v[148:149], v[164:165]
	v_pk_fma_f32 v[166:167], v[82:83], v[150:151], v[166:167]
	v_pk_fma_f32 v[168:169], v[84:85], v[152:153], v[168:169]
	v_cvt_pk_bf16_f32 v162, v162, v163
	v_cvt_pk_bf16_f32 v163, v164, v165
	v_cvt_pk_bf16_f32 v164, v166, v167
	v_cvt_pk_bf16_f32 v165, v168, v169
	v_add_u32_e32 v132, 0x10000, v130
	global_store_dwordx4 v132, v[162:165], s[8:9] offset:256
	v_add_u32_e32 v131, 0x48000, v130
	global_load_dwordx4 v[170:173], v131, s[10:11]
	global_load_dwordx4 v[174:177], v131, s[6:7]
	s_waitcnt vmcnt(12)
	v_lshlrev_b32_e32 v146, 16, v178
	v_and_b32_e32 v147, 0xffff0000, v178
	v_lshlrev_b32_e32 v148, 16, v179
	v_and_b32_e32 v149, 0xffff0000, v179
	v_lshlrev_b32_e32 v150, 16, v180
	v_and_b32_e32 v151, 0xffff0000, v180
	v_lshlrev_b32_e32 v152, 16, v181
	v_and_b32_e32 v153, 0xffff0000, v181
	v_pk_mul_f32 v[146:147], v[146:147], s[100:101] op_sel_hi:[1,0]
	v_pk_mul_f32 v[148:149], v[148:149], s[100:101] op_sel_hi:[1,0]
	v_pk_mul_f32 v[150:151], v[150:151], s[100:101] op_sel_hi:[1,0]
	v_pk_mul_f32 v[152:153], v[152:153], s[100:101] op_sel_hi:[1,0]
	v_exp_f32_e32 v146, v146
	v_exp_f32_e32 v147, v147
	v_exp_f32_e32 v148, v148
	v_exp_f32_e32 v149, v149
	v_exp_f32_e32 v150, v150
	v_exp_f32_e32 v151, v151
	v_exp_f32_e32 v152, v152
	v_exp_f32_e32 v153, v153
	v_pk_add_f32 v[146:147], v[146:147], 1.0 op_sel_hi:[1,0]
	v_pk_add_f32 v[148:149], v[148:149], 1.0 op_sel_hi:[1,0]
	v_pk_add_f32 v[150:151], v[150:151], 1.0 op_sel_hi:[1,0]
	v_pk_add_f32 v[152:153], v[152:153], 1.0 op_sel_hi:[1,0]
	v_rcp_f32_e32 v146, v146
	v_rcp_f32_e32 v147, v147
	v_rcp_f32_e32 v148, v148
	v_rcp_f32_e32 v149, v149
	v_rcp_f32_e32 v150, v150
	v_rcp_f32_e32 v151, v151
	v_rcp_f32_e32 v152, v152
	v_rcp_f32_e32 v153, v153
	v_lshlrev_b32_e32 v162, 16, v182
	v_and_b32_e32 v163, 0xffff0000, v182
	v_lshlrev_b32_e32 v164, 16, v183
	v_and_b32_e32 v165, 0xffff0000, v183
	v_lshlrev_b32_e32 v166, 16, v184
	v_and_b32_e32 v167, 0xffff0000, v184
	v_lshlrev_b32_e32 v168, 16, v185
	v_and_b32_e32 v169, 0xffff0000, v185
	v_pk_fma_f32 v[162:163], v[78:79], v[146:147], v[162:163]
	v_pk_fma_f32 v[164:165], v[80:81], v[148:149], v[164:165]
	v_pk_fma_f32 v[166:167], v[74:75], v[150:151], v[166:167]
	v_pk_fma_f32 v[168:169], v[76:77], v[152:153], v[168:169]
	v_cvt_pk_bf16_f32 v162, v162, v163
	v_cvt_pk_bf16_f32 v163, v164, v165
	v_cvt_pk_bf16_f32 v164, v166, v167
	v_cvt_pk_bf16_f32 v165, v168, v169
	v_add_u32_e32 v132, 0x18000, v130
	global_store_dwordx4 v132, v[162:165], s[8:9]
	v_add_u32_e32 v131, 0x48000, v130
	global_load_dwordx4 v[178:181], v131, s[10:11] offset:256
	global_load_dwordx4 v[182:185], v131, s[6:7] offset:256
	s_waitcnt vmcnt(12)
	v_lshlrev_b32_e32 v146, 16, v186
	v_and_b32_e32 v147, 0xffff0000, v186
	v_lshlrev_b32_e32 v148, 16, v187
	v_and_b32_e32 v149, 0xffff0000, v187
	v_lshlrev_b32_e32 v150, 16, v188
	v_and_b32_e32 v151, 0xffff0000, v188
	v_lshlrev_b32_e32 v152, 16, v189
	v_and_b32_e32 v153, 0xffff0000, v189
	v_pk_mul_f32 v[146:147], v[146:147], s[100:101] op_sel_hi:[1,0]
	v_pk_mul_f32 v[148:149], v[148:149], s[100:101] op_sel_hi:[1,0]
	v_pk_mul_f32 v[150:151], v[150:151], s[100:101] op_sel_hi:[1,0]
	v_pk_mul_f32 v[152:153], v[152:153], s[100:101] op_sel_hi:[1,0]
	v_exp_f32_e32 v146, v146
	v_exp_f32_e32 v147, v147
	v_exp_f32_e32 v148, v148
	v_exp_f32_e32 v149, v149
	v_exp_f32_e32 v150, v150
	v_exp_f32_e32 v151, v151
	v_exp_f32_e32 v152, v152
	v_exp_f32_e32 v153, v153
	v_pk_add_f32 v[146:147], v[146:147], 1.0 op_sel_hi:[1,0]
	v_pk_add_f32 v[148:149], v[148:149], 1.0 op_sel_hi:[1,0]
	v_pk_add_f32 v[150:151], v[150:151], 1.0 op_sel_hi:[1,0]
	v_pk_add_f32 v[152:153], v[152:153], 1.0 op_sel_hi:[1,0]
	v_rcp_f32_e32 v146, v146
	v_rcp_f32_e32 v147, v147
	v_rcp_f32_e32 v148, v148
	v_rcp_f32_e32 v149, v149
	v_rcp_f32_e32 v150, v150
	v_rcp_f32_e32 v151, v151
	v_rcp_f32_e32 v152, v152
	v_rcp_f32_e32 v153, v153
	v_lshlrev_b32_e32 v162, 16, v190
	v_and_b32_e32 v163, 0xffff0000, v190
	v_lshlrev_b32_e32 v164, 16, v191
	v_and_b32_e32 v165, 0xffff0000, v191
	v_lshlrev_b32_e32 v166, 16, v192
	v_and_b32_e32 v167, 0xffff0000, v192
	v_lshlrev_b32_e32 v168, 16, v193
	v_and_b32_e32 v169, 0xffff0000, v193
	v_pk_fma_f32 v[162:163], v[70:71], v[146:147], v[162:163]
	v_pk_fma_f32 v[164:165], v[72:73], v[148:149], v[164:165]
	v_pk_fma_f32 v[166:167], v[66:67], v[150:151], v[166:167]
	v_pk_fma_f32 v[168:169], v[68:69], v[152:153], v[168:169]
	v_cvt_pk_bf16_f32 v162, v162, v163
	v_cvt_pk_bf16_f32 v163, v164, v165
	v_cvt_pk_bf16_f32 v164, v166, v167
	v_cvt_pk_bf16_f32 v165, v168, v169
	v_add_u32_e32 v132, 0x18000, v130
	global_store_dwordx4 v132, v[162:165], s[8:9] offset:256
	v_add_u32_e32 v131, 0x50000, v130
	global_load_dwordx4 v[186:189], v131, s[10:11]
	global_load_dwordx4 v[190:193], v131, s[6:7]
	s_waitcnt vmcnt(12)
; __device__ __forceinline__ unsigned cvt_pk_bf16(float lo, float hi) { unsigned r; asm volatile("v_cvt_pk_bf16_f32 %0, %1, %2" : "=v"(r) : "v"(lo), "v"(hi)); return r; }
;     __device__ __forceinline__ void operator()(const f32x4 (&acc)[2][2][4][2], const Unit& u, int wr, int wc, int fr, int fq) const {
;     ...
;             for (int m = 0; m < 4; ++m) { const size_t ro = (size_t)(row0 + ai * HALF + m * 16) * ldc + col0;
; #pragma unroll
;                 for (int bj = 0; bj < 2; ++bj) { const f32x4 v0 = acc[ai][bj][m][0], v1 = acc[ai][bj][m][1];
;                     const u32x4 gw = *(const u32x4*)(G + ro + bj * HALF);
;                     float r[8]; const float a[8] = {v0[0], v0[1], v0[2], v0[3], v1[0], v1[1], v1[2], v1[3]};
; #pragma unroll
;                     for (int i = 0; i < 4; ++i) { const unsigned w = gw[i]; const float g0 = __builtin_bit_cast(float, w << 16), g1 = __builtin_bit_cast(float, w & 0xffff0000u);
;                         if (MODE == 0) { r[2 * i] = a[2 * i] * __builtin_amdgcn_rcpf(1.0f + __builtin_amdgcn_exp2f(-1.4426950408889634f * g0)); r[2 * i + 1] = a[2 * i + 1] * __builtin_amdgcn_rcpf(1.0f + __builtin_amdgcn_exp2f(-1.4426950408889634f * g1)); }
;                         else { r[2 * i] = g0 * a[2 * i] * __builtin_amdgcn_rcpf(1.0f + __builtin_amdgcn_exp2f(-1.4426950408889634f * a[2 * i])); r[2 * i + 1] = g1 * a[2 * i + 1] * __builtin_amdgcn_rcpf(1.0f + __builtin_amdgcn_exp2f(-1.4426950408889634f * a[2 * i + 1])); } }
;                     if (Add) { const u32x4 aw = *(const u32x4*)(Add + ro + bj * HALF);
; #pragma unroll
;                         for (int i = 0; i < 4; ++i) { const unsigned w = aw[i]; r[2 * i] += __builtin_bit_cast(float, w << 16); r[2 * i + 1] += __builtin_bit_cast(float, w & 0xffff0000u); } }
;                     u32x4 w; w.x = cvt_pk_bf16(r[0], r[1]); w.y = cvt_pk_bf16(r[2], r[3]); w.z = cvt_pk_bf16(r[4], r[5]); w.w = cvt_pk_bf16(r[6], r[7]);
;                     *(u32x4*)(O + ro + bj * HALF) = w; } }
;     __device__ __forceinline__ void operator()(const f32x4 (&acc)[2][2][4][2], const Unit& u, int wr, int wc, int fr, int fq) const {
;     ...
;         else { Unit v; v.pm = u.pm - nM; v.pn = u.pn - nN; EpiGate<0> E{merged, gates + gate_stride, m1, 1024, 0}; E(acc, v, wr, wc, fr, fq); }
	v_lshlrev_b32_e32 v146, 16, v194
	v_and_b32_e32 v147, 0xffff0000, v194
	v_lshlrev_b32_e32 v148, 16, v195
	v_and_b32_e32 v149, 0xffff0000, v195
	v_lshlrev_b32_e32 v150, 16, v196
	v_and_b32_e32 v151, 0xffff0000, v196
	v_lshlrev_b32_e32 v152, 16, v197
	v_and_b32_e32 v153, 0xffff0000, v197
	v_pk_mul_f32 v[146:147], v[146:147], s[100:101] op_sel_hi:[1,0]
	v_pk_mul_f32 v[148:149], v[148:149], s[100:101] op_sel_hi:[1,0]
	v_pk_mul_f32 v[150:151], v[150:151], s[100:101] op_sel_hi:[1,0]
	v_pk_mul_f32 v[152:153], v[152:153], s[100:101] op_sel_hi:[1,0]
	v_exp_f32_e32 v146, v146
	v_exp_f32_e32 v147, v147
	v_exp_f32_e32 v148, v148
	v_exp_f32_e32 v149, v149
	v_exp_f32_e32 v150, v150
	v_exp_f32_e32 v151, v151
	v_exp_f32_e32 v152, v152
	v_exp_f32_e32 v153, v153
	v_pk_add_f32 v[146:147], v[146:147], 1.0 op_sel_hi:[1,0]
	v_pk_add_f32 v[148:149], v[148:149], 1.0 op_sel_hi:[1,0]
	v_pk_add_f32 v[150:151], v[150:151], 1.0 op_sel_hi:[1,0]
	v_pk_add_f32 v[152:153], v[152:153], 1.0 op_sel_hi:[1,0]
	v_rcp_f32_e32 v146, v146
	v_rcp_f32_e32 v147, v147
	v_rcp_f32_e32 v148, v148
	v_rcp_f32_e32 v149, v149
	v_rcp_f32_e32 v150, v150
	v_rcp_f32_e32 v151, v151
	v_rcp_f32_e32 v152, v152
	v_rcp_f32_e32 v153, v153
	v_lshlrev_b32_e32 v162, 16, v198
	v_and_b32_e32 v163, 0xffff0000, v198
	v_lshlrev_b32_e32 v164, 16, v199
	v_and_b32_e32 v165, 0xffff0000, v199
	v_lshlrev_b32_e32 v166, 16, v200
	v_and_b32_e32 v167, 0xffff0000, v200
	v_lshlrev_b32_e32 v168, 16, v201
	v_and_b32_e32 v169, 0xffff0000, v201
	v_pk_fma_f32 v[162:163], v[62:63], v[146:147], v[162:163]
	v_pk_fma_f32 v[164:165], v[64:65], v[148:149], v[164:165]
	v_pk_fma_f32 v[166:167], v[58:59], v[150:151], v[166:167]
	v_pk_fma_f32 v[168:169], v[60:61], v[152:153], v[168:169]
	v_cvt_pk_bf16_f32 v162, v162, v163
	v_cvt_pk_bf16_f32 v163, v164, v165
	v_cvt_pk_bf16_f32 v164, v166, v167
	v_cvt_pk_bf16_f32 v165, v168, v169
	v_add_u32_e32 v132, 0x40000, v130
	global_store_dwordx4 v132, v[162:165], s[8:9]
	v_add_u32_e32 v131, 0x50000, v130
	global_load_dwordx4 v[194:197], v131, s[10:11] offset:256
	global_load_dwordx4 v[198:201], v131, s[6:7] offset:256
	s_waitcnt vmcnt(12)
	v_lshlrev_b32_e32 v146, 16, v202
	v_and_b32_e32 v147, 0xffff0000, v202
	v_lshlrev_b32_e32 v148, 16, v203
	v_and_b32_e32 v149, 0xffff0000, v203
	v_lshlrev_b32_e32 v150, 16, v204
	v_and_b32_e32 v151, 0xffff0000, v204
	v_lshlrev_b32_e32 v152, 16, v205
	v_and_b32_e32 v153, 0xffff0000, v205
	v_pk_mul_f32 v[146:147], v[146:147], s[100:101] op_sel_hi:[1,0]
	v_pk_mul_f32 v[148:149], v[148:149], s[100:101] op_sel_hi:[1,0]
	v_pk_mul_f32 v[150:151], v[150:151], s[100:101] op_sel_hi:[1,0]
	v_pk_mul_f32 v[152:153], v[152:153], s[100:101] op_sel_hi:[1,0]
	v_exp_f32_e32 v146, v146
	v_exp_f32_e32 v147, v147
	v_exp_f32_e32 v148, v148
	v_exp_f32_e32 v149, v149
	v_exp_f32_e32 v150, v150
	v_exp_f32_e32 v151, v151
	v_exp_f32_e32 v152, v152
	v_exp_f32_e32 v153, v153
	v_pk_add_f32 v[146:147], v[146:147], 1.0 op_sel_hi:[1,0]
	v_pk_add_f32 v[148:149], v[148:149], 1.0 op_sel_hi:[1,0]
	v_pk_add_f32 v[150:151], v[150:151], 1.0 op_sel_hi:[1,0]
	v_pk_add_f32 v[152:153], v[152:153], 1.0 op_sel_hi:[1,0]
	v_rcp_f32_e32 v146, v146
	v_rcp_f32_e32 v147, v147
	v_rcp_f32_e32 v148, v148
	v_rcp_f32_e32 v149, v149
	v_rcp_f32_e32 v150, v150
	v_rcp_f32_e32 v151, v151
	v_rcp_f32_e32 v152, v152
	v_rcp_f32_e32 v153, v153
	v_lshlrev_b32_e32 v162, 16, v206
	v_and_b32_e32 v163, 0xffff0000, v206
	v_lshlrev_b32_e32 v164, 16, v207
	v_and_b32_e32 v165, 0xffff0000, v207
	v_lshlrev_b32_e32 v166, 16, v208
	v_and_b32_e32 v167, 0xffff0000, v208
	v_lshlrev_b32_e32 v168, 16, v209
	v_and_b32_e32 v169, 0xffff0000, v209
	v_pk_fma_f32 v[162:163], v[54:55], v[146:147], v[162:163]
	v_pk_fma_f32 v[164:165], v[56:57], v[148:149], v[164:165]
	v_pk_fma_f32 v[166:167], v[50:51], v[150:151], v[166:167]
	v_pk_fma_f32 v[168:169], v[52:53], v[152:153], v[168:169]
	v_cvt_pk_bf16_f32 v162, v162, v163
	v_cvt_pk_bf16_f32 v163, v164, v165
	v_cvt_pk_bf16_f32 v164, v166, v167
	v_cvt_pk_bf16_f32 v165, v168, v169
	v_add_u32_e32 v132, 0x40000, v130
	global_store_dwordx4 v132, v[162:165], s[8:9] offset:256
	v_add_u32_e32 v131, 0x58000, v130
	global_load_dwordx4 v[202:205], v131, s[10:11]
	global_load_dwordx4 v[206:209], v131, s[6:7]
	s_waitcnt vmcnt(12)
	v_lshlrev_b32_e32 v146, 16, v170
	v_and_b32_e32 v147, 0xffff0000, v170
	v_lshlrev_b32_e32 v148, 16, v171
	v_and_b32_e32 v149, 0xffff0000, v171
	v_lshlrev_b32_e32 v150, 16, v172
	v_and_b32_e32 v151, 0xffff0000, v172
	v_lshlrev_b32_e32 v152, 16, v173
	v_and_b32_e32 v153, 0xffff0000, v173
	v_pk_mul_f32 v[146:147], v[146:147], s[100:101] op_sel_hi:[1,0]
	v_pk_mul_f32 v[148:149], v[148:149], s[100:101] op_sel_hi:[1,0]
	v_pk_mul_f32 v[150:151], v[150:151], s[100:101] op_sel_hi:[1,0]
	v_pk_mul_f32 v[152:153], v[152:153], s[100:101] op_sel_hi:[1,0]
	v_exp_f32_e32 v146, v146
	v_exp_f32_e32 v147, v147
	v_exp_f32_e32 v148, v148
	v_exp_f32_e32 v149, v149
	v_exp_f32_e32 v150, v150
	v_exp_f32_e32 v151, v151
	v_exp_f32_e32 v152, v152
	v_exp_f32_e32 v153, v153
	v_pk_add_f32 v[146:147], v[146:147], 1.0 op_sel_hi:[1,0]
	v_pk_add_f32 v[148:149], v[148:149], 1.0 op_sel_hi:[1,0]
	v_pk_add_f32 v[150:151], v[150:151], 1.0 op_sel_hi:[1,0]
	v_pk_add_f32 v[152:153], v[152:153], 1.0 op_sel_hi:[1,0]
	v_rcp_f32_e32 v146, v146
	v_rcp_f32_e32 v147, v147
	v_rcp_f32_e32 v148, v148
	v_rcp_f32_e32 v149, v149
	v_rcp_f32_e32 v150, v150
	v_rcp_f32_e32 v151, v151
	v_rcp_f32_e32 v152, v152
	v_rcp_f32_e32 v153, v153
	v_lshlrev_b32_e32 v162, 16, v174
	v_and_b32_e32 v163, 0xffff0000, v174
	v_lshlrev_b32_e32 v164, 16, v175
	v_and_b32_e32 v165, 0xffff0000, v175
	v_lshlrev_b32_e32 v166, 16, v176
	v_and_b32_e32 v167, 0xffff0000, v176
	v_lshlrev_b32_e32 v168, 16, v177
	v_and_b32_e32 v169, 0xffff0000, v177
	v_pk_fma_f32 v[162:163], v[46:47], v[146:147], v[162:163]
	v_pk_fma_f32 v[164:165], v[48:49], v[148:149], v[164:165]
	v_pk_fma_f32 v[166:167], v[42:43], v[150:151], v[166:167]
	v_pk_fma_f32 v[168:169], v[44:45], v[152:153], v[168:169]
	v_cvt_pk_bf16_f32 v162, v162, v163
	v_cvt_pk_bf16_f32 v163, v164, v165
	v_cvt_pk_bf16_f32 v164, v166, v167
	v_cvt_pk_bf16_f32 v165, v168, v169
	v_add_u32_e32 v132, 0x48000, v130
	global_store_dwordx4 v132, v[162:165], s[8:9]
	v_add_u32_e32 v131, 0x58000, v130
	global_load_dwordx4 v[170:173], v131, s[10:11] offset:256
	global_load_dwordx4 v[174:177], v131, s[6:7] offset:256
	s_waitcnt vmcnt(12)
; __device__ __forceinline__ unsigned cvt_pk_bf16(float lo, float hi) { unsigned r; asm volatile("v_cvt_pk_bf16_f32 %0, %1, %2" : "=v"(r) : "v"(lo), "v"(hi)); return r; }
;     __device__ __forceinline__ void operator()(const f32x4 (&acc)[2][2][4][2], const Unit& u, int wr, int wc, int fr, int fq) const {
;     ...
;             for (int m = 0; m < 4; ++m) { const size_t ro = (size_t)(row0 + ai * HALF + m * 16) * ldc + col0;
; #pragma unroll
;                 for (int bj = 0; bj < 2; ++bj) { const f32x4 v0 = acc[ai][bj][m][0], v1 = acc[ai][bj][m][1];
;                     const u32x4 gw = *(const u32x4*)(G + ro + bj * HALF);
;                     float r[8]; const float a[8] = {v0[0], v0[1], v0[2], v0[3], v1[0], v1[1], v1[2], v1[3]};
; #pragma unroll
;                     for (int i = 0; i < 4; ++i) { const unsigned w = gw[i]; const float g0 = __builtin_bit_cast(float, w << 16), g1 = __builtin_bit_cast(float, w & 0xffff0000u);
;                         if (MODE == 0) { r[2 * i] = a[2 * i] * __builtin_amdgcn_rcpf(1.0f + __builtin_amdgcn_exp2f(-1.4426950408889634f * g0)); r[2 * i + 1] = a[2 * i + 1] * __builtin_amdgcn_rcpf(1.0f + __builtin_amdgcn_exp2f(-1.4426950408889634f * g1)); }
;                         else { r[2 * i] = g0 * a[2 * i] * __builtin_amdgcn_rcpf(1.0f + __builtin_amdgcn_exp2f(-1.4426950408889634f * a[2 * i])); r[2 * i + 1] = g1 * a[2 * i + 1] * __builtin_amdgcn_rcpf(1.0f + __builtin_amdgcn_exp2f(-1.4426950408889634f * a[2 * i + 1])); } }
;                     if (Add) { const u32x4 aw = *(const u32x4*)(Add + ro + bj * HALF);
; #pragma unroll
;                         for (int i = 0; i < 4; ++i) { const unsigned w = aw[i]; r[2 * i] += __builtin_bit_cast(float, w << 16); r[2 * i + 1] += __builtin_bit_cast(float, w & 0xffff0000u); } }
;                     u32x4 w; w.x = cvt_pk_bf16(r[0], r[1]); w.y = cvt_pk_bf16(r[2], r[3]); w.z = cvt_pk_bf16(r[4], r[5]); w.w = cvt_pk_bf16(r[6], r[7]);
;                     *(u32x4*)(O + ro + bj * HALF) = w; } }
;     __device__ __forceinline__ void operator()(const f32x4 (&acc)[2][2][4][2], const Unit& u, int wr, int wc, int fr, int fq) const {
;     ...
;         else { Unit v; v.pm = u.pm - nM; v.pn = u.pn - nN; EpiGate<0> E{merged, gates + gate_stride, m1, 1024, 0}; E(acc, v, wr, wc, fr, fq); }
	v_lshlrev_b32_e32 v146, 16, v178
	v_and_b32_e32 v147, 0xffff0000, v178
	v_lshlrev_b32_e32 v148, 16, v179
	v_and_b32_e32 v149, 0xffff0000, v179
	v_lshlrev_b32_e32 v150, 16, v180
	v_and_b32_e32 v151, 0xffff0000, v180
	v_lshlrev_b32_e32 v152, 16, v181
	v_and_b32_e32 v153, 0xffff0000, v181
	v_pk_mul_f32 v[146:147], v[146:147], s[100:101] op_sel_hi:[1,0]
	v_pk_mul_f32 v[148:149], v[148:149], s[100:101] op_sel_hi:[1,0]
	v_pk_mul_f32 v[150:151], v[150:151], s[100:101] op_sel_hi:[1,0]
	v_pk_mul_f32 v[152:153], v[152:153], s[100:101] op_sel_hi:[1,0]
	v_exp_f32_e32 v146, v146
	v_exp_f32_e32 v147, v147
	v_exp_f32_e32 v148, v148
	v_exp_f32_e32 v149, v149
	v_exp_f32_e32 v150, v150
	v_exp_f32_e32 v151, v151
	v_exp_f32_e32 v152, v152
	v_exp_f32_e32 v153, v153
	v_pk_add_f32 v[146:147], v[146:147], 1.0 op_sel_hi:[1,0]
	v_pk_add_f32 v[148:149], v[148:149], 1.0 op_sel_hi:[1,0]
	v_pk_add_f32 v[150:151], v[150:151], 1.0 op_sel_hi:[1,0]
	v_pk_add_f32 v[152:153], v[152:153], 1.0 op_sel_hi:[1,0]
	v_rcp_f32_e32 v146, v146
	v_rcp_f32_e32 v147, v147
	v_rcp_f32_e32 v148, v148
	v_rcp_f32_e32 v149, v149
	v_rcp_f32_e32 v150, v150
	v_rcp_f32_e32 v151, v151
	v_rcp_f32_e32 v152, v152
	v_rcp_f32_e32 v153, v153
	v_lshlrev_b32_e32 v162, 16, v182
	v_and_b32_e32 v163, 0xffff0000, v182
	v_lshlrev_b32_e32 v164, 16, v183
	v_and_b32_e32 v165, 0xffff0000, v183
	v_lshlrev_b32_e32 v166, 16, v184
	v_and_b32_e32 v167, 0xffff0000, v184
	v_lshlrev_b32_e32 v168, 16, v185
	v_and_b32_e32 v169, 0xffff0000, v185
	v_pk_fma_f32 v[162:163], v[38:39], v[146:147], v[162:163]
	v_pk_fma_f32 v[164:165], v[40:41], v[148:149], v[164:165]
	v_pk_fma_f32 v[166:167], v[34:35], v[150:151], v[166:167]
	v_pk_fma_f32 v[168:169], v[36:37], v[152:153], v[168:169]
	v_cvt_pk_bf16_f32 v162, v162, v163
	v_cvt_pk_bf16_f32 v163, v164, v165
	v_cvt_pk_bf16_f32 v164, v166, v167
	v_cvt_pk_bf16_f32 v165, v168, v169
	v_add_u32_e32 v132, 0x48000, v130
	global_store_dwordx4 v132, v[162:165], s[8:9] offset:256
	s_waitcnt vmcnt(10)
	v_lshlrev_b32_e32 v146, 16, v186
	v_and_b32_e32 v147, 0xffff0000, v186
	v_lshlrev_b32_e32 v148, 16, v187
	v_and_b32_e32 v149, 0xffff0000, v187
	v_lshlrev_b32_e32 v150, 16, v188
	v_and_b32_e32 v151, 0xffff0000, v188
	v_lshlrev_b32_e32 v152, 16, v189
	v_and_b32_e32 v153, 0xffff0000, v189
	v_pk_mul_f32 v[146:147], v[146:147], s[100:101] op_sel_hi:[1,0]
	v_pk_mul_f32 v[148:149], v[148:149], s[100:101] op_sel_hi:[1,0]
	v_pk_mul_f32 v[150:151], v[150:151], s[100:101] op_sel_hi:[1,0]
	v_pk_mul_f32 v[152:153], v[152:153], s[100:101] op_sel_hi:[1,0]
	v_exp_f32_e32 v146, v146
	v_exp_f32_e32 v147, v147
	v_exp_f32_e32 v148, v148
	v_exp_f32_e32 v149, v149
	v_exp_f32_e32 v150, v150
	v_exp_f32_e32 v151, v151
	v_exp_f32_e32 v152, v152
	v_exp_f32_e32 v153, v153
	v_pk_add_f32 v[146:147], v[146:147], 1.0 op_sel_hi:[1,0]
	v_pk_add_f32 v[148:149], v[148:149], 1.0 op_sel_hi:[1,0]
	v_pk_add_f32 v[150:151], v[150:151], 1.0 op_sel_hi:[1,0]
	v_pk_add_f32 v[152:153], v[152:153], 1.0 op_sel_hi:[1,0]
	v_rcp_f32_e32 v146, v146
	v_rcp_f32_e32 v147, v147
	v_rcp_f32_e32 v148, v148
	v_rcp_f32_e32 v149, v149
	v_rcp_f32_e32 v150, v150
	v_rcp_f32_e32 v151, v151
	v_rcp_f32_e32 v152, v152
	v_rcp_f32_e32 v153, v153
	v_lshlrev_b32_e32 v162, 16, v190
	v_and_b32_e32 v163, 0xffff0000, v190
	v_lshlrev_b32_e32 v164, 16, v191
	v_and_b32_e32 v165, 0xffff0000, v191
	v_lshlrev_b32_e32 v166, 16, v192
	v_and_b32_e32 v167, 0xffff0000, v192
	v_lshlrev_b32_e32 v168, 16, v193
	v_and_b32_e32 v169, 0xffff0000, v193
	v_pk_fma_f32 v[162:163], v[30:31], v[146:147], v[162:163]
	v_pk_fma_f32 v[164:165], v[32:33], v[148:149], v[164:165]
	v_pk_fma_f32 v[166:167], v[26:27], v[150:151], v[166:167]
	v_pk_fma_f32 v[168:169], v[28:29], v[152:153], v[168:169]
	v_cvt_pk_bf16_f32 v162, v162, v163
	v_cvt_pk_bf16_f32 v163, v164, v165
	v_cvt_pk_bf16_f32 v164, v166, v167
	v_cvt_pk_bf16_f32 v165, v168, v169
	v_add_u32_e32 v132, 0x50000, v130
	global_store_dwordx4 v132, v[162:165], s[8:9]
	s_waitcnt vmcnt(8)
	v_lshlrev_b32_e32 v146, 16, v194
	v_and_b32_e32 v147, 0xffff0000, v194
	v_lshlrev_b32_e32 v148, 16, v195
	v_and_b32_e32 v149, 0xffff0000, v195
	v_lshlrev_b32_e32 v150, 16, v196
	v_and_b32_e32 v151, 0xffff0000, v196
	v_lshlrev_b32_e32 v152, 16, v197
	v_and_b32_e32 v153, 0xffff0000, v197
	v_pk_mul_f32 v[146:147], v[146:147], s[100:101] op_sel_hi:[1,0]
	v_pk_mul_f32 v[148:149], v[148:149], s[100:101] op_sel_hi:[1,0]
	v_pk_mul_f32 v[150:151], v[150:151], s[100:101] op_sel_hi:[1,0]
	v_pk_mul_f32 v[152:153], v[152:153], s[100:101] op_sel_hi:[1,0]
	v_exp_f32_e32 v146, v146
	v_exp_f32_e32 v147, v147
	v_exp_f32_e32 v148, v148
	v_exp_f32_e32 v149, v149
	v_exp_f32_e32 v150, v150
	v_exp_f32_e32 v151, v151
	v_exp_f32_e32 v152, v152
	v_exp_f32_e32 v153, v153
	v_pk_add_f32 v[146:147], v[146:147], 1.0 op_sel_hi:[1,0]
	v_pk_add_f32 v[148:149], v[148:149], 1.0 op_sel_hi:[1,0]
	v_pk_add_f32 v[150:151], v[150:151], 1.0 op_sel_hi:[1,0]
	v_pk_add_f32 v[152:153], v[152:153], 1.0 op_sel_hi:[1,0]
	v_rcp_f32_e32 v146, v146
	v_rcp_f32_e32 v147, v147
	v_rcp_f32_e32 v148, v148
	v_rcp_f32_e32 v149, v149
	v_rcp_f32_e32 v150, v150
	v_rcp_f32_e32 v151, v151
	v_rcp_f32_e32 v152, v152
	v_rcp_f32_e32 v153, v153
	v_lshlrev_b32_e32 v162, 16, v198
	v_and_b32_e32 v163, 0xffff0000, v198
	v_lshlrev_b32_e32 v164, 16, v199
	v_and_b32_e32 v165, 0xffff0000, v199
	v_lshlrev_b32_e32 v166, 16, v200
	v_and_b32_e32 v167, 0xffff0000, v200
	v_lshlrev_b32_e32 v168, 16, v201
	v_and_b32_e32 v169, 0xffff0000, v201
	v_pk_fma_f32 v[162:163], v[22:23], v[146:147], v[162:163]
	v_pk_fma_f32 v[164:165], v[24:25], v[148:149], v[164:165]
	v_pk_fma_f32 v[166:167], v[18:19], v[150:151], v[166:167]
	v_pk_fma_f32 v[168:169], v[20:21], v[152:153], v[168:169]
	v_cvt_pk_bf16_f32 v162, v162, v163
	v_cvt_pk_bf16_f32 v163, v164, v165
	v_cvt_pk_bf16_f32 v164, v166, v167
	v_cvt_pk_bf16_f32 v165, v168, v169
	v_add_u32_e32 v132, 0x50000, v130
	global_store_dwordx4 v132, v[162:165], s[8:9] offset:256
	s_waitcnt vmcnt(6)
; __device__ __forceinline__ unsigned cvt_pk_bf16(float lo, float hi) { unsigned r; asm volatile("v_cvt_pk_bf16_f32 %0, %1, %2" : "=v"(r) : "v"(lo), "v"(hi)); return r; }
;     __device__ __forceinline__ void operator()(const f32x4 (&acc)[2][2][4][2], const Unit& u, int wr, int wc, int fr, int fq) const {
;     ...
;             for (int m = 0; m < 4; ++m) { const size_t ro = (size_t)(row0 + ai * HALF + m * 16) * ldc + col0;
; #pragma unroll
;                 for (int bj = 0; bj < 2; ++bj) { const f32x4 v0 = acc[ai][bj][m][0], v1 = acc[ai][bj][m][1];
;                     const u32x4 gw = *(const u32x4*)(G + ro + bj * HALF);
;                     float r[8]; const float a[8] = {v0[0], v0[1], v0[2], v0[3], v1[0], v1[1], v1[2], v1[3]};
; #pragma unroll
;                     for (int i = 0; i < 4; ++i) { const unsigned w = gw[i]; const float g0 = __builtin_bit_cast(float, w << 16), g1 = __builtin_bit_cast(float, w & 0xffff0000u);
;                         if (MODE == 0) { r[2 * i] = a[2 * i] * __builtin_amdgcn_rcpf(1.0f + __builtin_amdgcn_exp2f(-1.4426950408889634f * g0)); r[2 * i + 1] = a[2 * i + 1] * __builtin_amdgcn_rcpf(1.0f + __builtin_amdgcn_exp2f(-1.4426950408889634f * g1)); }
;                         else { r[2 * i] = g0 * a[2 * i] * __builtin_amdgcn_rcpf(1.0f + __builtin_amdgcn_exp2f(-1.4426950408889634f * a[2 * i])); r[2 * i + 1] = g1 * a[2 * i + 1] * __builtin_amdgcn_rcpf(1.0f + __builtin_amdgcn_exp2f(-1.4426950408889634f * a[2 * i + 1])); } }
;                     if (Add) { const u32x4 aw = *(const u32x4*)(Add + ro + bj * HALF);
; #pragma unroll
;                         for (int i = 0; i < 4; ++i) { const unsigned w = aw[i]; r[2 * i] += __builtin_bit_cast(float, w << 16); r[2 * i + 1] += __builtin_bit_cast(float, w & 0xffff0000u); } }
;                     u32x4 w; w.x = cvt_pk_bf16(r[0], r[1]); w.y = cvt_pk_bf16(r[2], r[3]); w.z = cvt_pk_bf16(r[4], r[5]); w.w = cvt_pk_bf16(r[6], r[7]);
;                     *(u32x4*)(O + ro + bj * HALF) = w; } }
;     __device__ __forceinline__ void operator()(const f32x4 (&acc)[2][2][4][2], const Unit& u, int wr, int wc, int fr, int fq) const {
;     ...
;         else { Unit v; v.pm = u.pm - nM; v.pn = u.pn - nN; EpiGate<0> E{merged, gates + gate_stride, m1, 1024, 0}; E(acc, v, wr, wc, fr, fq); }
	v_lshlrev_b32_e32 v146, 16, v202
	v_and_b32_e32 v147, 0xffff0000, v202
	v_lshlrev_b32_e32 v148, 16, v203
	v_and_b32_e32 v149, 0xffff0000, v203
	v_lshlrev_b32_e32 v150, 16, v204
	v_and_b32_e32 v151, 0xffff0000, v204
	v_lshlrev_b32_e32 v152, 16, v205
	v_and_b32_e32 v153, 0xffff0000, v205
	v_pk_mul_f32 v[146:147], v[146:147], s[100:101] op_sel_hi:[1,0]
	v_pk_mul_f32 v[148:149], v[148:149], s[100:101] op_sel_hi:[1,0]
	v_pk_mul_f32 v[150:151], v[150:151], s[100:101] op_sel_hi:[1,0]
	v_pk_mul_f32 v[152:153], v[152:153], s[100:101] op_sel_hi:[1,0]
	v_exp_f32_e32 v146, v146
	v_exp_f32_e32 v147, v147
	v_exp_f32_e32 v148, v148
	v_exp_f32_e32 v149, v149
	v_exp_f32_e32 v150, v150
	v_exp_f32_e32 v151, v151
	v_exp_f32_e32 v152, v152
	v_exp_f32_e32 v153, v153
	v_pk_add_f32 v[146:147], v[146:147], 1.0 op_sel_hi:[1,0]
	v_pk_add_f32 v[148:149], v[148:149], 1.0 op_sel_hi:[1,0]
	v_pk_add_f32 v[150:151], v[150:151], 1.0 op_sel_hi:[1,0]
	v_pk_add_f32 v[152:153], v[152:153], 1.0 op_sel_hi:[1,0]
	v_rcp_f32_e32 v146, v146
	v_rcp_f32_e32 v147, v147
	v_rcp_f32_e32 v148, v148
	v_rcp_f32_e32 v149, v149
	v_rcp_f32_e32 v150, v150
	v_rcp_f32_e32 v151, v151
	v_rcp_f32_e32 v152, v152
	v_rcp_f32_e32 v153, v153
	v_lshlrev_b32_e32 v162, 16, v206
	v_and_b32_e32 v163, 0xffff0000, v206
	v_lshlrev_b32_e32 v164, 16, v207
	v_and_b32_e32 v165, 0xffff0000, v207
	v_lshlrev_b32_e32 v166, 16, v208
	v_and_b32_e32 v167, 0xffff0000, v208
	v_lshlrev_b32_e32 v168, 16, v209
	v_and_b32_e32 v169, 0xffff0000, v209
	v_pk_fma_f32 v[162:163], v[14:15], v[146:147], v[162:163]
	v_pk_fma_f32 v[164:165], v[16:17], v[148:149], v[164:165]
	v_pk_fma_f32 v[166:167], v[10:11], v[150:151], v[166:167]
	v_pk_fma_f32 v[168:169], v[12:13], v[152:153], v[168:169]
	v_cvt_pk_bf16_f32 v162, v162, v163
	v_cvt_pk_bf16_f32 v163, v164, v165
	v_cvt_pk_bf16_f32 v164, v166, v167
	v_cvt_pk_bf16_f32 v165, v168, v169
	v_add_u32_e32 v132, 0x58000, v130
	global_store_dwordx4 v132, v[162:165], s[8:9]
	s_waitcnt vmcnt(4)
	v_lshlrev_b32_e32 v146, 16, v170
	v_and_b32_e32 v147, 0xffff0000, v170
	v_lshlrev_b32_e32 v148, 16, v171
	v_and_b32_e32 v149, 0xffff0000, v171
	v_lshlrev_b32_e32 v150, 16, v172
	v_and_b32_e32 v151, 0xffff0000, v172
	v_lshlrev_b32_e32 v152, 16, v173
	v_and_b32_e32 v153, 0xffff0000, v173
	v_pk_mul_f32 v[146:147], v[146:147], s[100:101] op_sel_hi:[1,0]
	v_pk_mul_f32 v[148:149], v[148:149], s[100:101] op_sel_hi:[1,0]
	v_pk_mul_f32 v[150:151], v[150:151], s[100:101] op_sel_hi:[1,0]
	v_pk_mul_f32 v[152:153], v[152:153], s[100:101] op_sel_hi:[1,0]
	v_exp_f32_e32 v146, v146
	v_exp_f32_e32 v147, v147
	v_exp_f32_e32 v148, v148
	v_exp_f32_e32 v149, v149
	v_exp_f32_e32 v150, v150
	v_exp_f32_e32 v151, v151
	v_exp_f32_e32 v152, v152
	v_exp_f32_e32 v153, v153
	v_pk_add_f32 v[146:147], v[146:147], 1.0 op_sel_hi:[1,0]
	v_pk_add_f32 v[148:149], v[148:149], 1.0 op_sel_hi:[1,0]
	v_pk_add_f32 v[150:151], v[150:151], 1.0 op_sel_hi:[1,0]
	v_pk_add_f32 v[152:153], v[152:153], 1.0 op_sel_hi:[1,0]
	v_rcp_f32_e32 v146, v146
	v_rcp_f32_e32 v147, v147
	v_rcp_f32_e32 v148, v148
	v_rcp_f32_e32 v149, v149
	v_rcp_f32_e32 v150, v150
	v_rcp_f32_e32 v151, v151
	v_rcp_f32_e32 v152, v152
	v_rcp_f32_e32 v153, v153
	v_lshlrev_b32_e32 v162, 16, v174
	v_and_b32_e32 v163, 0xffff0000, v174
	v_lshlrev_b32_e32 v164, 16, v175
	v_and_b32_e32 v165, 0xffff0000, v175
	v_lshlrev_b32_e32 v166, 16, v176
	v_and_b32_e32 v167, 0xffff0000, v176
	v_lshlrev_b32_e32 v168, 16, v177
	v_and_b32_e32 v169, 0xffff0000, v177
	v_pk_fma_f32 v[162:163], v[6:7], v[146:147], v[162:163]
	v_pk_fma_f32 v[164:165], v[8:9], v[148:149], v[164:165]
	v_pk_fma_f32 v[166:167], v[2:3], v[150:151], v[166:167]
	v_pk_fma_f32 v[168:169], v[4:5], v[152:153], v[168:169]
	v_cvt_pk_bf16_f32 v162, v162, v163
	v_cvt_pk_bf16_f32 v163, v164, v165
	v_cvt_pk_bf16_f32 v164, v166, v167
	v_cvt_pk_bf16_f32 v165, v168, v169
	v_add_u32_e32 v132, 0x58000, v130
	global_store_dwordx4 v132, v[162:165], s[8:9] offset:256
	s_and_b64 vcc, exec, s[38:39]
	s_mov_b64 s[38:39], -1
	s_cbranch_vccnz .LBB0_882
	s_branch .LBB0_892

; __device__ __forceinline__ unsigned cvt_pk_bf16(float lo, float hi) { unsigned r; asm volatile("v_cvt_pk_bf16_f32 %0, %1, %2" : "=v"(r) : "v"(lo), "v"(hi)); return r; }
;     __device__ __forceinline__ void operator()(const f32x4 (&acc)[2][2][4][2], const Unit& u, int wr, int wc, int fr, int fq) const {
;     ...
;             for (int m = 0; m < 4; ++m) { const size_t ro = (size_t)(row0 + ai * HALF + m * 16) * ldc + col0;
; #pragma unroll
;                 for (int bj = 0; bj < 2; ++bj) { const f32x4 v0 = acc[ai][bj][m][0], v1 = acc[ai][bj][m][1];
;                     const u32x4 gw = *(const u32x4*)(G + ro + bj * HALF);
;                     float r[8]; const float a[8] = {v0[0], v0[1], v0[2], v0[3], v1[0], v1[1], v1[2], v1[3]};
; #pragma unroll
;                     for (int i = 0; i < 4; ++i) { const unsigned w = gw[i]; const float g0 = __builtin_bit_cast(float, w << 16), g1 = __builtin_bit_cast(float, w & 0xffff0000u);
;                         if (MODE == 0) { r[2 * i] = a[2 * i] * __builtin_amdgcn_rcpf(1.0f + __builtin_amdgcn_exp2f(-1.4426950408889634f * g0)); r[2 * i + 1] = a[2 * i + 1] * __builtin_amdgcn_rcpf(1.0f + __builtin_amdgcn_exp2f(-1.4426950408889634f * g1)); }
;                         else { r[2 * i] = g0 * a[2 * i] * __builtin_amdgcn_rcpf(1.0f + __builtin_amdgcn_exp2f(-1.4426950408889634f * a[2 * i])); r[2 * i + 1] = g1 * a[2 * i + 1] * __builtin_amdgcn_rcpf(1.0f + __builtin_amdgcn_exp2f(-1.4426950408889634f * a[2 * i + 1])); } }
;                     if (Add) { const u32x4 aw = *(const u32x4*)(Add + ro + bj * HALF);
; #pragma unroll
;                         for (int i = 0; i < 4; ++i) { const unsigned w = aw[i]; r[2 * i] += __builtin_bit_cast(float, w << 16); r[2 * i + 1] += __builtin_bit_cast(float, w & 0xffff0000u); } }
;                     u32x4 w; w.x = cvt_pk_bf16(r[0], r[1]); w.y = cvt_pk_bf16(r[2], r[3]); w.z = cvt_pk_bf16(r[4], r[5]); w.w = cvt_pk_bf16(r[6], r[7]);
;                     *(u32x4*)(O + ro + bj * HALF) = w; } }
;     __device__ __forceinline__ void operator()(const f32x4 (&acc)[2][2][4][2], const Unit& u, int wr, int wc, int fr, int fq) const {
;         if (u.pm < nM) { EpiGate<0> E{m1, gates, nullptr, 1024, 0}; E(acc, u, wr, wc, fr, fq); }
.LBB0_891:
	v_readlane_b32 s42, v253, 63
	v_readlane_b32 s43, v252, 0
	v_add_u32_e32 v131, s17, v154
	v_or_b32_e32 v132, s19, v156
	v_lshl_add_u32 v130, v131, 10, v132
	v_lshlrev_b32_e32 v130, 1, v130
	s_mov_b32 s100, 0xbfb8aa3b
	s_nop 1
	v_mov_b32_e32 v131, v130
	global_load_dwordx4 v[170:173], v131, s[42:43]
	v_mov_b32_e32 v131, v130
	global_load_dwordx4 v[174:177], v131, s[42:43] offset:256
	v_add_u32_e32 v131, 0x8000, v130
	global_load_dwordx4 v[178:181], v131, s[42:43]
	v_add_u32_e32 v131, 0x8000, v130
	global_load_dwordx4 v[182:185], v131, s[42:43] offset:256
	v_add_u32_e32 v131, 0x10000, v130
	global_load_dwordx4 v[186:189], v131, s[42:43]
	v_add_u32_e32 v131, 0x10000, v130
	global_load_dwordx4 v[190:193], v131, s[42:43] offset:256
	v_add_u32_e32 v131, 0x18000, v130
	global_load_dwordx4 v[194:197], v131, s[42:43]
	v_add_u32_e32 v131, 0x18000, v130
	global_load_dwordx4 v[198:201], v131, s[42:43] offset:256
	v_add_u32_e32 v131, 0x40000, v130
	global_load_dwordx4 v[202:205], v131, s[42:43]
	v_add_u32_e32 v131, 0x40000, v130
	global_load_dwordx4 v[206:209], v131, s[42:43] offset:256
	v_add_u32_e32 v131, 0x48000, v130
	global_load_dwordx4 v[210:213], v131, s[42:43]
	s_waitcnt vmcnt(10)
	v_lshlrev_b32_e32 v146, 16, v170
	v_and_b32_e32 v147, 0xffff0000, v170
	v_lshlrev_b32_e32 v148, 16, v171
	v_and_b32_e32 v149, 0xffff0000, v171
	v_lshlrev_b32_e32 v150, 16, v172
	v_and_b32_e32 v151, 0xffff0000, v172
	v_lshlrev_b32_e32 v152, 16, v173
	v_and_b32_e32 v153, 0xffff0000, v173
	v_pk_mul_f32 v[146:147], v[146:147], s[100:101] op_sel_hi:[1,0]
	v_pk_mul_f32 v[148:149], v[148:149], s[100:101] op_sel_hi:[1,0]
	v_pk_mul_f32 v[150:151], v[150:151], s[100:101] op_sel_hi:[1,0]
	v_pk_mul_f32 v[152:153], v[152:153], s[100:101] op_sel_hi:[1,0]
	v_exp_f32_e32 v146, v146
	v_exp_f32_e32 v147, v147
	v_exp_f32_e32 v148, v148
	v_exp_f32_e32 v149, v149
	v_exp_f32_e32 v150, v150
	v_exp_f32_e32 v151, v151
	v_exp_f32_e32 v152, v152
	v_exp_f32_e32 v153, v153
	v_pk_add_f32 v[146:147], v[146:147], 1.0 op_sel_hi:[1,0]
	v_pk_add_f32 v[148:149], v[148:149], 1.0 op_sel_hi:[1,0]
	v_pk_add_f32 v[150:151], v[150:151], 1.0 op_sel_hi:[1,0]
	v_pk_add_f32 v[152:153], v[152:153], 1.0 op_sel_hi:[1,0]
	v_rcp_f32_e32 v146, v146
	v_rcp_f32_e32 v147, v147
	v_rcp_f32_e32 v148, v148
	v_rcp_f32_e32 v149, v149
	v_rcp_f32_e32 v150, v150
	v_rcp_f32_e32 v151, v151
	v_rcp_f32_e32 v152, v152
	v_rcp_f32_e32 v153, v153
	v_pk_mul_f32 v[162:163], v[126:127], v[146:147]
	v_pk_mul_f32 v[164:165], v[128:129], v[148:149]
	v_pk_mul_f32 v[166:167], v[122:123], v[150:151]
	v_pk_mul_f32 v[168:169], v[124:125], v[152:153]
	v_cvt_pk_bf16_f32 v162, v162, v163
	v_cvt_pk_bf16_f32 v163, v164, v165
	v_cvt_pk_bf16_f32 v164, v166, v167
	v_cvt_pk_bf16_f32 v165, v168, v169
	v_mov_b32_e32 v132, v130
	global_store_dwordx4 v132, v[162:165], s[6:7]
	v_add_u32_e32 v131, 0x48000, v130
	global_load_dwordx4 v[170:173], v131, s[42:43] offset:256
	s_waitcnt vmcnt(11)
	v_lshlrev_b32_e32 v146, 16, v174
	v_and_b32_e32 v147, 0xffff0000, v174
	v_lshlrev_b32_e32 v148, 16, v175
	v_and_b32_e32 v149, 0xffff0000, v175
	v_lshlrev_b32_e32 v150, 16, v176
	v_and_b32_e32 v151, 0xffff0000, v176
	v_lshlrev_b32_e32 v152, 16, v177
	v_and_b32_e32 v153, 0xffff0000, v177
	v_pk_mul_f32 v[146:147], v[146:147], s[100:101] op_sel_hi:[1,0]
	v_pk_mul_f32 v[148:149], v[148:149], s[100:101] op_sel_hi:[1,0]
	v_pk_mul_f32 v[150:151], v[150:151], s[100:101] op_sel_hi:[1,0]
	v_pk_mul_f32 v[152:153], v[152:153], s[100:101] op_sel_hi:[1,0]
	v_exp_f32_e32 v146, v146
	v_exp_f32_e32 v147, v147
	v_exp_f32_e32 v148, v148
	v_exp_f32_e32 v149, v149
	v_exp_f32_e32 v150, v150
	v_exp_f32_e32 v151, v151
	v_exp_f32_e32 v152, v152
	v_exp_f32_e32 v153, v153
	v_pk_add_f32 v[146:147], v[146:147], 1.0 op_sel_hi:[1,0]
	v_pk_add_f32 v[148:149], v[148:149], 1.0 op_sel_hi:[1,0]
	v_pk_add_f32 v[150:151], v[150:151], 1.0 op_sel_hi:[1,0]
	v_pk_add_f32 v[152:153], v[152:153], 1.0 op_sel_hi:[1,0]
	v_rcp_f32_e32 v146, v146
	v_rcp_f32_e32 v147, v147
	v_rcp_f32_e32 v148, v148
	v_rcp_f32_e32 v149, v149
	v_rcp_f32_e32 v150, v150
	v_rcp_f32_e32 v151, v151
	v_rcp_f32_e32 v152, v152
	v_rcp_f32_e32 v153, v153
	v_pk_mul_f32 v[162:163], v[118:119], v[146:147]
	v_pk_mul_f32 v[164:165], v[120:121], v[148:149]
	v_pk_mul_f32 v[166:167], v[114:115], v[150:151]
	v_pk_mul_f32 v[168:169], v[116:117], v[152:153]
	v_cvt_pk_bf16_f32 v162, v162, v163
	v_cvt_pk_bf16_f32 v163, v164, v165
	v_cvt_pk_bf16_f32 v164, v166, v167
	v_cvt_pk_bf16_f32 v165, v168, v169
	v_mov_b32_e32 v132, v130
	global_store_dwordx4 v132, v[162:165], s[6:7] offset:256
	v_add_u32_e32 v131, 0x50000, v130
	global_load_dwordx4 v[174:177], v131, s[42:43]
	s_waitcnt vmcnt(12)
	v_lshlrev_b32_e32 v146, 16, v178
	v_and_b32_e32 v147, 0xffff0000, v178
	v_lshlrev_b32_e32 v148, 16, v179
	v_and_b32_e32 v149, 0xffff0000, v179
	v_lshlrev_b32_e32 v150, 16, v180
	v_and_b32_e32 v151, 0xffff0000, v180
	v_lshlrev_b32_e32 v152, 16, v181
	v_and_b32_e32 v153, 0xffff0000, v181
	v_pk_mul_f32 v[146:147], v[146:147], s[100:101] op_sel_hi:[1,0]
	v_pk_mul_f32 v[148:149], v[148:149], s[100:101] op_sel_hi:[1,0]
	v_pk_mul_f32 v[150:151], v[150:151], s[100:101] op_sel_hi:[1,0]
	v_pk_mul_f32 v[152:153], v[152:153], s[100:101] op_sel_hi:[1,0]
	v_exp_f32_e32 v146, v146
	v_exp_f32_e32 v147, v147
	v_exp_f32_e32 v148, v148
	v_exp_f32_e32 v149, v149
	v_exp_f32_e32 v150, v150
	v_exp_f32_e32 v151, v151
	v_exp_f32_e32 v152, v152
	v_exp_f32_e32 v153, v153
	v_pk_add_f32 v[146:147], v[146:147], 1.0 op_sel_hi:[1,0]
	v_pk_add_f32 v[148:149], v[148:149], 1.0 op_sel_hi:[1,0]
	v_pk_add_f32 v[150:151], v[150:151], 1.0 op_sel_hi:[1,0]
	v_pk_add_f32 v[152:153], v[152:153], 1.0 op_sel_hi:[1,0]
	v_rcp_f32_e32 v146, v146
	v_rcp_f32_e32 v147, v147
	v_rcp_f32_e32 v148, v148
	v_rcp_f32_e32 v149, v149
	v_rcp_f32_e32 v150, v150
	v_rcp_f32_e32 v151, v151
	v_rcp_f32_e32 v152, v152
	v_rcp_f32_e32 v153, v153
	v_pk_mul_f32 v[162:163], v[110:111], v[146:147]
	v_pk_mul_f32 v[164:165], v[112:113], v[148:149]
	v_pk_mul_f32 v[166:167], v[106:107], v[150:151]
	v_pk_mul_f32 v[168:169], v[108:109], v[152:153]
	v_cvt_pk_bf16_f32 v162, v162, v163
	v_cvt_pk_bf16_f32 v163, v164, v165
	v_cvt_pk_bf16_f32 v164, v166, v167
	v_cvt_pk_bf16_f32 v165, v168, v169
	v_add_u32_e32 v132, 0x8000, v130
	global_store_dwordx4 v132, v[162:165], s[6:7]
	v_add_u32_e32 v131, 0x50000, v130
	global_load_dwordx4 v[178:181], v131, s[42:43] offset:256
	s_waitcnt vmcnt(13)
; __device__ __forceinline__ unsigned cvt_pk_bf16(float lo, float hi) { unsigned r; asm volatile("v_cvt_pk_bf16_f32 %0, %1, %2" : "=v"(r) : "v"(lo), "v"(hi)); return r; }
;     __device__ __forceinline__ void operator()(const f32x4 (&acc)[2][2][4][2], const Unit& u, int wr, int wc, int fr, int fq) const {
;     ...
;             for (int m = 0; m < 4; ++m) { const size_t ro = (size_t)(row0 + ai * HALF + m * 16) * ldc + col0;
; #pragma unroll
;                 for (int bj = 0; bj < 2; ++bj) { const f32x4 v0 = acc[ai][bj][m][0], v1 = acc[ai][bj][m][1];
;                     const u32x4 gw = *(const u32x4*)(G + ro + bj * HALF);
;                     float r[8]; const float a[8] = {v0[0], v0[1], v0[2], v0[3], v1[0], v1[1], v1[2], v1[3]};
; #pragma unroll
;                     for (int i = 0; i < 4; ++i) { const unsigned w = gw[i]; const float g0 = __builtin_bit_cast(float, w << 16), g1 = __builtin_bit_cast(float, w & 0xffff0000u);
;                         if (MODE == 0) { r[2 * i] = a[2 * i] * __builtin_amdgcn_rcpf(1.0f + __builtin_amdgcn_exp2f(-1.4426950408889634f * g0)); r[2 * i + 1] = a[2 * i + 1] * __builtin_amdgcn_rcpf(1.0f + __builtin_amdgcn_exp2f(-1.4426950408889634f * g1)); }
;                         else { r[2 * i] = g0 * a[2 * i] * __builtin_amdgcn_rcpf(1.0f + __builtin_amdgcn_exp2f(-1.4426950408889634f * a[2 * i])); r[2 * i + 1] = g1 * a[2 * i + 1] * __builtin_amdgcn_rcpf(1.0f + __builtin_amdgcn_exp2f(-1.4426950408889634f * a[2 * i + 1])); } }
;                     if (Add) { const u32x4 aw = *(const u32x4*)(Add + ro + bj * HALF);
; #pragma unroll
;                         for (int i = 0; i < 4; ++i) { const unsigned w = aw[i]; r[2 * i] += __builtin_bit_cast(float, w << 16); r[2 * i + 1] += __builtin_bit_cast(float, w & 0xffff0000u); } }
;                     u32x4 w; w.x = cvt_pk_bf16(r[0], r[1]); w.y = cvt_pk_bf16(r[2], r[3]); w.z = cvt_pk_bf16(r[4], r[5]); w.w = cvt_pk_bf16(r[6], r[7]);
;                     *(u32x4*)(O + ro + bj * HALF) = w; } }
;     __device__ __forceinline__ void operator()(const f32x4 (&acc)[2][2][4][2], const Unit& u, int wr, int wc, int fr, int fq) const {
;         if (u.pm < nM) { EpiGate<0> E{m1, gates, nullptr, 1024, 0}; E(acc, u, wr, wc, fr, fq); }
	v_lshlrev_b32_e32 v146, 16, v182
	v_and_b32_e32 v147, 0xffff0000, v182
	v_lshlrev_b32_e32 v148, 16, v183
	v_and_b32_e32 v149, 0xffff0000, v183
	v_lshlrev_b32_e32 v150, 16, v184
	v_and_b32_e32 v151, 0xffff0000, v184
	v_lshlrev_b32_e32 v152, 16, v185
	v_and_b32_e32 v153, 0xffff0000, v185
	v_pk_mul_f32 v[146:147], v[146:147], s[100:101] op_sel_hi:[1,0]
	v_pk_mul_f32 v[148:149], v[148:149], s[100:101] op_sel_hi:[1,0]
	v_pk_mul_f32 v[150:151], v[150:151], s[100:101] op_sel_hi:[1,0]
	v_pk_mul_f32 v[152:153], v[152:153], s[100:101] op_sel_hi:[1,0]
	v_exp_f32_e32 v146, v146
	v_exp_f32_e32 v147, v147
	v_exp_f32_e32 v148, v148
	v_exp_f32_e32 v149, v149
	v_exp_f32_e32 v150, v150
	v_exp_f32_e32 v151, v151
	v_exp_f32_e32 v152, v152
	v_exp_f32_e32 v153, v153
	v_pk_add_f32 v[146:147], v[146:147], 1.0 op_sel_hi:[1,0]
	v_pk_add_f32 v[148:149], v[148:149], 1.0 op_sel_hi:[1,0]
	v_pk_add_f32 v[150:151], v[150:151], 1.0 op_sel_hi:[1,0]
	v_pk_add_f32 v[152:153], v[152:153], 1.0 op_sel_hi:[1,0]
	v_rcp_f32_e32 v146, v146
	v_rcp_f32_e32 v147, v147
	v_rcp_f32_e32 v148, v148
	v_rcp_f32_e32 v149, v149
	v_rcp_f32_e32 v150, v150
	v_rcp_f32_e32 v151, v151
	v_rcp_f32_e32 v152, v152
	v_rcp_f32_e32 v153, v153
	v_pk_mul_f32 v[162:163], v[102:103], v[146:147]
	v_pk_mul_f32 v[164:165], v[104:105], v[148:149]
	v_pk_mul_f32 v[166:167], v[98:99], v[150:151]
	v_pk_mul_f32 v[168:169], v[100:101], v[152:153]
	v_cvt_pk_bf16_f32 v162, v162, v163
	v_cvt_pk_bf16_f32 v163, v164, v165
	v_cvt_pk_bf16_f32 v164, v166, v167
	v_cvt_pk_bf16_f32 v165, v168, v169
	v_add_u32_e32 v132, 0x8000, v130
	global_store_dwordx4 v132, v[162:165], s[6:7] offset:256
	v_add_u32_e32 v131, 0x58000, v130
	global_load_dwordx4 v[182:185], v131, s[42:43]
	s_waitcnt vmcnt(14)
	v_lshlrev_b32_e32 v146, 16, v186
	v_and_b32_e32 v147, 0xffff0000, v186
	v_lshlrev_b32_e32 v148, 16, v187
	v_and_b32_e32 v149, 0xffff0000, v187
	v_lshlrev_b32_e32 v150, 16, v188
	v_and_b32_e32 v151, 0xffff0000, v188
	v_lshlrev_b32_e32 v152, 16, v189
	v_and_b32_e32 v153, 0xffff0000, v189
	v_pk_mul_f32 v[146:147], v[146:147], s[100:101] op_sel_hi:[1,0]
	v_pk_mul_f32 v[148:149], v[148:149], s[100:101] op_sel_hi:[1,0]
	v_pk_mul_f32 v[150:151], v[150:151], s[100:101] op_sel_hi:[1,0]
	v_pk_mul_f32 v[152:153], v[152:153], s[100:101] op_sel_hi:[1,0]
	v_exp_f32_e32 v146, v146
	v_exp_f32_e32 v147, v147
	v_exp_f32_e32 v148, v148
	v_exp_f32_e32 v149, v149
	v_exp_f32_e32 v150, v150
	v_exp_f32_e32 v151, v151
	v_exp_f32_e32 v152, v152
	v_exp_f32_e32 v153, v153
	v_pk_add_f32 v[146:147], v[146:147], 1.0 op_sel_hi:[1,0]
	v_pk_add_f32 v[148:149], v[148:149], 1.0 op_sel_hi:[1,0]
	v_pk_add_f32 v[150:151], v[150:151], 1.0 op_sel_hi:[1,0]
	v_pk_add_f32 v[152:153], v[152:153], 1.0 op_sel_hi:[1,0]
	v_rcp_f32_e32 v146, v146
	v_rcp_f32_e32 v147, v147
	v_rcp_f32_e32 v148, v148
	v_rcp_f32_e32 v149, v149
	v_rcp_f32_e32 v150, v150
	v_rcp_f32_e32 v151, v151
	v_rcp_f32_e32 v152, v152
	v_rcp_f32_e32 v153, v153
	v_pk_mul_f32 v[162:163], v[94:95], v[146:147]
	v_pk_mul_f32 v[164:165], v[96:97], v[148:149]
	v_pk_mul_f32 v[166:167], v[90:91], v[150:151]
	v_pk_mul_f32 v[168:169], v[92:93], v[152:153]
	v_cvt_pk_bf16_f32 v162, v162, v163
	v_cvt_pk_bf16_f32 v163, v164, v165
	v_cvt_pk_bf16_f32 v164, v166, v167
	v_cvt_pk_bf16_f32 v165, v168, v169
	v_add_u32_e32 v132, 0x10000, v130
	global_store_dwordx4 v132, v[162:165], s[6:7]
	v_add_u32_e32 v131, 0x58000, v130
	global_load_dwordx4 v[186:189], v131, s[42:43] offset:256
	s_waitcnt vmcnt(15)
	v_lshlrev_b32_e32 v146, 16, v190
	v_and_b32_e32 v147, 0xffff0000, v190
	v_lshlrev_b32_e32 v148, 16, v191
	v_and_b32_e32 v149, 0xffff0000, v191
	v_lshlrev_b32_e32 v150, 16, v192
	v_and_b32_e32 v151, 0xffff0000, v192
	v_lshlrev_b32_e32 v152, 16, v193
	v_and_b32_e32 v153, 0xffff0000, v193
	v_pk_mul_f32 v[146:147], v[146:147], s[100:101] op_sel_hi:[1,0]
	v_pk_mul_f32 v[148:149], v[148:149], s[100:101] op_sel_hi:[1,0]
	v_pk_mul_f32 v[150:151], v[150:151], s[100:101] op_sel_hi:[1,0]
	v_pk_mul_f32 v[152:153], v[152:153], s[100:101] op_sel_hi:[1,0]
	v_exp_f32_e32 v146, v146
	v_exp_f32_e32 v147, v147
	v_exp_f32_e32 v148, v148
	v_exp_f32_e32 v149, v149
	v_exp_f32_e32 v150, v150
	v_exp_f32_e32 v151, v151
	v_exp_f32_e32 v152, v152
	v_exp_f32_e32 v153, v153
	v_pk_add_f32 v[146:147], v[146:147], 1.0 op_sel_hi:[1,0]
	v_pk_add_f32 v[148:149], v[148:149], 1.0 op_sel_hi:[1,0]
	v_pk_add_f32 v[150:151], v[150:151], 1.0 op_sel_hi:[1,0]
	v_pk_add_f32 v[152:153], v[152:153], 1.0 op_sel_hi:[1,0]
	v_rcp_f32_e32 v146, v146
	v_rcp_f32_e32 v147, v147
	v_rcp_f32_e32 v148, v148
	v_rcp_f32_e32 v149, v149
	v_rcp_f32_e32 v150, v150
	v_rcp_f32_e32 v151, v151
	v_rcp_f32_e32 v152, v152
	v_rcp_f32_e32 v153, v153
	v_pk_mul_f32 v[162:163], v[86:87], v[146:147]
	v_pk_mul_f32 v[164:165], v[88:89], v[148:149]
	v_pk_mul_f32 v[166:167], v[82:83], v[150:151]
	v_pk_mul_f32 v[168:169], v[84:85], v[152:153]
	v_cvt_pk_bf16_f32 v162, v162, v163
	v_cvt_pk_bf16_f32 v163, v164, v165
	v_cvt_pk_bf16_f32 v164, v166, v167
	v_cvt_pk_bf16_f32 v165, v168, v169
	v_add_u32_e32 v132, 0x10000, v130
	global_store_dwordx4 v132, v[162:165], s[6:7] offset:256
	s_waitcnt vmcnt(15)
; __device__ __forceinline__ unsigned cvt_pk_bf16(float lo, float hi) { unsigned r; asm volatile("v_cvt_pk_bf16_f32 %0, %1, %2" : "=v"(r) : "v"(lo), "v"(hi)); return r; }
;     __device__ __forceinline__ void operator()(const f32x4 (&acc)[2][2][4][2], const Unit& u, int wr, int wc, int fr, int fq) const {
;     ...
;             for (int m = 0; m < 4; ++m) { const size_t ro = (size_t)(row0 + ai * HALF + m * 16) * ldc + col0;
; #pragma unroll
;                 for (int bj = 0; bj < 2; ++bj) { const f32x4 v0 = acc[ai][bj][m][0], v1 = acc[ai][bj][m][1];
;                     const u32x4 gw = *(const u32x4*)(G + ro + bj * HALF);
;                     float r[8]; const float a[8] = {v0[0], v0[1], v0[2], v0[3], v1[0], v1[1], v1[2], v1[3]};
; #pragma unroll
;                     for (int i = 0; i < 4; ++i) { const unsigned w = gw[i]; const float g0 = __builtin_bit_cast(float, w << 16), g1 = __builtin_bit_cast(float, w & 0xffff0000u);
;                         if (MODE == 0) { r[2 * i] = a[2 * i] * __builtin_amdgcn_rcpf(1.0f + __builtin_amdgcn_exp2f(-1.4426950408889634f * g0)); r[2 * i + 1] = a[2 * i + 1] * __builtin_amdgcn_rcpf(1.0f + __builtin_amdgcn_exp2f(-1.4426950408889634f * g1)); }
;                         else { r[2 * i] = g0 * a[2 * i] * __builtin_amdgcn_rcpf(1.0f + __builtin_amdgcn_exp2f(-1.4426950408889634f * a[2 * i])); r[2 * i + 1] = g1 * a[2 * i + 1] * __builtin_amdgcn_rcpf(1.0f + __builtin_amdgcn_exp2f(-1.4426950408889634f * a[2 * i + 1])); } }
;                     if (Add) { const u32x4 aw = *(const u32x4*)(Add + ro + bj * HALF);
; #pragma unroll
;                         for (int i = 0; i < 4; ++i) { const unsigned w = aw[i]; r[2 * i] += __builtin_bit_cast(float, w << 16); r[2 * i + 1] += __builtin_bit_cast(float, w & 0xffff0000u); } }
;                     u32x4 w; w.x = cvt_pk_bf16(r[0], r[1]); w.y = cvt_pk_bf16(r[2], r[3]); w.z = cvt_pk_bf16(r[4], r[5]); w.w = cvt_pk_bf16(r[6], r[7]);
;                     *(u32x4*)(O + ro + bj * HALF) = w; } }
;     __device__ __forceinline__ void operator()(const f32x4 (&acc)[2][2][4][2], const Unit& u, int wr, int wc, int fr, int fq) const {
;         if (u.pm < nM) { EpiGate<0> E{m1, gates, nullptr, 1024, 0}; E(acc, u, wr, wc, fr, fq); }
	v_lshlrev_b32_e32 v146, 16, v194
	v_and_b32_e32 v147, 0xffff0000, v194
	v_lshlrev_b32_e32 v148, 16, v195
	v_and_b32_e32 v149, 0xffff0000, v195
	v_lshlrev_b32_e32 v150, 16, v196
	v_and_b32_e32 v151, 0xffff0000, v196
	v_lshlrev_b32_e32 v152, 16, v197
	v_and_b32_e32 v153, 0xffff0000, v197
	v_pk_mul_f32 v[146:147], v[146:147], s[100:101] op_sel_hi:[1,0]
	v_pk_mul_f32 v[148:149], v[148:149], s[100:101] op_sel_hi:[1,0]
	v_pk_mul_f32 v[150:151], v[150:151], s[100:101] op_sel_hi:[1,0]
	v_pk_mul_f32 v[152:153], v[152:153], s[100:101] op_sel_hi:[1,0]
	v_exp_f32_e32 v146, v146
	v_exp_f32_e32 v147, v147
	v_exp_f32_e32 v148, v148
	v_exp_f32_e32 v149, v149
	v_exp_f32_e32 v150, v150
	v_exp_f32_e32 v151, v151
	v_exp_f32_e32 v152, v152
	v_exp_f32_e32 v153, v153
	v_pk_add_f32 v[146:147], v[146:147], 1.0 op_sel_hi:[1,0]
	v_pk_add_f32 v[148:149], v[148:149], 1.0 op_sel_hi:[1,0]
	v_pk_add_f32 v[150:151], v[150:151], 1.0 op_sel_hi:[1,0]
	v_pk_add_f32 v[152:153], v[152:153], 1.0 op_sel_hi:[1,0]
	v_rcp_f32_e32 v146, v146
	v_rcp_f32_e32 v147, v147
	v_rcp_f32_e32 v148, v148
	v_rcp_f32_e32 v149, v149
	v_rcp_f32_e32 v150, v150
	v_rcp_f32_e32 v151, v151
	v_rcp_f32_e32 v152, v152
	v_rcp_f32_e32 v153, v153
	v_pk_mul_f32 v[162:163], v[78:79], v[146:147]
	v_pk_mul_f32 v[164:165], v[80:81], v[148:149]
	v_pk_mul_f32 v[166:167], v[74:75], v[150:151]
	v_pk_mul_f32 v[168:169], v[76:77], v[152:153]
	v_cvt_pk_bf16_f32 v162, v162, v163
	v_cvt_pk_bf16_f32 v163, v164, v165
	v_cvt_pk_bf16_f32 v164, v166, v167
	v_cvt_pk_bf16_f32 v165, v168, v169
	v_add_u32_e32 v132, 0x18000, v130
	global_store_dwordx4 v132, v[162:165], s[6:7]
	s_waitcnt vmcnt(15)
	v_lshlrev_b32_e32 v146, 16, v198
	v_and_b32_e32 v147, 0xffff0000, v198
	v_lshlrev_b32_e32 v148, 16, v199
	v_and_b32_e32 v149, 0xffff0000, v199
	v_lshlrev_b32_e32 v150, 16, v200
	v_and_b32_e32 v151, 0xffff0000, v200
	v_lshlrev_b32_e32 v152, 16, v201
	v_and_b32_e32 v153, 0xffff0000, v201
	v_pk_mul_f32 v[146:147], v[146:147], s[100:101] op_sel_hi:[1,0]
	v_pk_mul_f32 v[148:149], v[148:149], s[100:101] op_sel_hi:[1,0]
	v_pk_mul_f32 v[150:151], v[150:151], s[100:101] op_sel_hi:[1,0]
	v_pk_mul_f32 v[152:153], v[152:153], s[100:101] op_sel_hi:[1,0]
	v_exp_f32_e32 v146, v146
	v_exp_f32_e32 v147, v147
	v_exp_f32_e32 v148, v148
	v_exp_f32_e32 v149, v149
	v_exp_f32_e32 v150, v150
	v_exp_f32_e32 v151, v151
	v_exp_f32_e32 v152, v152
	v_exp_f32_e32 v153, v153
	v_pk_add_f32 v[146:147], v[146:147], 1.0 op_sel_hi:[1,0]
	v_pk_add_f32 v[148:149], v[148:149], 1.0 op_sel_hi:[1,0]
	v_pk_add_f32 v[150:151], v[150:151], 1.0 op_sel_hi:[1,0]
	v_pk_add_f32 v[152:153], v[152:153], 1.0 op_sel_hi:[1,0]
	v_rcp_f32_e32 v146, v146
	v_rcp_f32_e32 v147, v147
	v_rcp_f32_e32 v148, v148
	v_rcp_f32_e32 v149, v149
	v_rcp_f32_e32 v150, v150
	v_rcp_f32_e32 v151, v151
	v_rcp_f32_e32 v152, v152
	v_rcp_f32_e32 v153, v153
	v_pk_mul_f32 v[162:163], v[70:71], v[146:147]
	v_pk_mul_f32 v[164:165], v[72:73], v[148:149]
	v_pk_mul_f32 v[166:167], v[66:67], v[150:151]
	v_pk_mul_f32 v[168:169], v[68:69], v[152:153]
	v_cvt_pk_bf16_f32 v162, v162, v163
	v_cvt_pk_bf16_f32 v163, v164, v165
	v_cvt_pk_bf16_f32 v164, v166, v167
	v_cvt_pk_bf16_f32 v165, v168, v169
	v_add_u32_e32 v132, 0x18000, v130
	global_store_dwordx4 v132, v[162:165], s[6:7] offset:256
	s_waitcnt vmcnt(15)
	v_lshlrev_b32_e32 v146, 16, v202
	v_and_b32_e32 v147, 0xffff0000, v202
	v_lshlrev_b32_e32 v148, 16, v203
	v_and_b32_e32 v149, 0xffff0000, v203
	v_lshlrev_b32_e32 v150, 16, v204
	v_and_b32_e32 v151, 0xffff0000, v204
	v_lshlrev_b32_e32 v152, 16, v205
	v_and_b32_e32 v153, 0xffff0000, v205
	v_pk_mul_f32 v[146:147], v[146:147], s[100:101] op_sel_hi:[1,0]
	v_pk_mul_f32 v[148:149], v[148:149], s[100:101] op_sel_hi:[1,0]
	v_pk_mul_f32 v[150:151], v[150:151], s[100:101] op_sel_hi:[1,0]
	v_pk_mul_f32 v[152:153], v[152:153], s[100:101] op_sel_hi:[1,0]
	v_exp_f32_e32 v146, v146
	v_exp_f32_e32 v147, v147
	v_exp_f32_e32 v148, v148
	v_exp_f32_e32 v149, v149
	v_exp_f32_e32 v150, v150
	v_exp_f32_e32 v151, v151
	v_exp_f32_e32 v152, v152
	v_exp_f32_e32 v153, v153
	v_pk_add_f32 v[146:147], v[146:147], 1.0 op_sel_hi:[1,0]
	v_pk_add_f32 v[148:149], v[148:149], 1.0 op_sel_hi:[1,0]
	v_pk_add_f32 v[150:151], v[150:151], 1.0 op_sel_hi:[1,0]
	v_pk_add_f32 v[152:153], v[152:153], 1.0 op_sel_hi:[1,0]
	v_rcp_f32_e32 v146, v146
	v_rcp_f32_e32 v147, v147
	v_rcp_f32_e32 v148, v148
	v_rcp_f32_e32 v149, v149
	v_rcp_f32_e32 v150, v150
	v_rcp_f32_e32 v151, v151
	v_rcp_f32_e32 v152, v152
	v_rcp_f32_e32 v153, v153
	v_pk_mul_f32 v[162:163], v[62:63], v[146:147]
	v_pk_mul_f32 v[164:165], v[64:65], v[148:149]
	v_pk_mul_f32 v[166:167], v[58:59], v[150:151]
	v_pk_mul_f32 v[168:169], v[60:61], v[152:153]
	v_cvt_pk_bf16_f32 v162, v162, v163
	v_cvt_pk_bf16_f32 v163, v164, v165
	v_cvt_pk_bf16_f32 v164, v166, v167
	v_cvt_pk_bf16_f32 v165, v168, v169
	v_add_u32_e32 v132, 0x40000, v130
	global_store_dwordx4 v132, v[162:165], s[6:7]
	s_waitcnt vmcnt(15)
; __device__ __forceinline__ unsigned cvt_pk_bf16(float lo, float hi) { unsigned r; asm volatile("v_cvt_pk_bf16_f32 %0, %1, %2" : "=v"(r) : "v"(lo), "v"(hi)); return r; }
;     __device__ __forceinline__ void operator()(const f32x4 (&acc)[2][2][4][2], const Unit& u, int wr, int wc, int fr, int fq) const {
;     ...
;             for (int m = 0; m < 4; ++m) { const size_t ro = (size_t)(row0 + ai * HALF + m * 16) * ldc + col0;
; #pragma unroll
;                 for (int bj = 0; bj < 2; ++bj) { const f32x4 v0 = acc[ai][bj][m][0], v1 = acc[ai][bj][m][1];
;                     const u32x4 gw = *(const u32x4*)(G + ro + bj * HALF);
;                     float r[8]; const float a[8] = {v0[0], v0[1], v0[2], v0[3], v1[0], v1[1], v1[2], v1[3]};
; #pragma unroll
;                     for (int i = 0; i < 4; ++i) { const unsigned w = gw[i]; const float g0 = __builtin_bit_cast(float, w << 16), g1 = __builtin_bit_cast(float, w & 0xffff0000u);
;                         if (MODE == 0) { r[2 * i] = a[2 * i] * __builtin_amdgcn_rcpf(1.0f + __builtin_amdgcn_exp2f(-1.4426950408889634f * g0)); r[2 * i + 1] = a[2 * i + 1] * __builtin_amdgcn_rcpf(1.0f + __builtin_amdgcn_exp2f(-1.4426950408889634f * g1)); }
;                         else { r[2 * i] = g0 * a[2 * i] * __builtin_amdgcn_rcpf(1.0f + __builtin_amdgcn_exp2f(-1.4426950408889634f * a[2 * i])); r[2 * i + 1] = g1 * a[2 * i + 1] * __builtin_amdgcn_rcpf(1.0f + __builtin_amdgcn_exp2f(-1.4426950408889634f * a[2 * i + 1])); } }
;                     if (Add) { const u32x4 aw = *(const u32x4*)(Add + ro + bj * HALF);
; #pragma unroll
;                         for (int i = 0; i < 4; ++i) { const unsigned w = aw[i]; r[2 * i] += __builtin_bit_cast(float, w << 16); r[2 * i + 1] += __builtin_bit_cast(float, w & 0xffff0000u); } }
;                     u32x4 w; w.x = cvt_pk_bf16(r[0], r[1]); w.y = cvt_pk_bf16(r[2], r[3]); w.z = cvt_pk_bf16(r[4], r[5]); w.w = cvt_pk_bf16(r[6], r[7]);
;                     *(u32x4*)(O + ro + bj * HALF) = w; } }
;     __device__ __forceinline__ void operator()(const f32x4 (&acc)[2][2][4][2], const Unit& u, int wr, int wc, int fr, int fq) const {
;         if (u.pm < nM) { EpiGate<0> E{m1, gates, nullptr, 1024, 0}; E(acc, u, wr, wc, fr, fq); }
	v_lshlrev_b32_e32 v146, 16, v206
	v_and_b32_e32 v147, 0xffff0000, v206
	v_lshlrev_b32_e32 v148, 16, v207
	v_and_b32_e32 v149, 0xffff0000, v207
	v_lshlrev_b32_e32 v150, 16, v208
	v_and_b32_e32 v151, 0xffff0000, v208
	v_lshlrev_b32_e32 v152, 16, v209
	v_and_b32_e32 v153, 0xffff0000, v209
	v_pk_mul_f32 v[146:147], v[146:147], s[100:101] op_sel_hi:[1,0]
	v_pk_mul_f32 v[148:149], v[148:149], s[100:101] op_sel_hi:[1,0]
	v_pk_mul_f32 v[150:151], v[150:151], s[100:101] op_sel_hi:[1,0]
	v_pk_mul_f32 v[152:153], v[152:153], s[100:101] op_sel_hi:[1,0]
	v_exp_f32_e32 v146, v146
	v_exp_f32_e32 v147, v147
	v_exp_f32_e32 v148, v148
	v_exp_f32_e32 v149, v149
	v_exp_f32_e32 v150, v150
	v_exp_f32_e32 v151, v151
	v_exp_f32_e32 v152, v152
	v_exp_f32_e32 v153, v153
	v_pk_add_f32 v[146:147], v[146:147], 1.0 op_sel_hi:[1,0]
	v_pk_add_f32 v[148:149], v[148:149], 1.0 op_sel_hi:[1,0]
	v_pk_add_f32 v[150:151], v[150:151], 1.0 op_sel_hi:[1,0]
	v_pk_add_f32 v[152:153], v[152:153], 1.0 op_sel_hi:[1,0]
	v_rcp_f32_e32 v146, v146
	v_rcp_f32_e32 v147, v147
	v_rcp_f32_e32 v148, v148
	v_rcp_f32_e32 v149, v149
	v_rcp_f32_e32 v150, v150
	v_rcp_f32_e32 v151, v151
	v_rcp_f32_e32 v152, v152
	v_rcp_f32_e32 v153, v153
	v_pk_mul_f32 v[162:163], v[54:55], v[146:147]
	v_pk_mul_f32 v[164:165], v[56:57], v[148:149]
	v_pk_mul_f32 v[166:167], v[50:51], v[150:151]
	v_pk_mul_f32 v[168:169], v[52:53], v[152:153]
	v_cvt_pk_bf16_f32 v162, v162, v163
	v_cvt_pk_bf16_f32 v163, v164, v165
	v_cvt_pk_bf16_f32 v164, v166, v167
	v_cvt_pk_bf16_f32 v165, v168, v169
	v_add_u32_e32 v132, 0x40000, v130
	global_store_dwordx4 v132, v[162:165], s[6:7] offset:256
	s_waitcnt vmcnt(15)
	v_lshlrev_b32_e32 v146, 16, v210
	v_and_b32_e32 v147, 0xffff0000, v210
	v_lshlrev_b32_e32 v148, 16, v211
	v_and_b32_e32 v149, 0xffff0000, v211
	v_lshlrev_b32_e32 v150, 16, v212
	v_and_b32_e32 v151, 0xffff0000, v212
	v_lshlrev_b32_e32 v152, 16, v213
	v_and_b32_e32 v153, 0xffff0000, v213
	v_pk_mul_f32 v[146:147], v[146:147], s[100:101] op_sel_hi:[1,0]
	v_pk_mul_f32 v[148:149], v[148:149], s[100:101] op_sel_hi:[1,0]
	v_pk_mul_f32 v[150:151], v[150:151], s[100:101] op_sel_hi:[1,0]
	v_pk_mul_f32 v[152:153], v[152:153], s[100:101] op_sel_hi:[1,0]
	v_exp_f32_e32 v146, v146
	v_exp_f32_e32 v147, v147
	v_exp_f32_e32 v148, v148
	v_exp_f32_e32 v149, v149
	v_exp_f32_e32 v150, v150
	v_exp_f32_e32 v151, v151
	v_exp_f32_e32 v152, v152
	v_exp_f32_e32 v153, v153
	v_pk_add_f32 v[146:147], v[146:147], 1.0 op_sel_hi:[1,0]
	v_pk_add_f32 v[148:149], v[148:149], 1.0 op_sel_hi:[1,0]
	v_pk_add_f32 v[150:151], v[150:151], 1.0 op_sel_hi:[1,0]
	v_pk_add_f32 v[152:153], v[152:153], 1.0 op_sel_hi:[1,0]
	v_rcp_f32_e32 v146, v146
	v_rcp_f32_e32 v147, v147
	v_rcp_f32_e32 v148, v148
	v_rcp_f32_e32 v149, v149
	v_rcp_f32_e32 v150, v150
	v_rcp_f32_e32 v151, v151
	v_rcp_f32_e32 v152, v152
	v_rcp_f32_e32 v153, v153
	v_pk_mul_f32 v[162:163], v[46:47], v[146:147]
	v_pk_mul_f32 v[164:165], v[48:49], v[148:149]
	v_pk_mul_f32 v[166:167], v[42:43], v[150:151]
	v_pk_mul_f32 v[168:169], v[44:45], v[152:153]
	v_cvt_pk_bf16_f32 v162, v162, v163
	v_cvt_pk_bf16_f32 v163, v164, v165
	v_cvt_pk_bf16_f32 v164, v166, v167
	v_cvt_pk_bf16_f32 v165, v168, v169
	v_add_u32_e32 v132, 0x48000, v130
	global_store_dwordx4 v132, v[162:165], s[6:7]
	s_waitcnt vmcnt(14)
	v_lshlrev_b32_e32 v146, 16, v170
	v_and_b32_e32 v147, 0xffff0000, v170
	v_lshlrev_b32_e32 v148, 16, v171
	v_and_b32_e32 v149, 0xffff0000, v171
	v_lshlrev_b32_e32 v150, 16, v172
	v_and_b32_e32 v151, 0xffff0000, v172
	v_lshlrev_b32_e32 v152, 16, v173
	v_and_b32_e32 v153, 0xffff0000, v173
	v_pk_mul_f32 v[146:147], v[146:147], s[100:101] op_sel_hi:[1,0]
	v_pk_mul_f32 v[148:149], v[148:149], s[100:101] op_sel_hi:[1,0]
	v_pk_mul_f32 v[150:151], v[150:151], s[100:101] op_sel_hi:[1,0]
	v_pk_mul_f32 v[152:153], v[152:153], s[100:101] op_sel_hi:[1,0]
	v_exp_f32_e32 v146, v146
	v_exp_f32_e32 v147, v147
	v_exp_f32_e32 v148, v148
	v_exp_f32_e32 v149, v149
	v_exp_f32_e32 v150, v150
	v_exp_f32_e32 v151, v151
	v_exp_f32_e32 v152, v152
	v_exp_f32_e32 v153, v153
	v_pk_add_f32 v[146:147], v[146:147], 1.0 op_sel_hi:[1,0]
	v_pk_add_f32 v[148:149], v[148:149], 1.0 op_sel_hi:[1,0]
	v_pk_add_f32 v[150:151], v[150:151], 1.0 op_sel_hi:[1,0]
	v_pk_add_f32 v[152:153], v[152:153], 1.0 op_sel_hi:[1,0]
	v_rcp_f32_e32 v146, v146
	v_rcp_f32_e32 v147, v147
	v_rcp_f32_e32 v148, v148
	v_rcp_f32_e32 v149, v149
	v_rcp_f32_e32 v150, v150
	v_rcp_f32_e32 v151, v151
	v_rcp_f32_e32 v152, v152
	v_rcp_f32_e32 v153, v153
	v_pk_mul_f32 v[162:163], v[38:39], v[146:147]
	v_pk_mul_f32 v[164:165], v[40:41], v[148:149]
	v_pk_mul_f32 v[166:167], v[34:35], v[150:151]
	v_pk_mul_f32 v[168:169], v[36:37], v[152:153]
	v_cvt_pk_bf16_f32 v162, v162, v163
	v_cvt_pk_bf16_f32 v163, v164, v165
	v_cvt_pk_bf16_f32 v164, v166, v167
	v_cvt_pk_bf16_f32 v165, v168, v169
	v_add_u32_e32 v132, 0x48000, v130
	global_store_dwordx4 v132, v[162:165], s[6:7] offset:256
	s_waitcnt vmcnt(13)
; __device__ __forceinline__ unsigned cvt_pk_bf16(float lo, float hi) { unsigned r; asm volatile("v_cvt_pk_bf16_f32 %0, %1, %2" : "=v"(r) : "v"(lo), "v"(hi)); return r; }
;     __device__ __forceinline__ void operator()(const f32x4 (&acc)[2][2][4][2], const Unit& u, int wr, int wc, int fr, int fq) const {
;     ...
;             for (int m = 0; m < 4; ++m) { const size_t ro = (size_t)(row0 + ai * HALF + m * 16) * ldc + col0;
; #pragma unroll
;                 for (int bj = 0; bj < 2; ++bj) { const f32x4 v0 = acc[ai][bj][m][0], v1 = acc[ai][bj][m][1];
;                     const u32x4 gw = *(const u32x4*)(G + ro + bj * HALF);
;                     float r[8]; const float a[8] = {v0[0], v0[1], v0[2], v0[3], v1[0], v1[1], v1[2], v1[3]};
; #pragma unroll
;                     for (int i = 0; i < 4; ++i) { const unsigned w = gw[i]; const float g0 = __builtin_bit_cast(float, w << 16), g1 = __builtin_bit_cast(float, w & 0xffff0000u);
;                         if (MODE == 0) { r[2 * i] = a[2 * i] * __builtin_amdgcn_rcpf(1.0f + __builtin_amdgcn_exp2f(-1.4426950408889634f * g0)); r[2 * i + 1] = a[2 * i + 1] * __builtin_amdgcn_rcpf(1.0f + __builtin_amdgcn_exp2f(-1.4426950408889634f * g1)); }
;                         else { r[2 * i] = g0 * a[2 * i] * __builtin_amdgcn_rcpf(1.0f + __builtin_amdgcn_exp2f(-1.4426950408889634f * a[2 * i])); r[2 * i + 1] = g1 * a[2 * i + 1] * __builtin_amdgcn_rcpf(1.0f + __builtin_amdgcn_exp2f(-1.4426950408889634f * a[2 * i + 1])); } }
;                     if (Add) { const u32x4 aw = *(const u32x4*)(Add + ro + bj * HALF);
; #pragma unroll
;                         for (int i = 0; i < 4; ++i) { const unsigned w = aw[i]; r[2 * i] += __builtin_bit_cast(float, w << 16); r[2 * i + 1] += __builtin_bit_cast(float, w & 0xffff0000u); } }
;                     u32x4 w; w.x = cvt_pk_bf16(r[0], r[1]); w.y = cvt_pk_bf16(r[2], r[3]); w.z = cvt_pk_bf16(r[4], r[5]); w.w = cvt_pk_bf16(r[6], r[7]);
;                     *(u32x4*)(O + ro + bj * HALF) = w; } }
;     __device__ __forceinline__ void operator()(const f32x4 (&acc)[2][2][4][2], const Unit& u, int wr, int wc, int fr, int fq) const {
;         if (u.pm < nM) { EpiGate<0> E{m1, gates, nullptr, 1024, 0}; E(acc, u, wr, wc, fr, fq); }
	v_lshlrev_b32_e32 v146, 16, v174
	v_and_b32_e32 v147, 0xffff0000, v174
	v_lshlrev_b32_e32 v148, 16, v175
	v_and_b32_e32 v149, 0xffff0000, v175
	v_lshlrev_b32_e32 v150, 16, v176
	v_and_b32_e32 v151, 0xffff0000, v176
	v_lshlrev_b32_e32 v152, 16, v177
	v_and_b32_e32 v153, 0xffff0000, v177
	v_pk_mul_f32 v[146:147], v[146:147], s[100:101] op_sel_hi:[1,0]
	v_pk_mul_f32 v[148:149], v[148:149], s[100:101] op_sel_hi:[1,0]
	v_pk_mul_f32 v[150:151], v[150:151], s[100:101] op_sel_hi:[1,0]
	v_pk_mul_f32 v[152:153], v[152:153], s[100:101] op_sel_hi:[1,0]
	v_exp_f32_e32 v146, v146
	v_exp_f32_e32 v147, v147
	v_exp_f32_e32 v148, v148
	v_exp_f32_e32 v149, v149
	v_exp_f32_e32 v150, v150
	v_exp_f32_e32 v151, v151
	v_exp_f32_e32 v152, v152
	v_exp_f32_e32 v153, v153
	v_pk_add_f32 v[146:147], v[146:147], 1.0 op_sel_hi:[1,0]
	v_pk_add_f32 v[148:149], v[148:149], 1.0 op_sel_hi:[1,0]
	v_pk_add_f32 v[150:151], v[150:151], 1.0 op_sel_hi:[1,0]
	v_pk_add_f32 v[152:153], v[152:153], 1.0 op_sel_hi:[1,0]
	v_rcp_f32_e32 v146, v146
	v_rcp_f32_e32 v147, v147
	v_rcp_f32_e32 v148, v148
	v_rcp_f32_e32 v149, v149
	v_rcp_f32_e32 v150, v150
	v_rcp_f32_e32 v151, v151
	v_rcp_f32_e32 v152, v152
	v_rcp_f32_e32 v153, v153
	v_pk_mul_f32 v[162:163], v[30:31], v[146:147]
	v_pk_mul_f32 v[164:165], v[32:33], v[148:149]
	v_pk_mul_f32 v[166:167], v[26:27], v[150:151]
	v_pk_mul_f32 v[168:169], v[28:29], v[152:153]
	v_cvt_pk_bf16_f32 v162, v162, v163
	v_cvt_pk_bf16_f32 v163, v164, v165
	v_cvt_pk_bf16_f32 v164, v166, v167
	v_cvt_pk_bf16_f32 v165, v168, v169
	v_add_u32_e32 v132, 0x50000, v130
	global_store_dwordx4 v132, v[162:165], s[6:7]
	s_waitcnt vmcnt(12)
	v_lshlrev_b32_e32 v146, 16, v178
	v_and_b32_e32 v147, 0xffff0000, v178
	v_lshlrev_b32_e32 v148, 16, v179
	v_and_b32_e32 v149, 0xffff0000, v179
	v_lshlrev_b32_e32 v150, 16, v180
	v_and_b32_e32 v151, 0xffff0000, v180
	v_lshlrev_b32_e32 v152, 16, v181
	v_and_b32_e32 v153, 0xffff0000, v181
	v_pk_mul_f32 v[146:147], v[146:147], s[100:101] op_sel_hi:[1,0]
	v_pk_mul_f32 v[148:149], v[148:149], s[100:101] op_sel_hi:[1,0]
	v_pk_mul_f32 v[150:151], v[150:151], s[100:101] op_sel_hi:[1,0]
	v_pk_mul_f32 v[152:153], v[152:153], s[100:101] op_sel_hi:[1,0]
	v_exp_f32_e32 v146, v146
	v_exp_f32_e32 v147, v147
	v_exp_f32_e32 v148, v148
	v_exp_f32_e32 v149, v149
	v_exp_f32_e32 v150, v150
	v_exp_f32_e32 v151, v151
	v_exp_f32_e32 v152, v152
	v_exp_f32_e32 v153, v153
	v_pk_add_f32 v[146:147], v[146:147], 1.0 op_sel_hi:[1,0]
	v_pk_add_f32 v[148:149], v[148:149], 1.0 op_sel_hi:[1,0]
	v_pk_add_f32 v[150:151], v[150:151], 1.0 op_sel_hi:[1,0]
	v_pk_add_f32 v[152:153], v[152:153], 1.0 op_sel_hi:[1,0]
	v_rcp_f32_e32 v146, v146
	v_rcp_f32_e32 v147, v147
	v_rcp_f32_e32 v148, v148
	v_rcp_f32_e32 v149, v149
	v_rcp_f32_e32 v150, v150
	v_rcp_f32_e32 v151, v151
	v_rcp_f32_e32 v152, v152
	v_rcp_f32_e32 v153, v153
	v_pk_mul_f32 v[162:163], v[22:23], v[146:147]
	v_pk_mul_f32 v[164:165], v[24:25], v[148:149]
	v_pk_mul_f32 v[166:167], v[18:19], v[150:151]
	v_pk_mul_f32 v[168:169], v[20:21], v[152:153]
	v_cvt_pk_bf16_f32 v162, v162, v163
	v_cvt_pk_bf16_f32 v163, v164, v165
	v_cvt_pk_bf16_f32 v164, v166, v167
	v_cvt_pk_bf16_f32 v165, v168, v169
	v_add_u32_e32 v132, 0x50000, v130
	global_store_dwordx4 v132, v[162:165], s[6:7] offset:256
	s_waitcnt vmcnt(11)
	v_lshlrev_b32_e32 v146, 16, v182
	v_and_b32_e32 v147, 0xffff0000, v182
	v_lshlrev_b32_e32 v148, 16, v183
	v_and_b32_e32 v149, 0xffff0000, v183
	v_lshlrev_b32_e32 v150, 16, v184
	v_and_b32_e32 v151, 0xffff0000, v184
	v_lshlrev_b32_e32 v152, 16, v185
	v_and_b32_e32 v153, 0xffff0000, v185
	v_pk_mul_f32 v[146:147], v[146:147], s[100:101] op_sel_hi:[1,0]
	v_pk_mul_f32 v[148:149], v[148:149], s[100:101] op_sel_hi:[1,0]
	v_pk_mul_f32 v[150:151], v[150:151], s[100:101] op_sel_hi:[1,0]
	v_pk_mul_f32 v[152:153], v[152:153], s[100:101] op_sel_hi:[1,0]
	v_exp_f32_e32 v146, v146
	v_exp_f32_e32 v147, v147
	v_exp_f32_e32 v148, v148
	v_exp_f32_e32 v149, v149
	v_exp_f32_e32 v150, v150
	v_exp_f32_e32 v151, v151
	v_exp_f32_e32 v152, v152
	v_exp_f32_e32 v153, v153
	v_pk_add_f32 v[146:147], v[146:147], 1.0 op_sel_hi:[1,0]
	v_pk_add_f32 v[148:149], v[148:149], 1.0 op_sel_hi:[1,0]
	v_pk_add_f32 v[150:151], v[150:151], 1.0 op_sel_hi:[1,0]
	v_pk_add_f32 v[152:153], v[152:153], 1.0 op_sel_hi:[1,0]
	v_rcp_f32_e32 v146, v146
	v_rcp_f32_e32 v147, v147
	v_rcp_f32_e32 v148, v148
	v_rcp_f32_e32 v149, v149
	v_rcp_f32_e32 v150, v150
	v_rcp_f32_e32 v151, v151
	v_rcp_f32_e32 v152, v152
	v_rcp_f32_e32 v153, v153
	v_pk_mul_f32 v[162:163], v[14:15], v[146:147]
	v_pk_mul_f32 v[164:165], v[16:17], v[148:149]
	v_pk_mul_f32 v[166:167], v[10:11], v[150:151]
	v_pk_mul_f32 v[168:169], v[12:13], v[152:153]
	v_cvt_pk_bf16_f32 v162, v162, v163
	v_cvt_pk_bf16_f32 v163, v164, v165
	v_cvt_pk_bf16_f32 v164, v166, v167
	v_cvt_pk_bf16_f32 v165, v168, v169
	v_add_u32_e32 v132, 0x58000, v130
	global_store_dwordx4 v132, v[162:165], s[6:7]
	s_waitcnt vmcnt(10)
	v_lshlrev_b32_e32 v146, 16, v186
	v_and_b32_e32 v147, 0xffff0000, v186
	v_lshlrev_b32_e32 v148, 16, v187
	v_and_b32_e32 v149, 0xffff0000, v187
	v_lshlrev_b32_e32 v150, 16, v188
	v_and_b32_e32 v151, 0xffff0000, v188
	v_lshlrev_b32_e32 v152, 16, v189
	v_and_b32_e32 v153, 0xffff0000, v189
	v_pk_mul_f32 v[146:147], v[146:147], s[100:101] op_sel_hi:[1,0]
	v_pk_mul_f32 v[148:149], v[148:149], s[100:101] op_sel_hi:[1,0]
	v_pk_mul_f32 v[150:151], v[150:151], s[100:101] op_sel_hi:[1,0]
	v_pk_mul_f32 v[152:153], v[152:153], s[100:101] op_sel_hi:[1,0]
	v_exp_f32_e32 v146, v146
	v_exp_f32_e32 v147, v147
	v_exp_f32_e32 v148, v148
	v_exp_f32_e32 v149, v149
	v_exp_f32_e32 v150, v150
	v_exp_f32_e32 v151, v151
	v_exp_f32_e32 v152, v152
	v_exp_f32_e32 v153, v153
	v_pk_add_f32 v[146:147], v[146:147], 1.0 op_sel_hi:[1,0]
	v_pk_add_f32 v[148:149], v[148:149], 1.0 op_sel_hi:[1,0]
	v_pk_add_f32 v[150:151], v[150:151], 1.0 op_sel_hi:[1,0]
	v_pk_add_f32 v[152:153], v[152:153], 1.0 op_sel_hi:[1,0]
	v_rcp_f32_e32 v146, v146
	v_rcp_f32_e32 v147, v147
	v_rcp_f32_e32 v148, v148
	v_rcp_f32_e32 v149, v149
	v_rcp_f32_e32 v150, v150
	v_rcp_f32_e32 v151, v151
	v_rcp_f32_e32 v152, v152
	v_rcp_f32_e32 v153, v153
	v_pk_mul_f32 v[162:163], v[6:7], v[146:147]
	v_pk_mul_f32 v[164:165], v[8:9], v[148:149]
	v_pk_mul_f32 v[166:167], v[2:3], v[150:151]
	v_pk_mul_f32 v[168:169], v[4:5], v[152:153]
	v_cvt_pk_bf16_f32 v162, v162, v163
	v_cvt_pk_bf16_f32 v163, v164, v165
	v_cvt_pk_bf16_f32 v164, v166, v167
	v_cvt_pk_bf16_f32 v165, v168, v169
	v_add_u32_e32 v132, 0x58000, v130
	global_store_dwordx4 v132, v[162:165], s[6:7] offset:256
	s_and_b64 vcc, exec, s[38:39]
	s_mov_b64 s[38:39], -1
	s_cbranch_vccnz .LBB0_882

;     __device__ __forceinline__ void fused(f32x4 (&acc)[2][2][4][2], const Unit& u, int wr, int wc, int fr, int fq, PG8_LAS unsigned char* lds, int wid, int lane) const {
;     ...
;         const int col0 = u.pn * BM + wc * 32 + 4 * fq;
; #pragma unroll
;         for (int ai = 0; ai < 2; ++ai)
; #pragma unroll
;             for (int m = 0; m < 4; ++m) { const int r = ai * HALF + wr * 64 + m * 16 + fr; const float rs = R[r]; const size_t off = (size_t)(u.pm * BM + r) * 1024 + col0;
; #pragma unroll
;                 for (int bj = 0; bj < 2; ++bj)
; #pragma unroll
;                     for (int n = 0; n < 2; ++n) { const int c = bj * HALF + n * 16; const f32x4 xv = *(const f32x4*)(xres + off + c); const f32x4 wv = *(const f32x4*)(w + col0 + c);
;                         *(f32x4*)(out + off + c) = xv + acc[ai][bj][m][n] * rs * wv; }
;                 if (m & 1) asm volatile("" ::: "memory"); }
.LBB0_1001:
	s_or_b64 exec, exec, s[4:5]
	s_lshl_b32 s0, s34, 5
	s_lshl_b32 s1, s6, 8
	s_or_b32 s0, s1, s0
	v_lshrrev_b32_e32 v0, 2, v0
	v_add_u32_e32 v132, s7, v146
	v_readlane_b32 s12, v250, 0
	v_and_or_b32 v130, v0, 12, s0
	v_ashrrev_i32_e32 v133, 31, v132
	v_readlane_b32 s13, v250, 1
	v_readlane_b32 s14, v250, 2
	v_readlane_b32 s15, v250, 3
	v_ashrrev_i32_e32 v131, 31, v130
	v_lshlrev_b64 v[0:1], 10, v[132:133]
	v_mov_b32_e32 v134, s14
	v_mov_b32_e32 v135, s15
	v_lshl_add_u64 v[0:1], v[0:1], 0, v[130:131]
	v_readlane_b32 s0, v250, 10
	s_waitcnt vmcnt(0) lgkmcnt(0)
	s_barrier
	v_lshlrev_b64 v[142:143], 2, v[0:1]
	v_readlane_b32 s1, v250, 11
	v_lshl_add_u64 v[0:1], v[130:131], 2, v[134:135]
	v_lshl_add_u32 v133, v146, 2, 0
	v_lshl_add_u64 v[144:145], s[0:1], 0, v[142:143]
	global_load_dwordx4 v[134:137], v[0:1], off
	global_load_dwordx4 v[138:141], v[144:145], off
	v_add_u32_e32 v133, 0x1000, v133
	ds_read2_b32 v[146:147], v133 offset1:16
	v_readlane_b32 s16, v250, 4
	v_readlane_b32 s17, v250, 5
	v_readlane_b32 s18, v250, 6
	v_readlane_b32 s19, v250, 7
	s_waitcnt lgkmcnt(0)
	v_pk_mul_f32 v[126:127], v[126:127], v[146:147] op_sel_hi:[1,0]
	v_pk_mul_f32 v[128:129], v[128:129], v[146:147] op_sel_hi:[1,0]
	v_lshl_add_u64 v[142:143], s[16:17], 0, v[142:143]
	v_pk_mul_f32 v[122:123], v[122:123], v[146:147] op_sel_hi:[1,0]
	v_pk_mul_f32 v[124:125], v[124:125], v[146:147] op_sel_hi:[1,0]
	v_pk_mul_f32 v[118:119], v[118:119], v[146:147] op_sel_hi:[1,0]
	v_pk_mul_f32 v[120:121], v[120:121], v[146:147] op_sel_hi:[1,0]
	v_pk_mul_f32 v[110:111], v[110:111], v[146:147] op_sel_hi:[1,0]
	v_pk_mul_f32 v[112:113], v[112:113], v[146:147] op_sel_hi:[1,0]
	v_readlane_b32 s2, v250, 12
	v_readlane_b32 s3, v250, 13
	v_readlane_b32 s4, v250, 14
	v_readlane_b32 s5, v250, 15
	v_readlane_b32 s6, v250, 16
	v_readlane_b32 s7, v250, 17
	v_readlane_b32 s8, v250, 18
	v_readlane_b32 s9, v250, 19
	v_readlane_b32 s10, v250, 20
	v_readlane_b32 s11, v250, 21
	v_readlane_b32 s12, v250, 22
	v_readlane_b32 s13, v250, 23
	v_readlane_b32 s14, v250, 24
	v_readlane_b32 s15, v250, 25
	s_waitcnt vmcnt(0)
	v_pk_fma_f32 v[128:129], v[136:137], v[128:129], v[140:141]
	v_pk_fma_f32 v[126:127], v[134:135], v[126:127], v[138:139]
	global_store_dwordx4 v[142:143], v[126:129], off
	global_load_dwordx4 v[126:129], v[144:145], off offset:64
	s_nop 0
	global_load_dwordx4 v[134:137], v[0:1], off offset:64
	s_waitcnt vmcnt(0)
	v_pk_fma_f32 v[124:125], v[124:125], v[136:137], v[128:129]
	v_pk_fma_f32 v[122:123], v[122:123], v[134:135], v[126:127]
	global_store_dwordx4 v[142:143], v[122:125], off offset:64
	global_load_dwordx4 v[122:125], v[144:145], off offset:512
	s_nop 0
	global_load_dwordx4 v[126:129], v[0:1], off offset:512
	s_waitcnt vmcnt(0)
	v_pk_fma_f32 v[120:121], v[120:121], v[128:129], v[124:125]
	v_pk_fma_f32 v[118:119], v[118:119], v[126:127], v[122:123]
	global_store_dwordx4 v[142:143], v[118:121], off offset:512
	global_load_dwordx4 v[118:121], v[144:145], off offset:576
	s_nop 0
	global_load_dwordx4 v[122:125], v[0:1], off offset:576
	v_add_u32_e32 v126, 16, v132
	v_ashrrev_i32_e32 v127, 31, v126
	v_lshlrev_b64 v[126:127], 10, v[126:127]
	v_lshl_add_u64 v[126:127], v[126:127], 0, v[130:131]
	v_lshlrev_b64 v[126:127], 2, v[126:127]
	v_lshl_add_u64 v[128:129], s[0:1], 0, v[126:127]
	s_waitcnt vmcnt(0)
	v_pk_fma_f32 v[112:113], v[112:113], v[124:125], v[120:121]
	v_pk_fma_f32 v[110:111], v[110:111], v[122:123], v[118:119]
	global_store_dwordx4 v[142:143], v[110:113], off offset:576
	global_load_dwordx4 v[110:113], v[0:1], off
	s_nop 0
	global_load_dwordx4 v[118:121], v[128:129], off
	v_mov_b32_e32 v124, v147
	v_pk_mul_f32 v[114:115], v[114:115], v[124:125] op_sel_hi:[1,0]
	v_pk_mul_f32 v[116:117], v[116:117], v[124:125] op_sel_hi:[1,0]
	v_lshl_add_u64 v[122:123], s[16:17], 0, v[126:127]
	v_pk_mul_f32 v[106:107], v[106:107], v[124:125] op_sel_hi:[1,0]
	v_pk_mul_f32 v[108:109], v[108:109], v[124:125] op_sel_hi:[1,0]
	v_pk_mul_f32 v[102:103], v[102:103], v[124:125] op_sel_hi:[1,0]
	v_pk_mul_f32 v[104:105], v[104:105], v[124:125] op_sel_hi:[1,0]
	v_pk_mul_f32 v[94:95], v[94:95], v[124:125] op_sel_hi:[1,0]
	v_pk_mul_f32 v[96:97], v[96:97], v[124:125] op_sel_hi:[1,0]
	s_waitcnt vmcnt(0)
	v_pk_fma_f32 v[112:113], v[112:113], v[116:117], v[120:121]
	v_pk_fma_f32 v[110:111], v[110:111], v[114:115], v[118:119]
	global_store_dwordx4 v[122:123], v[110:113], off
	global_load_dwordx4 v[110:113], v[128:129], off offset:64
	s_nop 0
	global_load_dwordx4 v[114:117], v[0:1], off offset:64
	s_waitcnt vmcnt(0)
	v_pk_fma_f32 v[108:109], v[108:109], v[116:117], v[112:113]
	v_pk_fma_f32 v[106:107], v[106:107], v[114:115], v[110:111]
	global_store_dwordx4 v[122:123], v[106:109], off offset:64
	global_load_dwordx4 v[106:109], v[128:129], off offset:512
	s_nop 0
	global_load_dwordx4 v[110:113], v[0:1], off offset:512
	s_waitcnt vmcnt(0)
	v_pk_fma_f32 v[104:105], v[104:105], v[112:113], v[108:109]
	v_pk_fma_f32 v[102:103], v[102:103], v[110:111], v[106:107]
	global_store_dwordx4 v[122:123], v[102:105], off offset:512
	global_load_dwordx4 v[102:105], v[128:129], off offset:576
	s_nop 0
	global_load_dwordx4 v[106:109], v[0:1], off offset:576
	v_add_u32_e32 v110, 32, v132
	v_ashrrev_i32_e32 v111, 31, v110
	v_lshlrev_b64 v[110:111], 10, v[110:111]
	v_lshl_add_u64 v[110:111], v[110:111], 0, v[130:131]
	v_lshlrev_b64 v[110:111], 2, v[110:111]
	v_lshl_add_u64 v[112:113], s[0:1], 0, v[110:111]
	s_waitcnt vmcnt(0)
	v_pk_fma_f32 v[96:97], v[96:97], v[108:109], v[104:105]
	v_pk_fma_f32 v[94:95], v[94:95], v[106:107], v[102:103]
	global_store_dwordx4 v[122:123], v[94:97], off offset:576
	global_load_dwordx4 v[94:97], v[112:113], off
	global_load_dwordx4 v[102:105], v[0:1], off
	ds_read2_b32 v[106:107], v133 offset0:32 offset1:48
	v_lshl_add_u64 v[108:109], s[16:17], 0, v[110:111]
	s_waitcnt lgkmcnt(0)
;     __device__ __forceinline__ void fused(f32x4 (&acc)[2][2][4][2], const Unit& u, int wr, int wc, int fr, int fq, PG8_LAS unsigned char* lds, int wid, int lane) const {
;     ...
;         const int col0 = u.pn * BM + wc * 32 + 4 * fq;
; #pragma unroll
;         for (int ai = 0; ai < 2; ++ai)
; #pragma unroll
;             for (int m = 0; m < 4; ++m) { const int r = ai * HALF + wr * 64 + m * 16 + fr; const float rs = R[r]; const size_t off = (size_t)(u.pm * BM + r) * 1024 + col0;
; #pragma unroll
;                 for (int bj = 0; bj < 2; ++bj)
; #pragma unroll
;                     for (int n = 0; n < 2; ++n) { const int c = bj * HALF + n * 16; const f32x4 xv = *(const f32x4*)(xres + off + c); const f32x4 wv = *(const f32x4*)(w + col0 + c);
;                         *(f32x4*)(out + off + c) = xv + acc[ai][bj][m][n] * rs * wv; }
;                 if (m & 1) asm volatile("" ::: "memory"); }
	v_pk_mul_f32 v[98:99], v[98:99], v[106:107] op_sel_hi:[1,0]
	v_pk_mul_f32 v[100:101], v[100:101], v[106:107] op_sel_hi:[1,0]
	v_pk_mul_f32 v[90:91], v[90:91], v[106:107] op_sel_hi:[1,0]
	v_pk_mul_f32 v[92:93], v[92:93], v[106:107] op_sel_hi:[1,0]
	v_pk_mul_f32 v[86:87], v[86:87], v[106:107] op_sel_hi:[1,0]
	v_pk_mul_f32 v[88:89], v[88:89], v[106:107] op_sel_hi:[1,0]
	v_pk_mul_f32 v[78:79], v[78:79], v[106:107] op_sel_hi:[1,0]
	v_pk_mul_f32 v[80:81], v[80:81], v[106:107] op_sel_hi:[1,0]
	s_waitcnt vmcnt(0)
	v_pk_fma_f32 v[96:97], v[104:105], v[100:101], v[96:97]
	v_pk_fma_f32 v[94:95], v[102:103], v[98:99], v[94:95]
	global_store_dwordx4 v[108:109], v[94:97], off
	global_load_dwordx4 v[94:97], v[112:113], off offset:64
	s_nop 0
	global_load_dwordx4 v[98:101], v[0:1], off offset:64
	s_waitcnt vmcnt(0)
	v_pk_fma_f32 v[92:93], v[92:93], v[100:101], v[96:97]
	v_pk_fma_f32 v[90:91], v[90:91], v[98:99], v[94:95]
	global_store_dwordx4 v[108:109], v[90:93], off offset:64
	global_load_dwordx4 v[90:93], v[112:113], off offset:512
	s_nop 0
	global_load_dwordx4 v[94:97], v[0:1], off offset:512
	s_waitcnt vmcnt(0)
	v_pk_fma_f32 v[88:89], v[88:89], v[96:97], v[92:93]
	v_pk_fma_f32 v[86:87], v[86:87], v[94:95], v[90:91]
	global_store_dwordx4 v[108:109], v[86:89], off offset:512
	global_load_dwordx4 v[86:89], v[112:113], off offset:576
	s_nop 0
	global_load_dwordx4 v[90:93], v[0:1], off offset:576
	v_add_u32_e32 v94, 48, v132
	v_ashrrev_i32_e32 v95, 31, v94
	v_lshlrev_b64 v[94:95], 10, v[94:95]
	v_lshl_add_u64 v[94:95], v[94:95], 0, v[130:131]
	v_lshlrev_b64 v[94:95], 2, v[94:95]
	v_lshl_add_u64 v[96:97], s[0:1], 0, v[94:95]
	s_waitcnt vmcnt(0)
	v_pk_fma_f32 v[80:81], v[80:81], v[92:93], v[88:89]
	v_pk_fma_f32 v[78:79], v[78:79], v[90:91], v[86:87]
	global_store_dwordx4 v[108:109], v[78:81], off offset:576
	global_load_dwordx4 v[78:81], v[0:1], off
	s_nop 0
	global_load_dwordx4 v[86:89], v[96:97], off
	v_mov_b32_e32 v92, v107
	v_pk_mul_f32 v[82:83], v[82:83], v[92:93] op_sel_hi:[1,0]
	v_pk_mul_f32 v[84:85], v[84:85], v[92:93] op_sel_hi:[1,0]
	v_lshl_add_u64 v[90:91], s[16:17], 0, v[94:95]
	v_pk_mul_f32 v[74:75], v[74:75], v[92:93] op_sel_hi:[1,0]
	v_pk_mul_f32 v[76:77], v[76:77], v[92:93] op_sel_hi:[1,0]
	v_pk_mul_f32 v[70:71], v[70:71], v[92:93] op_sel_hi:[1,0]
	v_pk_mul_f32 v[72:73], v[72:73], v[92:93] op_sel_hi:[1,0]
	v_pk_mul_f32 v[66:67], v[66:67], v[92:93] op_sel_hi:[1,0]
	v_pk_mul_f32 v[68:69], v[68:69], v[92:93] op_sel_hi:[1,0]
	s_waitcnt vmcnt(0)
	v_pk_fma_f32 v[80:81], v[80:81], v[84:85], v[88:89]
	v_pk_fma_f32 v[78:79], v[78:79], v[82:83], v[86:87]
	global_store_dwordx4 v[90:91], v[78:81], off
	global_load_dwordx4 v[78:81], v[96:97], off offset:64
	s_nop 0
	global_load_dwordx4 v[82:85], v[0:1], off offset:64
	s_waitcnt vmcnt(0)
	v_pk_fma_f32 v[76:77], v[76:77], v[84:85], v[80:81]
	v_pk_fma_f32 v[74:75], v[74:75], v[82:83], v[78:79]
	global_store_dwordx4 v[90:91], v[74:77], off offset:64
	global_load_dwordx4 v[74:77], v[96:97], off offset:512
	s_nop 0
	global_load_dwordx4 v[78:81], v[0:1], off offset:512
	s_waitcnt vmcnt(0)
	v_pk_fma_f32 v[72:73], v[72:73], v[80:81], v[76:77]
	v_pk_fma_f32 v[70:71], v[70:71], v[78:79], v[74:75]
	global_store_dwordx4 v[90:91], v[70:73], off offset:512
	global_load_dwordx4 v[70:73], v[96:97], off offset:576
	s_nop 0
	global_load_dwordx4 v[74:77], v[0:1], off offset:576
	v_add_u32_e32 v78, 0x80, v132
	v_ashrrev_i32_e32 v79, 31, v78
	v_lshlrev_b64 v[78:79], 10, v[78:79]
	v_lshl_add_u64 v[78:79], v[78:79], 0, v[130:131]
	v_lshlrev_b64 v[78:79], 2, v[78:79]
	v_lshl_add_u64 v[80:81], s[0:1], 0, v[78:79]
	s_waitcnt vmcnt(0)
	v_pk_fma_f32 v[68:69], v[68:69], v[76:77], v[72:73]
	v_pk_fma_f32 v[66:67], v[66:67], v[74:75], v[70:71]
	global_store_dwordx4 v[90:91], v[66:69], off offset:576
	global_load_dwordx4 v[66:69], v[80:81], off
	global_load_dwordx4 v[70:73], v[0:1], off
	ds_read2_b32 v[74:75], v133 offset0:128 offset1:144
	v_lshl_add_u64 v[76:77], s[16:17], 0, v[78:79]
	s_waitcnt lgkmcnt(0)
	v_pk_mul_f32 v[62:63], v[62:63], v[74:75] op_sel_hi:[1,0]
	v_pk_mul_f32 v[64:65], v[64:65], v[74:75] op_sel_hi:[1,0]
	v_pk_mul_f32 v[58:59], v[58:59], v[74:75] op_sel_hi:[1,0]
	v_pk_mul_f32 v[60:61], v[60:61], v[74:75] op_sel_hi:[1,0]
	v_pk_mul_f32 v[54:55], v[54:55], v[74:75] op_sel_hi:[1,0]
	v_pk_mul_f32 v[56:57], v[56:57], v[74:75] op_sel_hi:[1,0]
	v_pk_mul_f32 v[46:47], v[46:47], v[74:75] op_sel_hi:[1,0]
	v_pk_mul_f32 v[48:49], v[48:49], v[74:75] op_sel_hi:[1,0]
	s_waitcnt vmcnt(0)
	v_pk_fma_f32 v[64:65], v[72:73], v[64:65], v[68:69]
	v_pk_fma_f32 v[62:63], v[70:71], v[62:63], v[66:67]
	global_store_dwordx4 v[76:77], v[62:65], off
	global_load_dwordx4 v[62:65], v[80:81], off offset:64
	s_nop 0
	global_load_dwordx4 v[66:69], v[0:1], off offset:64
	s_waitcnt vmcnt(0)
	v_pk_fma_f32 v[60:61], v[60:61], v[68:69], v[64:65]
	v_pk_fma_f32 v[58:59], v[58:59], v[66:67], v[62:63]
	global_store_dwordx4 v[76:77], v[58:61], off offset:64
	global_load_dwordx4 v[58:61], v[80:81], off offset:512
	s_nop 0
	global_load_dwordx4 v[62:65], v[0:1], off offset:512
	s_waitcnt vmcnt(0)
	v_pk_fma_f32 v[56:57], v[56:57], v[64:65], v[60:61]
	v_pk_fma_f32 v[54:55], v[54:55], v[62:63], v[58:59]
	global_store_dwordx4 v[76:77], v[54:57], off offset:512
	global_load_dwordx4 v[54:57], v[80:81], off offset:576
	s_nop 0
	global_load_dwordx4 v[58:61], v[0:1], off offset:576
	v_add_u32_e32 v62, 0x90, v132
	v_ashrrev_i32_e32 v63, 31, v62
	v_lshlrev_b64 v[62:63], 10, v[62:63]
	v_lshl_add_u64 v[62:63], v[62:63], 0, v[130:131]
	v_lshlrev_b64 v[62:63], 2, v[62:63]
	v_lshl_add_u64 v[64:65], s[0:1], 0, v[62:63]
	s_waitcnt vmcnt(0)
;     __device__ __forceinline__ void fused(f32x4 (&acc)[2][2][4][2], const Unit& u, int wr, int wc, int fr, int fq, PG8_LAS unsigned char* lds, int wid, int lane) const {
;     ...
;         const int col0 = u.pn * BM + wc * 32 + 4 * fq;
; #pragma unroll
;         for (int ai = 0; ai < 2; ++ai)
; #pragma unroll
;             for (int m = 0; m < 4; ++m) { const int r = ai * HALF + wr * 64 + m * 16 + fr; const float rs = R[r]; const size_t off = (size_t)(u.pm * BM + r) * 1024 + col0;
; #pragma unroll
;                 for (int bj = 0; bj < 2; ++bj)
; #pragma unroll
;                     for (int n = 0; n < 2; ++n) { const int c = bj * HALF + n * 16; const f32x4 xv = *(const f32x4*)(xres + off + c); const f32x4 wv = *(const f32x4*)(w + col0 + c);
;                         *(f32x4*)(out + off + c) = xv + acc[ai][bj][m][n] * rs * wv; }
;                 if (m & 1) asm volatile("" ::: "memory"); }
	v_pk_fma_f32 v[48:49], v[48:49], v[60:61], v[56:57]
	v_pk_fma_f32 v[46:47], v[46:47], v[58:59], v[54:55]
	global_store_dwordx4 v[76:77], v[46:49], off offset:576
	global_load_dwordx4 v[46:49], v[0:1], off
	s_nop 0
	global_load_dwordx4 v[54:57], v[64:65], off
	v_mov_b32_e32 v60, v75
	v_pk_mul_f32 v[50:51], v[50:51], v[60:61] op_sel_hi:[1,0]
	v_pk_mul_f32 v[52:53], v[52:53], v[60:61] op_sel_hi:[1,0]
	v_lshl_add_u64 v[58:59], s[16:17], 0, v[62:63]
	v_pk_mul_f32 v[42:43], v[42:43], v[60:61] op_sel_hi:[1,0]
	v_pk_mul_f32 v[44:45], v[44:45], v[60:61] op_sel_hi:[1,0]
	v_pk_mul_f32 v[38:39], v[38:39], v[60:61] op_sel_hi:[1,0]
	v_pk_mul_f32 v[40:41], v[40:41], v[60:61] op_sel_hi:[1,0]
	v_pk_mul_f32 v[30:31], v[30:31], v[60:61] op_sel_hi:[1,0]
	v_pk_mul_f32 v[32:33], v[32:33], v[60:61] op_sel_hi:[1,0]
	s_waitcnt vmcnt(0)
	v_pk_fma_f32 v[48:49], v[48:49], v[52:53], v[56:57]
	v_pk_fma_f32 v[46:47], v[46:47], v[50:51], v[54:55]
	global_store_dwordx4 v[58:59], v[46:49], off
	global_load_dwordx4 v[46:49], v[64:65], off offset:64
	s_nop 0
	global_load_dwordx4 v[50:53], v[0:1], off offset:64
	s_waitcnt vmcnt(0)
	v_pk_fma_f32 v[44:45], v[44:45], v[52:53], v[48:49]
	v_pk_fma_f32 v[42:43], v[42:43], v[50:51], v[46:47]
	global_store_dwordx4 v[58:59], v[42:45], off offset:64
	global_load_dwordx4 v[42:45], v[64:65], off offset:512
	s_nop 0
	global_load_dwordx4 v[46:49], v[0:1], off offset:512
	s_waitcnt vmcnt(0)
	v_pk_fma_f32 v[40:41], v[40:41], v[48:49], v[44:45]
	v_pk_fma_f32 v[38:39], v[38:39], v[46:47], v[42:43]
	global_store_dwordx4 v[58:59], v[38:41], off offset:512
	global_load_dwordx4 v[38:41], v[64:65], off offset:576
	s_nop 0
	global_load_dwordx4 v[42:45], v[0:1], off offset:576
	v_add_u32_e32 v46, 0xa0, v132
	v_ashrrev_i32_e32 v47, 31, v46
	v_lshlrev_b64 v[46:47], 10, v[46:47]
	v_lshl_add_u64 v[46:47], v[46:47], 0, v[130:131]
	v_lshlrev_b64 v[46:47], 2, v[46:47]
	v_lshl_add_u64 v[48:49], s[0:1], 0, v[46:47]
	s_waitcnt vmcnt(0)
	v_pk_fma_f32 v[32:33], v[32:33], v[44:45], v[40:41]
	v_pk_fma_f32 v[30:31], v[30:31], v[42:43], v[38:39]
	global_store_dwordx4 v[58:59], v[30:33], off offset:576
	global_load_dwordx4 v[30:33], v[48:49], off
	global_load_dwordx4 v[38:41], v[0:1], off
	ds_read2_b32 v[42:43], v133 offset0:160 offset1:176
	v_lshl_add_u64 v[44:45], s[16:17], 0, v[46:47]
	s_waitcnt lgkmcnt(0)
	v_pk_mul_f32 v[34:35], v[34:35], v[42:43] op_sel_hi:[1,0]
	v_pk_mul_f32 v[36:37], v[36:37], v[42:43] op_sel_hi:[1,0]
	v_pk_mul_f32 v[26:27], v[26:27], v[42:43] op_sel_hi:[1,0]
	v_pk_mul_f32 v[28:29], v[28:29], v[42:43] op_sel_hi:[1,0]
	v_pk_mul_f32 v[22:23], v[22:23], v[42:43] op_sel_hi:[1,0]
	v_pk_mul_f32 v[24:25], v[24:25], v[42:43] op_sel_hi:[1,0]
	v_pk_mul_f32 v[14:15], v[14:15], v[42:43] op_sel_hi:[1,0]
	v_pk_mul_f32 v[16:17], v[16:17], v[42:43] op_sel_hi:[1,0]
	s_waitcnt vmcnt(0)
	v_pk_fma_f32 v[32:33], v[40:41], v[36:37], v[32:33]
	v_pk_fma_f32 v[30:31], v[38:39], v[34:35], v[30:31]
	global_store_dwordx4 v[44:45], v[30:33], off
	global_load_dwordx4 v[30:33], v[48:49], off offset:64
	s_nop 0
	global_load_dwordx4 v[34:37], v[0:1], off offset:64
	s_waitcnt vmcnt(0)
	v_pk_fma_f32 v[28:29], v[28:29], v[36:37], v[32:33]
	v_pk_fma_f32 v[26:27], v[26:27], v[34:35], v[30:31]
	global_store_dwordx4 v[44:45], v[26:29], off offset:64
	global_load_dwordx4 v[26:29], v[48:49], off offset:512
	s_nop 0
	global_load_dwordx4 v[30:33], v[0:1], off offset:512
	s_waitcnt vmcnt(0)
	v_pk_fma_f32 v[24:25], v[24:25], v[32:33], v[28:29]
	v_pk_fma_f32 v[22:23], v[22:23], v[30:31], v[26:27]
	global_store_dwordx4 v[44:45], v[22:25], off offset:512
	global_load_dwordx4 v[22:25], v[48:49], off offset:576
	s_nop 0
	global_load_dwordx4 v[26:29], v[0:1], off offset:576
	v_add_u32_e32 v30, 0xb0, v132
	v_ashrrev_i32_e32 v31, 31, v30
	v_lshlrev_b64 v[30:31], 10, v[30:31]
	v_lshl_add_u64 v[30:31], v[30:31], 0, v[130:131]
	v_lshlrev_b64 v[30:31], 2, v[30:31]
	v_lshl_add_u64 v[32:33], s[0:1], 0, v[30:31]
	s_waitcnt vmcnt(0)
	v_pk_fma_f32 v[16:17], v[16:17], v[28:29], v[24:25]
	v_pk_fma_f32 v[14:15], v[14:15], v[26:27], v[22:23]
	global_store_dwordx4 v[44:45], v[14:17], off offset:576
	global_load_dwordx4 v[14:17], v[0:1], off
	s_nop 0
	global_load_dwordx4 v[22:25], v[32:33], off
	v_mov_b32_e32 v28, v43
	v_pk_mul_f32 v[18:19], v[18:19], v[28:29] op_sel_hi:[1,0]
	v_pk_mul_f32 v[20:21], v[20:21], v[28:29] op_sel_hi:[1,0]
	v_lshl_add_u64 v[26:27], s[16:17], 0, v[30:31]
	v_pk_mul_f32 v[10:11], v[10:11], v[28:29] op_sel_hi:[1,0]
	v_pk_mul_f32 v[12:13], v[12:13], v[28:29] op_sel_hi:[1,0]
	v_pk_mul_f32 v[6:7], v[6:7], v[28:29] op_sel_hi:[1,0]
	v_pk_mul_f32 v[8:9], v[8:9], v[28:29] op_sel_hi:[1,0]
	s_waitcnt vmcnt(0)
	v_pk_fma_f32 v[16:17], v[16:17], v[20:21], v[24:25]
	v_pk_fma_f32 v[14:15], v[14:15], v[18:19], v[22:23]
	global_store_dwordx4 v[26:27], v[14:17], off
	global_load_dwordx4 v[14:17], v[32:33], off offset:64
	s_nop 0
	global_load_dwordx4 v[18:21], v[0:1], off offset:64
	s_waitcnt vmcnt(0)
	v_pk_fma_f32 v[12:13], v[12:13], v[20:21], v[16:17]
	v_pk_fma_f32 v[10:11], v[10:11], v[18:19], v[14:15]
	global_store_dwordx4 v[26:27], v[10:13], off offset:64
	global_load_dwordx4 v[10:13], v[32:33], off offset:512
	s_nop 0
	global_load_dwordx4 v[14:17], v[0:1], off offset:512
	s_waitcnt vmcnt(0)
	v_pk_fma_f32 v[8:9], v[8:9], v[16:17], v[12:13]
	v_pk_fma_f32 v[6:7], v[6:7], v[14:15], v[10:11]
	global_store_dwordx4 v[26:27], v[6:9], off offset:512
	global_load_dwordx4 v[6:9], v[32:33], off offset:576
	s_nop 0
	global_load_dwordx4 v[10:13], v[0:1], off offset:576
	v_pk_mul_f32 v[0:1], v[2:3], v[28:29] op_sel_hi:[1,0]
	v_pk_mul_f32 v[2:3], v[4:5], v[28:29] op_sel_hi:[1,0]
	s_waitcnt vmcnt(0)
	v_pk_fma_f32 v[0:1], v[0:1], v[10:11], v[6:7]
	v_pk_fma_f32 v[2:3], v[2:3], v[12:13], v[8:9]
	global_store_dwordx4 v[26:27], v[0:3], off offset:576

; __global__ void __launch_bounds__(512, 2) mega(MegaArgs a) {
	.amdhsa_kernel _Z4mega8MegaArgs
		.amdhsa_group_segment_fixed_size 0
		.amdhsa_private_segment_fixed_size 0
		.amdhsa_kernarg_size 424
		.amdhsa_user_sgpr_count 2
		.amdhsa_user_sgpr_dispatch_ptr 0
		.amdhsa_user_sgpr_queue_ptr 0
		.amdhsa_user_sgpr_kernarg_segment_ptr 1
		.amdhsa_user_sgpr_dispatch_id 0
		.amdhsa_user_sgpr_kernarg_preload_length 0
		.amdhsa_user_sgpr_kernarg_preload_offset 0
		.amdhsa_user_sgpr_private_segment_size 0
		.amdhsa_uses_dynamic_stack 0
		.amdhsa_enable_private_segment 0
		.amdhsa_system_sgpr_workgroup_id_x 1
		.amdhsa_system_sgpr_workgroup_id_y 0
		.amdhsa_system_sgpr_workgroup_id_z 0
		.amdhsa_system_sgpr_workgroup_info 0
		.amdhsa_system_vgpr_workitem_id 0
		.amdhsa_next_free_vgpr 256
		.amdhsa_next_free_sgpr 102
		.amdhsa_accum_offset 256
		.amdhsa_reserve_vcc 1
		.amdhsa_float_round_mode_32 0
		.amdhsa_float_round_mode_16_64 0
		.amdhsa_float_denorm_mode_32 3
		.amdhsa_float_denorm_mode_16_64 3
		.amdhsa_dx10_clamp 1
		.amdhsa_ieee_mode 1
		.amdhsa_fp16_overflow 0
		.amdhsa_tg_split 0
		.amdhsa_exception_fp_ieee_invalid_op 0
		.amdhsa_exception_fp_denorm_src 0
		.amdhsa_exception_fp_ieee_div_zero 0
		.amdhsa_exception_fp_ieee_overflow 0
		.amdhsa_exception_fp_ieee_underflow 0
		.amdhsa_exception_fp_ieee_inexact 0
		.amdhsa_exception_int_div_zero 0
	.end_amdhsa_kernel

; __global__ void __launch_bounds__(512, 2) mega(MegaArgs a) {
amdhsa.kernels:
  - .agpr_count:     0
    .args:
      - .offset:         0
        .size:           168
        .value_kind:     by_value
      - .offset:         168
        .size:           4
        .value_kind:     hidden_block_count_x
      - .offset:         172
        .size:           4
        .value_kind:     hidden_block_count_y
      - .offset:         176
        .size:           4
        .value_kind:     hidden_block_count_z
      - .offset:         180
        .size:           2
        .value_kind:     hidden_group_size_x
      - .offset:         182
        .size:           2
        .value_kind:     hidden_group_size_y
      - .offset:         184
        .size:           2
        .value_kind:     hidden_group_size_z
      - .offset:         186
        .size:           2
        .value_kind:     hidden_remainder_x
      - .offset:         188
        .size:           2
        .value_kind:     hidden_remainder_y
      - .offset:         190
        .size:           2
        .value_kind:     hidden_remainder_z
      - .offset:         208
        .size:           8
        .value_kind:     hidden_global_offset_x
      - .offset:         216
        .size:           8
        .value_kind:     hidden_global_offset_y
      - .offset:         224
        .size:           8
        .value_kind:     hidden_global_offset_z
      - .offset:         232
        .size:           2
        .value_kind:     hidden_grid_dims
      - .offset:         288
        .size:           4
        .value_kind:     hidden_dynamic_lds_size
    .group_segment_fixed_size: 0
    .kernarg_segment_align: 8
    .kernarg_segment_size: 424
    .language:       OpenCL C
    .language_version:
      - 2
      - 0
    .max_flat_workgroup_size: 512
    .name:           _Z4mega8MegaArgs
    .private_segment_fixed_size: 0
    .sgpr_count:     108
    .sgpr_spill_count: 412
    .symbol:         _Z4mega8MegaArgs.kd
    .uniform_work_group_size: 1
    .uses_dynamic_stack: false
    .vgpr_count:     256
    .vgpr_spill_count: 0
    .wavefront_size: 64
